# pair-tile FFN-up with grid-size guard (falls back to the compiler tile loop when gridDim != 512)
# speedup vs baseline: 1.0049x; 1.0049x over previous
; template <class AL, class BL, class EP>
; DI void gemm_phase(int MT, int NTL, int K, AL al, BL bl, EP ep, char* smem) {
;   for (int t = blockIdx.x; t < MT * NTL; t += gridDim.x) {
;     const int tm = t % MT, tn = t / MT;
;     f32x16 acc[2][2];
;     gemm_core(al, bl, tm * 128, tn * 128, K, smem, acc);
;     ep(acc, tm * 128, tn * 128);
;   }
; }
; DI void ffn_up_phase(const Params& p, const u16* xb, int ldx, const u16* wupT, u16* hid, char* smem) {
;   const float* rs = (const float*)(p.ws + W_RS);
;   gemm_phase(NT / 128, 32, 1024,
;              [=](int m, int k) { return xb + (long)m * ldx + k; },
;              [=](int n, int k) { return wupT + (long)n * 1024 + k; },
;              [=](const f32x16 (&acc)[2][2], int m0, int n0) {
;                epi_bf16_tile(acc, m0, n0, hid + (long)m0 * 4096 + n0, 4096, smem, [=](int m, int n, float v) {
;                  const float a = fmaxf(v * rs[m], 0.f);
;                  return a * a;
;                });
;              }, smem);
; }
.LBB0_976:
	s_or_b64 exec, exec, s[0:1]
	s_cmpk_lt_i32 s78, 0x1200
	s_cselect_b64 s[58:59], -1, 0
	s_cmpk_gt_i32 s78, 0x11ff
	s_mov_b64 s[2:3], s[70:71]
	s_waitcnt lgkmcnt(0)
	s_barrier
	s_cbranch_scc1 .LBB0_980
	s_add_u32 s8, s70, 0xdc00000
	s_addc_u32 s9, s71, 0
	s_add_u32 s22, s70, 0x4c00000
	s_addc_u32 s23, s71, 0
	s_add_u32 s14, s70, 0x10000
	s_mov_b64 s[12:13], 0x10000
	s_addc_u32 s15, s71, 0
	s_add_i32 s24, s67, 48
	s_lshl_b32 s25, s50, 7
	v_mov_b32_e32 v65, 0
	s_mov_b32 s26, 0x10000
	s_mov_b64 s[16:17], 0x20000
	s_mov_b32 s27, 0x20000
	s_mov_b64 s[18:19], 0x30000
	s_mov_b32 s28, 0x30000
	s_movk_i32 s29, 0x90
	s_mov_b32 s30, 0xfffffc0
	s_movk_i32 s31, 0x110
	s_mov_b32 s33, s78
	s_mov_b32 s99, 0
	s_cmpk_eq_u32 s50, 0x200
	s_cbranch_scc0 .Lfu0_fallback
	s_mov_b32 s99, 1
	v_bfe_u32 v62, v202, 5, 1
	v_and_b32_e32 v63, 31, v202
	v_lshrrev_b32_e32 v64, 7, v202
	v_bfe_u32 v254, v202, 6, 1
	v_lshlrev_b32_e32 v253, 2, v62
	v_lshl_add_u32 v253, v64, 6, v253
	v_mul_u32_u24_e32 v59, 528, v253
	v_lshlrev_b32_e32 v252, 2, v253
	v_lshl_add_u32 v253, v254, 7, v63
	v_lshl_add_u32 v59, v253, 1, v59
	v_mul_u32_u24_e32 v57, 80, v253
	v_lshl_add_u32 v57, v62, 4, v57
	v_add_u32_e32 v57, 10240, v57
	v_lshl_add_u32 v253, v64, 6, v63
	v_mul_u32_u24_e32 v56, 80, v253
	v_lshl_add_u32 v56, v62, 4, v56
	v_lshrrev_b32_e32 v253, 5, v202
	v_mul_u32_u24_e32 v60, 528, v253
	v_lshl_add_u32 v60, v63, 4, v60
	v_mul_u32_u24_e32 v227, 8192, v253
	v_lshl_add_u32 v227, v63, 4, v227
	v_lshrrev_b32_e32 v253, 2, v202
	v_and_b32_e32 v254, 3, v202
	v_lshlrev_b32_e32 v254, 4, v254
	v_mov_b32_e32 v255, 0
	v_mul_u32_u24_e32 v58, 80, v253
	v_add_u32_e32 v58, v58, v254
	s_mov_b32 s98, s78
	s_cmpk_lt_u32 s98, 2016
	s_cbranch_scc1 .Lfu0_m0
	s_sub_u32 s34, s98, 2016
	s_mov_b32 s35, 14
	s_branch .Lfu0_g0

; #define G_LOAD(S, kt_) do { G_LD1(S##a0, S##b0, 0, kt_); G_LD1(S##a1, S##b1, 1, kt_); G_LD1(S##a2, S##b2, 2, kt_); G_LD1(S##a3, S##b3, 3, kt_); } while (0)
; #define G_STORE(S, buf_) do { G_ST1(S##a0, S##b0, 0, buf_); G_ST1(S##a1, S##b1, 1, buf_); G_ST1(S##a2, S##b2, 2, buf_); G_ST1(S##a3, S##b3, 3, buf_); } while (0)
; template <class AL, class BL>
; DI void gemm_core(AL al, BL bl, int m0, int n0, int K, char* smem, f32x16 (&acc)[2][2]) {
;     ...
;   const int srow = tid >> 3, sch = tid & 7;
;     ...
;   G_LOAD(x, 0);
;   G_STORE(x, 0);
;   G_LOAD(x, 1);
;   G_LOAD(y, (nk > 2) ? 2 : 1);
;   __syncthreads();
;   for (int kt = 0; kt < nk; kt += 2) {
;     G_TILE(0, x, true, (kt + 3 < nk), kt + 3);
;     __syncthreads();
;     G_TILE(1, y, (kt + 2 < nk), (kt + 4 < nk), kt + 4);
.Lfu0_fallback:
.LBB0_978:
	s_mul_hi_i32 s0, s33, 0x38e38e39
	s_lshr_b32 s1, s0, 31
	s_ashr_i32 s0, s0, 5
	s_add_i32 s1, s0, s1
	v_mov_b32_e32 v32, v202
	s_lshl_b32 s0, s1, 7
	s_mul_i32 s34, s1, 0x4800
	v_ashrrev_i32_e32 v33, 3, v32
	v_add_u32_e32 v4, s0, v33
	v_ashrrev_i32_e32 v5, 31, v4
	v_lshlrev_b32_e32 v2, 4, v32
	v_lshlrev_b64 v[4:5], 11, v[4:5]
	v_and_b32_e32 v64, 0x70, v2
	v_lshl_add_u64 v[4:5], s[8:9], 0, v[4:5]
	v_lshl_add_u64 v[78:79], v[4:5], 0, v[64:65]
	v_subrev_u32_e32 v0, s34, v33
	v_add_co_u32_e32 v12, vcc, s26, v78
	v_add_u32_e32 v24, s24, v0
	s_nop 0
	v_addc_co_u32_e32 v13, vcc, 0, v79, vcc
	v_subrev_u32_e32 v0, 48, v24
	v_add_co_u32_e32 v20, vcc, s27, v78
	v_ashrrev_i32_e32 v1, 31, v0
	global_load_dwordx4 v[4:7], v[78:79], off
	v_add_u32_e32 v8, -16, v24
	v_addc_co_u32_e32 v21, vcc, 0, v79, vcc
	v_lshlrev_b64 v[0:1], 12, v[0:1]
	v_ashrrev_i32_e32 v9, 31, v8
	global_load_dwordx4 v[12:15], v[12:13], off
	v_add_u32_e32 v16, 16, v24
	v_add_u32_e32 v28, 48, v24
	v_add_co_u32_e32 v24, vcc, s28, v78
	v_lshl_add_u64 v[0:1], s[68:69], 0, v[0:1]
	v_lshlrev_b64 v[8:9], 12, v[8:9]
	v_ashrrev_i32_e32 v17, 31, v16
	global_load_dwordx4 v[20:23], v[20:21], off
	v_addc_co_u32_e32 v25, vcc, 0, v79, vcc
	v_lshl_add_u64 v[76:77], v[0:1], 0, v[64:65]
	v_lshl_add_u64 v[8:9], s[68:69], 0, v[8:9]
	v_lshlrev_b64 v[16:17], 12, v[16:17]
	v_ashrrev_i32_e32 v29, 31, v28
	global_load_dwordx4 v[24:27], v[24:25], off
	v_lshl_add_u64 v[74:75], v[8:9], 0, v[64:65]
	global_load_dwordx4 v[0:3], v[76:77], off offset:2048
	global_load_dwordx4 v[8:11], v[74:75], off offset:2048
	v_lshl_add_u64 v[16:17], s[68:69], 0, v[16:17]
	v_lshlrev_b64 v[28:29], 12, v[28:29]
	v_lshl_add_u64 v[70:71], v[16:17], 0, v[64:65]
	v_lshl_add_u64 v[28:29], s[68:69], 0, v[28:29]
	global_load_dwordx4 v[16:19], v[70:71], off offset:2048
	v_lshl_add_u64 v[72:73], v[28:29], 0, v[64:65]
	global_load_dwordx4 v[28:31], v[72:73], off offset:2048
	v_lshrrev_b32_e32 v34, 1, v32
	v_and_b32_e32 v35, 31, v32
	v_mad_u64_u32 v[68:69], s[2:3], v33, s29, v[64:65]
	v_lshl_add_u64 v[84:85], v[78:79], 0, s[12:13]
	v_lshl_add_u64 v[82:83], v[78:79], 0, s[16:17]
	v_lshl_add_u64 v[80:81], v[78:79], 0, s[18:19]
	global_load_dwordx4 v[86:89], v[78:79], off offset:128
	global_load_dwordx4 v[90:93], v[78:79], off offset:256
	global_load_dwordx4 v[94:97], v[84:85], off offset:128
	global_load_dwordx4 v[98:101], v[84:85], off offset:256
	global_load_dwordx4 v[102:105], v[82:83], off offset:128
	global_load_dwordx4 v[106:109], v[82:83], off offset:256
	global_load_dwordx4 v[110:113], v[80:81], off offset:128
	global_load_dwordx4 v[114:117], v[80:81], off offset:256
	global_load_dwordx4 v[118:121], v[76:77], off offset:2176
	global_load_dwordx4 v[122:125], v[74:75], off offset:2176
	global_load_dwordx4 v[126:129], v[70:71], off offset:2176
	global_load_dwordx4 v[130:133], v[72:73], off offset:2176
	global_load_dwordx4 v[134:137], v[76:77], off offset:2304
	global_load_dwordx4 v[138:141], v[74:75], off offset:2304
	global_load_dwordx4 v[142:145], v[70:71], off offset:2304
	global_load_dwordx4 v[146:149], v[72:73], off offset:2304
	s_mulk_i32 s1, 0xb800
	s_add_i32 s1, s24, s1
	s_sub_i32 s20, s1, 48
	s_waitcnt vmcnt(23)
	ds_write_b128 v68, v[4:7] offset:36864
	s_waitcnt vmcnt(22)
	ds_write_b128 v68, v[12:15] offset:41472
	s_waitcnt vmcnt(21)
	ds_write_b128 v68, v[20:23] offset:46080
	s_waitcnt vmcnt(20)
	ds_write_b128 v68, v[24:27] offset:50688
	s_waitcnt vmcnt(19)
	ds_write_b128 v68, v[0:3]
	s_waitcnt vmcnt(18)
	ds_write_b128 v68, v[8:11] offset:4608
	s_waitcnt vmcnt(17)
	ds_write_b128 v68, v[16:19] offset:9216
	s_waitcnt vmcnt(16)
	ds_write_b128 v68, v[28:31] offset:13824
	v_and_or_b32 v0, v34, s30, v35
	v_and_b32_e32 v4, 16, v34
	v_mad_u64_u32 v[66:67], s[2:3], v0, s29, v[4:5]
	s_waitcnt lgkmcnt(0)
	s_barrier
	ds_read_b128 v[0:3], v66
	v_and_b32_e32 v5, 0x5f, v32
	v_mul_u32_u24_e32 v5, 0x48, v5
	v_lshl_add_u32 v64, v5, 1, v4
	ds_read_b128 v[4:7], v64 offset:36864
	ds_read_b128 v[150:153], v66 offset:32
	ds_read_b128 v[154:157], v64 offset:36896
	ds_read_b128 v[8:11], v64 offset:41472
	ds_read_b128 v[158:161], v64 offset:41504
	s_waitcnt lgkmcnt(4)
	v_mfma_f32_32x32x16_bf16 v[48:63], v[0:3], v[4:7], 0
	v_add_u32_e32 v67, 0x9000, v68
	s_waitcnt lgkmcnt(1)
	v_mfma_f32_32x32x16_bf16 v[32:47], v[0:3], v[8:11], 0
	ds_read_b128 v[0:3], v66 offset:4608
	ds_read_b128 v[162:165], v66 offset:4640
	global_load_dwordx4 v[166:169], v[76:77], off offset:2432
	global_load_dwordx4 v[170:173], v[78:79], off offset:384
	s_waitcnt vmcnt(9)
	ds_write_b128 v68, v[118:121] offset:18432
	ds_write_b128 v68, v[86:89] offset:55296
	s_waitcnt lgkmcnt(3)
	v_mfma_f32_32x32x16_bf16 v[16:31], v[0:3], v[4:7], 0
	v_mfma_f32_32x32x16_bf16 v[0:15], v[0:3], v[8:11], 0
	global_load_dwordx4 v[86:89], v[74:75], off offset:2432
	global_load_dwordx4 v[118:121], v[84:85], off offset:384
	v_mfma_f32_32x32x16_bf16 v[48:63], v[150:153], v[154:157], v[48:63]
	v_mfma_f32_32x32x16_bf16 v[32:47], v[150:153], v[158:161], v[32:47]
	s_waitcnt lgkmcnt(2)
	v_mfma_f32_32x32x16_bf16 v[16:31], v[162:165], v[154:157], v[16:31]
	ds_read_b128 v[150:153], v66 offset:64
	ds_read_b128 v[154:157], v66 offset:4672
	ds_read_b128 v[174:177], v64 offset:36928
	ds_read_b128 v[178:181], v64 offset:41536
	s_waitcnt vmcnt(10)
	ds_write_b128 v68, v[122:125] offset:23040
	ds_write_b128 v68, v[94:97] offset:59904
	v_mfma_f32_32x32x16_bf16 v[0:15], v[162:165], v[158:161], v[0:15]
	global_load_dwordx4 v[94:97], v[70:71], off offset:2432
	global_load_dwordx4 v[122:125], v[82:83], off offset:384
	s_waitcnt lgkmcnt(3)
	v_mfma_f32_32x32x16_bf16 v[48:63], v[150:153], v[174:177], v[48:63]
	s_waitcnt lgkmcnt(2)
	v_mfma_f32_32x32x16_bf16 v[32:47], v[150:153], v[178:181], v[32:47]
	v_mfma_f32_32x32x16_bf16 v[16:31], v[154:157], v[174:177], v[16:31]
	ds_read_b128 v[150:153], v66 offset:96
	ds_read_b128 v[158:161], v66 offset:4704
	ds_read_b128 v[162:165], v64 offset:36960
	ds_read_b128 v[174:177], v64 offset:41568
	s_waitcnt vmcnt(11)
	ds_write_b128 v68, v[126:129] offset:27648
	ds_write_b128 v68, v[102:105] offset:64512
	v_mfma_f32_32x32x16_bf16 v[0:15], v[154:157], v[178:181], v[0:15]
	global_load_dwordx4 v[102:105], v[72:73], off offset:2432
	global_load_dwordx4 v[126:129], v[80:81], off offset:384
	s_waitcnt lgkmcnt(3)
	v_mfma_f32_32x32x16_bf16 v[48:63], v[150:153], v[162:165], v[48:63]
	s_waitcnt vmcnt(12)
	ds_write_b128 v68, v[130:133] offset:32256
	ds_write_b128 v67, v[110:113] offset:32256
	s_waitcnt lgkmcnt(4)
	v_mfma_f32_32x32x16_bf16 v[32:47], v[150:153], v[174:177], v[32:47]
	v_mfma_f32_32x32x16_bf16 v[16:31], v[158:161], v[162:165], v[16:31]
	v_mfma_f32_32x32x16_bf16 v[0:15], v[158:161], v[174:177], v[0:15]
	s_waitcnt lgkmcnt(0)
	s_barrier
; #define G_LOAD(S, kt_) do { G_LD1(S##a0, S##b0, 0, kt_); G_LD1(S##a1, S##b1, 1, kt_); G_LD1(S##a2, S##b2, 2, kt_); G_LD1(S##a3, S##b3, 3, kt_); } while (0)
; #define G_STORE(S, buf_) do { G_ST1(S##a0, S##b0, 0, buf_); G_ST1(S##a1, S##b1, 1, buf_); G_ST1(S##a2, S##b2, 2, buf_); G_ST1(S##a3, S##b3, 3, buf_); } while (0)
; template <class AL, class BL>
; DI void gemm_core(AL al, BL bl, int m0, int n0, int K, char* smem, f32x16 (&acc)[2][2]) {
;     ...
;   G_LOAD(x, 0);
;   G_STORE(x, 0);
;   G_LOAD(x, 1);
;   G_LOAD(y, (nk > 2) ? 2 : 1);
;   __syncthreads();
;   for (int kt = 0; kt < nk; kt += 2) {
;     G_TILE(0, x, true, (kt + 3 < nk), kt + 3);
;     __syncthreads();
;     G_TILE(1, y, (kt + 2 < nk), (kt + 4 < nk), kt + 4);
;     __syncthreads();
	ds_read_b128 v[110:113], v66 offset:18432
	ds_read_b128 v[130:133], v64 offset:55296
	ds_read_b128 v[150:153], v66 offset:18464
	ds_read_b128 v[154:157], v64 offset:55328
	ds_read_b128 v[158:161], v64 offset:59904
	ds_read_b128 v[162:165], v64 offset:59936
	s_waitcnt lgkmcnt(4)
	v_mfma_f32_32x32x16_bf16 v[48:63], v[110:113], v[130:133], v[48:63]
	s_waitcnt lgkmcnt(1)
	v_mfma_f32_32x32x16_bf16 v[32:47], v[110:113], v[158:161], v[32:47]
	ds_read_b128 v[110:113], v66 offset:23040
	ds_read_b128 v[174:177], v66 offset:23072
	s_waitcnt lgkmcnt(1)
	v_mfma_f32_32x32x16_bf16 v[16:31], v[110:113], v[130:133], v[16:31]
	global_load_dwordx4 v[130:133], v[76:77], off offset:2560
	global_load_dwordx4 v[178:181], v[78:79], off offset:512
	s_waitcnt vmcnt(13)
	ds_write_b128 v68, v[134:137]
	ds_write_b128 v68, v[90:93] offset:36864
	v_mfma_f32_32x32x16_bf16 v[0:15], v[110:113], v[158:161], v[0:15]
	global_load_dwordx4 v[90:93], v[74:75], off offset:2560
	global_load_dwordx4 v[110:113], v[84:85], off offset:512
	v_mfma_f32_32x32x16_bf16 v[48:63], v[150:153], v[154:157], v[48:63]
	v_mfma_f32_32x32x16_bf16 v[32:47], v[150:153], v[162:165], v[32:47]
	s_waitcnt lgkmcnt(2)
	v_mfma_f32_32x32x16_bf16 v[16:31], v[174:177], v[154:157], v[16:31]
	ds_read_b128 v[134:137], v66 offset:18496
	ds_read_b128 v[150:153], v66 offset:23104
	ds_read_b128 v[154:157], v64 offset:55360
	ds_read_b128 v[158:161], v64 offset:59968
	s_waitcnt vmcnt(14)
	ds_write_b128 v68, v[138:141] offset:4608
	ds_write_b128 v68, v[98:101] offset:41472
	v_mfma_f32_32x32x16_bf16 v[0:15], v[174:177], v[162:165], v[0:15]
	s_waitcnt lgkmcnt(3)
	v_mfma_f32_32x32x16_bf16 v[48:63], v[134:137], v[154:157], v[48:63]
	s_waitcnt lgkmcnt(2)
	v_mfma_f32_32x32x16_bf16 v[32:47], v[134:137], v[158:161], v[32:47]
	global_load_dwordx4 v[98:101], v[70:71], off offset:2560
	global_load_dwordx4 v[134:137], v[82:83], off offset:512
	v_mfma_f32_32x32x16_bf16 v[16:31], v[150:153], v[154:157], v[16:31]
	ds_read_b128 v[138:141], v66 offset:18528
	ds_read_b128 v[154:157], v66 offset:23136
	ds_read_b128 v[162:165], v64 offset:55392
	ds_read_b128 v[174:177], v64 offset:60000
	s_waitcnt vmcnt(15)
	ds_write_b128 v68, v[142:145] offset:9216
	ds_write_b128 v68, v[106:109] offset:46080
	v_mfma_f32_32x32x16_bf16 v[0:15], v[150:153], v[158:161], v[0:15]
	s_waitcnt lgkmcnt(3)
	v_mfma_f32_32x32x16_bf16 v[48:63], v[138:141], v[162:165], v[48:63]
	s_waitcnt lgkmcnt(2)
	v_mfma_f32_32x32x16_bf16 v[32:47], v[138:141], v[174:177], v[32:47]
	global_load_dwordx4 v[106:109], v[72:73], off offset:2560
	global_load_dwordx4 v[138:141], v[80:81], off offset:512
	s_waitcnt vmcnt(16)
	ds_write_b128 v68, v[146:149] offset:13824
	ds_write_b128 v68, v[114:117] offset:50688
	v_mfma_f32_32x32x16_bf16 v[16:31], v[154:157], v[162:165], v[16:31]
	v_mfma_f32_32x32x16_bf16 v[0:15], v[154:157], v[174:177], v[0:15]
	s_waitcnt lgkmcnt(0)
	s_barrier
	ds_read_b128 v[114:117], v66
	ds_read_b128 v[142:145], v64 offset:36864
	ds_read_b128 v[146:149], v66 offset:32
	ds_read_b128 v[150:153], v64 offset:36896
	ds_read_b128 v[154:157], v64 offset:41472
	ds_read_b128 v[158:161], v64 offset:41504
	s_waitcnt lgkmcnt(4)
	v_mfma_f32_32x32x16_bf16 v[48:63], v[114:117], v[142:145], v[48:63]
	s_waitcnt lgkmcnt(1)
	v_mfma_f32_32x32x16_bf16 v[32:47], v[114:117], v[154:157], v[32:47]
	ds_read_b128 v[114:117], v66 offset:4608
	ds_read_b128 v[162:165], v66 offset:4640
	s_waitcnt lgkmcnt(1)
	v_mfma_f32_32x32x16_bf16 v[16:31], v[114:117], v[142:145], v[16:31]
	global_load_dwordx4 v[142:145], v[76:77], off offset:2688
	global_load_dwordx4 v[174:177], v[78:79], off offset:640
	s_waitcnt vmcnt(17)
	ds_write_b128 v68, v[166:169] offset:18432
	s_waitcnt vmcnt(16)
	ds_write_b128 v68, v[170:173] offset:55296
	v_mfma_f32_32x32x16_bf16 v[0:15], v[114:117], v[154:157], v[0:15]
	v_mfma_f32_32x32x16_bf16 v[48:63], v[146:149], v[150:153], v[48:63]
	v_mfma_f32_32x32x16_bf16 v[32:47], v[146:149], v[158:161], v[32:47]
	global_load_dwordx4 v[114:117], v[74:75], off offset:2688
	global_load_dwordx4 v[146:149], v[84:85], off offset:640
	s_waitcnt lgkmcnt(2)
	v_mfma_f32_32x32x16_bf16 v[16:31], v[162:165], v[150:153], v[16:31]
	ds_read_b128 v[150:153], v66 offset:64
	ds_read_b128 v[154:157], v66 offset:4672
	ds_read_b128 v[166:169], v64 offset:36928
	ds_read_b128 v[170:173], v64 offset:41536
	s_waitcnt vmcnt(17)
	ds_write_b128 v68, v[86:89] offset:23040
	s_waitcnt vmcnt(16)
	ds_write_b128 v68, v[118:121] offset:59904
	v_mfma_f32_32x32x16_bf16 v[0:15], v[162:165], v[158:161], v[0:15]
	global_load_dwordx4 v[86:89], v[70:71], off offset:2688
	global_load_dwordx4 v[118:121], v[82:83], off offset:640
	s_waitcnt lgkmcnt(3)
	v_mfma_f32_32x32x16_bf16 v[48:63], v[150:153], v[166:169], v[48:63]
	s_waitcnt lgkmcnt(2)
	v_mfma_f32_32x32x16_bf16 v[32:47], v[150:153], v[170:173], v[32:47]
	v_mfma_f32_32x32x16_bf16 v[16:31], v[154:157], v[166:169], v[16:31]
	ds_read_b128 v[150:153], v66 offset:96
	ds_read_b128 v[158:161], v66 offset:4704
	ds_read_b128 v[162:165], v64 offset:36960
	ds_read_b128 v[166:169], v64 offset:41568
	s_waitcnt vmcnt(17)
	ds_write_b128 v68, v[94:97] offset:27648
	s_waitcnt vmcnt(16)
	ds_write_b128 v68, v[122:125] offset:64512
	v_mfma_f32_32x32x16_bf16 v[0:15], v[154:157], v[170:173], v[0:15]
	global_load_dwordx4 v[94:97], v[72:73], off offset:2688
	global_load_dwordx4 v[122:125], v[80:81], off offset:640
	s_waitcnt lgkmcnt(3)
	v_mfma_f32_32x32x16_bf16 v[48:63], v[150:153], v[162:165], v[48:63]
	s_waitcnt vmcnt(17)
	ds_write_b128 v68, v[102:105] offset:32256
	s_waitcnt vmcnt(16)
	ds_write_b128 v67, v[126:129] offset:32256
	s_waitcnt lgkmcnt(4)
	v_mfma_f32_32x32x16_bf16 v[32:47], v[150:153], v[166:169], v[32:47]
	v_mfma_f32_32x32x16_bf16 v[16:31], v[158:161], v[162:165], v[16:31]
	v_mfma_f32_32x32x16_bf16 v[0:15], v[158:161], v[166:169], v[0:15]
	s_waitcnt lgkmcnt(0)
	s_barrier
; #define G_LOAD(S, kt_) do { G_LD1(S##a0, S##b0, 0, kt_); G_LD1(S##a1, S##b1, 1, kt_); G_LD1(S##a2, S##b2, 2, kt_); G_LD1(S##a3, S##b3, 3, kt_); } while (0)
; #define G_STORE(S, buf_) do { G_ST1(S##a0, S##b0, 0, buf_); G_ST1(S##a1, S##b1, 1, buf_); G_ST1(S##a2, S##b2, 2, buf_); G_ST1(S##a3, S##b3, 3, buf_); } while (0)
; template <class AL, class BL>
; DI void gemm_core(AL al, BL bl, int m0, int n0, int K, char* smem, f32x16 (&acc)[2][2]) {
;     ...
;   G_LOAD(x, 0);
;   G_STORE(x, 0);
;   G_LOAD(x, 1);
;   G_LOAD(y, (nk > 2) ? 2 : 1);
;   __syncthreads();
;   for (int kt = 0; kt < nk; kt += 2) {
;     G_TILE(0, x, true, (kt + 3 < nk), kt + 3);
;     __syncthreads();
;     G_TILE(1, y, (kt + 2 < nk), (kt + 4 < nk), kt + 4);
;     __syncthreads();
	ds_read_b128 v[102:105], v66 offset:18432
	ds_read_b128 v[126:129], v64 offset:55296
	ds_read_b128 v[150:153], v66 offset:18464
	ds_read_b128 v[154:157], v64 offset:55328
	ds_read_b128 v[158:161], v64 offset:59904
	ds_read_b128 v[162:165], v64 offset:59936
	s_waitcnt lgkmcnt(4)
	v_mfma_f32_32x32x16_bf16 v[48:63], v[102:105], v[126:129], v[48:63]
	s_waitcnt lgkmcnt(1)
	v_mfma_f32_32x32x16_bf16 v[32:47], v[102:105], v[158:161], v[32:47]
	ds_read_b128 v[102:105], v66 offset:23040
	ds_read_b128 v[166:169], v66 offset:23072
	s_waitcnt lgkmcnt(1)
	v_mfma_f32_32x32x16_bf16 v[16:31], v[102:105], v[126:129], v[16:31]
	global_load_dwordx4 v[126:129], v[76:77], off offset:2816
	global_load_dwordx4 v[170:173], v[78:79], off offset:768
	s_waitcnt vmcnt(17)
	ds_write_b128 v68, v[130:133]
	s_waitcnt vmcnt(16)
	ds_write_b128 v68, v[178:181] offset:36864
	v_mfma_f32_32x32x16_bf16 v[0:15], v[102:105], v[158:161], v[0:15]
	global_load_dwordx4 v[102:105], v[74:75], off offset:2816
	global_load_dwordx4 v[130:133], v[84:85], off offset:768
	v_mfma_f32_32x32x16_bf16 v[48:63], v[150:153], v[154:157], v[48:63]
	v_mfma_f32_32x32x16_bf16 v[32:47], v[150:153], v[162:165], v[32:47]
	s_waitcnt lgkmcnt(2)
	v_mfma_f32_32x32x16_bf16 v[16:31], v[166:169], v[154:157], v[16:31]
	ds_read_b128 v[150:153], v66 offset:18496
	ds_read_b128 v[154:157], v66 offset:23104
	ds_read_b128 v[158:161], v64 offset:55360
	ds_read_b128 v[178:181], v64 offset:59968
	s_waitcnt vmcnt(17)
	ds_write_b128 v68, v[90:93] offset:4608
	s_waitcnt vmcnt(16)
	ds_write_b128 v68, v[110:113] offset:41472
	v_mfma_f32_32x32x16_bf16 v[0:15], v[166:169], v[162:165], v[0:15]
	global_load_dwordx4 v[90:93], v[70:71], off offset:2816
	global_load_dwordx4 v[110:113], v[82:83], off offset:768
	s_waitcnt lgkmcnt(3)
	v_mfma_f32_32x32x16_bf16 v[48:63], v[150:153], v[158:161], v[48:63]
	s_waitcnt lgkmcnt(2)
	v_mfma_f32_32x32x16_bf16 v[32:47], v[150:153], v[178:181], v[32:47]
	v_mfma_f32_32x32x16_bf16 v[16:31], v[154:157], v[158:161], v[16:31]
	ds_read_b128 v[150:153], v66 offset:18528
	ds_read_b128 v[158:161], v66 offset:23136
	ds_read_b128 v[162:165], v64 offset:55392
	ds_read_b128 v[166:169], v64 offset:60000
	s_waitcnt vmcnt(17)
	ds_write_b128 v68, v[98:101] offset:9216
	s_waitcnt vmcnt(16)
	ds_write_b128 v68, v[134:137] offset:46080
	v_mfma_f32_32x32x16_bf16 v[0:15], v[154:157], v[178:181], v[0:15]
	global_load_dwordx4 v[98:101], v[72:73], off offset:2816
	global_load_dwordx4 v[134:137], v[80:81], off offset:768
	s_waitcnt lgkmcnt(3)
	v_mfma_f32_32x32x16_bf16 v[48:63], v[150:153], v[162:165], v[48:63]
	s_waitcnt vmcnt(17)
	ds_write_b128 v68, v[106:109] offset:13824
	s_waitcnt vmcnt(16)
	ds_write_b128 v68, v[138:141] offset:50688
	s_waitcnt lgkmcnt(4)
	v_mfma_f32_32x32x16_bf16 v[32:47], v[150:153], v[166:169], v[32:47]
	v_mfma_f32_32x32x16_bf16 v[16:31], v[158:161], v[162:165], v[16:31]
	v_mfma_f32_32x32x16_bf16 v[0:15], v[158:161], v[166:169], v[0:15]
	s_waitcnt lgkmcnt(0)
	s_barrier
	ds_read_b128 v[106:109], v66
	ds_read_b128 v[138:141], v64 offset:36864
	ds_read_b128 v[150:153], v66 offset:32
	ds_read_b128 v[154:157], v64 offset:36896
	ds_read_b128 v[158:161], v64 offset:41472
	ds_read_b128 v[162:165], v64 offset:41504
	s_waitcnt lgkmcnt(4)
	v_mfma_f32_32x32x16_bf16 v[48:63], v[106:109], v[138:141], v[48:63]
	s_waitcnt lgkmcnt(1)
	v_mfma_f32_32x32x16_bf16 v[32:47], v[106:109], v[158:161], v[32:47]
	ds_read_b128 v[106:109], v66 offset:4608
	ds_read_b128 v[166:169], v66 offset:4640
	s_waitcnt lgkmcnt(1)
	v_mfma_f32_32x32x16_bf16 v[16:31], v[106:109], v[138:141], v[16:31]
	global_load_dwordx4 v[138:141], v[76:77], off offset:2944
	global_load_dwordx4 v[178:181], v[78:79], off offset:896
	s_waitcnt vmcnt(17)
	ds_write_b128 v68, v[142:145] offset:18432
	s_waitcnt vmcnt(16)
	ds_write_b128 v68, v[174:177] offset:55296
	v_mfma_f32_32x32x16_bf16 v[0:15], v[106:109], v[158:161], v[0:15]
	global_load_dwordx4 v[106:109], v[74:75], off offset:2944
	global_load_dwordx4 v[142:145], v[84:85], off offset:896
	v_mfma_f32_32x32x16_bf16 v[48:63], v[150:153], v[154:157], v[48:63]
	v_mfma_f32_32x32x16_bf16 v[32:47], v[150:153], v[162:165], v[32:47]
	s_waitcnt lgkmcnt(2)
	v_mfma_f32_32x32x16_bf16 v[16:31], v[166:169], v[154:157], v[16:31]
	ds_read_b128 v[150:153], v66 offset:64
	ds_read_b128 v[154:157], v66 offset:4672
	ds_read_b128 v[158:161], v64 offset:36928
	ds_read_b128 v[174:177], v64 offset:41536
	s_waitcnt vmcnt(17)
	ds_write_b128 v68, v[114:117] offset:23040
	s_waitcnt vmcnt(16)
	ds_write_b128 v68, v[146:149] offset:59904
	v_mfma_f32_32x32x16_bf16 v[0:15], v[166:169], v[162:165], v[0:15]
	global_load_dwordx4 v[114:117], v[70:71], off offset:2944
	global_load_dwordx4 v[146:149], v[82:83], off offset:896
	s_waitcnt lgkmcnt(3)
	v_mfma_f32_32x32x16_bf16 v[48:63], v[150:153], v[158:161], v[48:63]
	s_waitcnt lgkmcnt(2)
	v_mfma_f32_32x32x16_bf16 v[32:47], v[150:153], v[174:177], v[32:47]
	v_mfma_f32_32x32x16_bf16 v[16:31], v[154:157], v[158:161], v[16:31]
	ds_read_b128 v[150:153], v66 offset:96
	ds_read_b128 v[158:161], v66 offset:4704
	ds_read_b128 v[162:165], v64 offset:36960
	ds_read_b128 v[166:169], v64 offset:41568
	s_waitcnt vmcnt(17)
	ds_write_b128 v68, v[86:89] offset:27648
	s_waitcnt vmcnt(16)
	ds_write_b128 v68, v[118:121] offset:64512
	v_mfma_f32_32x32x16_bf16 v[0:15], v[154:157], v[174:177], v[0:15]
	global_load_dwordx4 v[86:89], v[72:73], off offset:2944
	global_load_dwordx4 v[118:121], v[80:81], off offset:896
	s_waitcnt lgkmcnt(3)
	v_mfma_f32_32x32x16_bf16 v[48:63], v[150:153], v[162:165], v[48:63]
	s_waitcnt vmcnt(17)
	ds_write_b128 v68, v[94:97] offset:32256
	s_waitcnt vmcnt(16)
	ds_write_b128 v67, v[122:125] offset:32256
	s_waitcnt lgkmcnt(4)
	v_mfma_f32_32x32x16_bf16 v[32:47], v[150:153], v[166:169], v[32:47]
	v_mfma_f32_32x32x16_bf16 v[16:31], v[158:161], v[162:165], v[16:31]
	v_mfma_f32_32x32x16_bf16 v[0:15], v[158:161], v[166:169], v[0:15]
	s_waitcnt lgkmcnt(0)
	s_barrier
; #define G_LOAD(S, kt_) do { G_LD1(S##a0, S##b0, 0, kt_); G_LD1(S##a1, S##b1, 1, kt_); G_LD1(S##a2, S##b2, 2, kt_); G_LD1(S##a3, S##b3, 3, kt_); } while (0)
; #define G_STORE(S, buf_) do { G_ST1(S##a0, S##b0, 0, buf_); G_ST1(S##a1, S##b1, 1, buf_); G_ST1(S##a2, S##b2, 2, buf_); G_ST1(S##a3, S##b3, 3, buf_); } while (0)
; template <class AL, class BL>
; DI void gemm_core(AL al, BL bl, int m0, int n0, int K, char* smem, f32x16 (&acc)[2][2]) {
;     ...
;   G_LOAD(x, 0);
;   G_STORE(x, 0);
;   G_LOAD(x, 1);
;   G_LOAD(y, (nk > 2) ? 2 : 1);
;   __syncthreads();
;   for (int kt = 0; kt < nk; kt += 2) {
;     G_TILE(0, x, true, (kt + 3 < nk), kt + 3);
;     __syncthreads();
;     G_TILE(1, y, (kt + 2 < nk), (kt + 4 < nk), kt + 4);
;     __syncthreads();
	ds_read_b128 v[94:97], v66 offset:18432
	ds_read_b128 v[122:125], v64 offset:55296
	ds_read_b128 v[150:153], v66 offset:18464
	ds_read_b128 v[154:157], v64 offset:55328
	ds_read_b128 v[158:161], v64 offset:59904
	ds_read_b128 v[162:165], v64 offset:59936
	s_waitcnt lgkmcnt(4)
	v_mfma_f32_32x32x16_bf16 v[48:63], v[94:97], v[122:125], v[48:63]
	s_waitcnt lgkmcnt(1)
	v_mfma_f32_32x32x16_bf16 v[32:47], v[94:97], v[158:161], v[32:47]
	ds_read_b128 v[94:97], v66 offset:23040
	ds_read_b128 v[166:169], v66 offset:23072
	s_waitcnt lgkmcnt(1)
	v_mfma_f32_32x32x16_bf16 v[16:31], v[94:97], v[122:125], v[16:31]
	global_load_dwordx4 v[122:125], v[76:77], off offset:3072
	global_load_dwordx4 v[174:177], v[78:79], off offset:1024
	s_waitcnt vmcnt(17)
	ds_write_b128 v68, v[126:129]
	s_waitcnt vmcnt(16)
	ds_write_b128 v68, v[170:173] offset:36864
	v_mfma_f32_32x32x16_bf16 v[0:15], v[94:97], v[158:161], v[0:15]
	global_load_dwordx4 v[94:97], v[74:75], off offset:3072
	global_load_dwordx4 v[126:129], v[84:85], off offset:1024
	v_mfma_f32_32x32x16_bf16 v[48:63], v[150:153], v[154:157], v[48:63]
	v_mfma_f32_32x32x16_bf16 v[32:47], v[150:153], v[162:165], v[32:47]
	s_waitcnt lgkmcnt(2)
	v_mfma_f32_32x32x16_bf16 v[16:31], v[166:169], v[154:157], v[16:31]
	ds_read_b128 v[150:153], v66 offset:18496
	ds_read_b128 v[154:157], v66 offset:23104
	ds_read_b128 v[158:161], v64 offset:55360
	ds_read_b128 v[170:173], v64 offset:59968
	s_waitcnt vmcnt(17)
	ds_write_b128 v68, v[102:105] offset:4608
	s_waitcnt vmcnt(16)
	ds_write_b128 v68, v[130:133] offset:41472
	v_mfma_f32_32x32x16_bf16 v[0:15], v[166:169], v[162:165], v[0:15]
	global_load_dwordx4 v[102:105], v[70:71], off offset:3072
	global_load_dwordx4 v[130:133], v[82:83], off offset:1024
	s_waitcnt lgkmcnt(3)
	v_mfma_f32_32x32x16_bf16 v[48:63], v[150:153], v[158:161], v[48:63]
	s_waitcnt lgkmcnt(2)
	v_mfma_f32_32x32x16_bf16 v[32:47], v[150:153], v[170:173], v[32:47]
	v_mfma_f32_32x32x16_bf16 v[16:31], v[154:157], v[158:161], v[16:31]
	ds_read_b128 v[150:153], v66 offset:18528
	ds_read_b128 v[158:161], v66 offset:23136
	ds_read_b128 v[162:165], v64 offset:55392
	ds_read_b128 v[166:169], v64 offset:60000
	s_waitcnt vmcnt(17)
	ds_write_b128 v68, v[90:93] offset:9216
	s_waitcnt vmcnt(16)
	ds_write_b128 v68, v[110:113] offset:46080
	v_mfma_f32_32x32x16_bf16 v[0:15], v[154:157], v[170:173], v[0:15]
	global_load_dwordx4 v[90:93], v[72:73], off offset:3072
	global_load_dwordx4 v[110:113], v[80:81], off offset:1024
	s_waitcnt lgkmcnt(3)
	v_mfma_f32_32x32x16_bf16 v[48:63], v[150:153], v[162:165], v[48:63]
	s_waitcnt vmcnt(17)
	ds_write_b128 v68, v[98:101] offset:13824
	s_waitcnt vmcnt(16)
	ds_write_b128 v68, v[134:137] offset:50688
	s_waitcnt lgkmcnt(4)
	v_mfma_f32_32x32x16_bf16 v[32:47], v[150:153], v[166:169], v[32:47]
	v_mfma_f32_32x32x16_bf16 v[16:31], v[158:161], v[162:165], v[16:31]
	v_mfma_f32_32x32x16_bf16 v[0:15], v[158:161], v[166:169], v[0:15]
	s_waitcnt lgkmcnt(0)
	s_barrier
	ds_read_b128 v[98:101], v66
	ds_read_b128 v[134:137], v64 offset:36864
	ds_read_b128 v[150:153], v66 offset:32
	ds_read_b128 v[154:157], v64 offset:36896
	ds_read_b128 v[158:161], v64 offset:41472
	ds_read_b128 v[162:165], v64 offset:41504
	s_waitcnt lgkmcnt(4)
	v_mfma_f32_32x32x16_bf16 v[48:63], v[98:101], v[134:137], v[48:63]
	s_waitcnt lgkmcnt(1)
	v_mfma_f32_32x32x16_bf16 v[32:47], v[98:101], v[158:161], v[32:47]
	ds_read_b128 v[98:101], v66 offset:4608
	ds_read_b128 v[166:169], v66 offset:4640
	s_waitcnt lgkmcnt(1)
	v_mfma_f32_32x32x16_bf16 v[16:31], v[98:101], v[134:137], v[16:31]
	global_load_dwordx4 v[134:137], v[76:77], off offset:3200
	global_load_dwordx4 v[170:173], v[78:79], off offset:1152
	s_waitcnt vmcnt(17)
	ds_write_b128 v68, v[138:141] offset:18432
	s_waitcnt vmcnt(16)
	ds_write_b128 v68, v[178:181] offset:55296
	v_mfma_f32_32x32x16_bf16 v[0:15], v[98:101], v[158:161], v[0:15]
	global_load_dwordx4 v[98:101], v[74:75], off offset:3200
	global_load_dwordx4 v[138:141], v[84:85], off offset:1152
	v_mfma_f32_32x32x16_bf16 v[48:63], v[150:153], v[154:157], v[48:63]
	v_mfma_f32_32x32x16_bf16 v[32:47], v[150:153], v[162:165], v[32:47]
	s_waitcnt lgkmcnt(2)
	v_mfma_f32_32x32x16_bf16 v[16:31], v[166:169], v[154:157], v[16:31]
	ds_read_b128 v[150:153], v66 offset:64
	ds_read_b128 v[154:157], v66 offset:4672
	ds_read_b128 v[158:161], v64 offset:36928
	ds_read_b128 v[178:181], v64 offset:41536
	s_waitcnt vmcnt(17)
	ds_write_b128 v68, v[106:109] offset:23040
	s_waitcnt vmcnt(16)
	ds_write_b128 v68, v[142:145] offset:59904
	v_mfma_f32_32x32x16_bf16 v[0:15], v[166:169], v[162:165], v[0:15]
	global_load_dwordx4 v[106:109], v[70:71], off offset:3200
	global_load_dwordx4 v[142:145], v[82:83], off offset:1152
	s_waitcnt lgkmcnt(3)
	v_mfma_f32_32x32x16_bf16 v[48:63], v[150:153], v[158:161], v[48:63]
	s_waitcnt lgkmcnt(2)
	v_mfma_f32_32x32x16_bf16 v[32:47], v[150:153], v[178:181], v[32:47]
	v_mfma_f32_32x32x16_bf16 v[16:31], v[154:157], v[158:161], v[16:31]
	ds_read_b128 v[150:153], v66 offset:96
	ds_read_b128 v[158:161], v66 offset:4704
	ds_read_b128 v[162:165], v64 offset:36960
	ds_read_b128 v[166:169], v64 offset:41568
	s_waitcnt vmcnt(17)
	ds_write_b128 v68, v[114:117] offset:27648
	s_waitcnt vmcnt(16)
	ds_write_b128 v68, v[146:149] offset:64512
	v_mfma_f32_32x32x16_bf16 v[0:15], v[154:157], v[178:181], v[0:15]
	global_load_dwordx4 v[114:117], v[72:73], off offset:3200
	global_load_dwordx4 v[146:149], v[80:81], off offset:1152
	s_waitcnt lgkmcnt(3)
	v_mfma_f32_32x32x16_bf16 v[48:63], v[150:153], v[162:165], v[48:63]
	s_waitcnt vmcnt(17)
	ds_write_b128 v68, v[86:89] offset:32256
	s_waitcnt vmcnt(16)
	ds_write_b128 v67, v[118:121] offset:32256
	s_waitcnt lgkmcnt(4)
	v_mfma_f32_32x32x16_bf16 v[32:47], v[150:153], v[166:169], v[32:47]
	v_mfma_f32_32x32x16_bf16 v[16:31], v[158:161], v[162:165], v[16:31]
	v_mfma_f32_32x32x16_bf16 v[0:15], v[158:161], v[166:169], v[0:15]
	s_waitcnt lgkmcnt(0)
	s_barrier
; #define G_LOAD(S, kt_) do { G_LD1(S##a0, S##b0, 0, kt_); G_LD1(S##a1, S##b1, 1, kt_); G_LD1(S##a2, S##b2, 2, kt_); G_LD1(S##a3, S##b3, 3, kt_); } while (0)
; #define G_STORE(S, buf_) do { G_ST1(S##a0, S##b0, 0, buf_); G_ST1(S##a1, S##b1, 1, buf_); G_ST1(S##a2, S##b2, 2, buf_); G_ST1(S##a3, S##b3, 3, buf_); } while (0)
; template <class AL, class BL>
; DI void gemm_core(AL al, BL bl, int m0, int n0, int K, char* smem, f32x16 (&acc)[2][2]) {
;     ...
;   G_LOAD(x, 0);
;   G_STORE(x, 0);
;   G_LOAD(x, 1);
;   G_LOAD(y, (nk > 2) ? 2 : 1);
;   __syncthreads();
;   for (int kt = 0; kt < nk; kt += 2) {
;     G_TILE(0, x, true, (kt + 3 < nk), kt + 3);
;     __syncthreads();
;     G_TILE(1, y, (kt + 2 < nk), (kt + 4 < nk), kt + 4);
;     __syncthreads();
	ds_read_b128 v[86:89], v66 offset:18432
	ds_read_b128 v[118:121], v64 offset:55296
	ds_read_b128 v[150:153], v66 offset:18464
	ds_read_b128 v[154:157], v64 offset:55328
	ds_read_b128 v[158:161], v64 offset:59904
	ds_read_b128 v[162:165], v64 offset:59936
	s_waitcnt lgkmcnt(4)
	v_mfma_f32_32x32x16_bf16 v[48:63], v[86:89], v[118:121], v[48:63]
	s_waitcnt lgkmcnt(1)
	v_mfma_f32_32x32x16_bf16 v[32:47], v[86:89], v[158:161], v[32:47]
	ds_read_b128 v[86:89], v66 offset:23040
	ds_read_b128 v[166:169], v66 offset:23072
	s_waitcnt lgkmcnt(1)
	v_mfma_f32_32x32x16_bf16 v[16:31], v[86:89], v[118:121], v[16:31]
	global_load_dwordx4 v[118:121], v[76:77], off offset:3328
	global_load_dwordx4 v[178:181], v[78:79], off offset:1280
	s_waitcnt vmcnt(17)
	ds_write_b128 v68, v[122:125]
	s_waitcnt vmcnt(16)
	ds_write_b128 v68, v[174:177] offset:36864
	v_mfma_f32_32x32x16_bf16 v[0:15], v[86:89], v[158:161], v[0:15]
	global_load_dwordx4 v[86:89], v[74:75], off offset:3328
	global_load_dwordx4 v[122:125], v[84:85], off offset:1280
	v_mfma_f32_32x32x16_bf16 v[48:63], v[150:153], v[154:157], v[48:63]
	v_mfma_f32_32x32x16_bf16 v[32:47], v[150:153], v[162:165], v[32:47]
	s_waitcnt lgkmcnt(2)
	v_mfma_f32_32x32x16_bf16 v[16:31], v[166:169], v[154:157], v[16:31]
	ds_read_b128 v[150:153], v66 offset:18496
	ds_read_b128 v[154:157], v66 offset:23104
	ds_read_b128 v[158:161], v64 offset:55360
	ds_read_b128 v[174:177], v64 offset:59968
	s_waitcnt vmcnt(17)
	ds_write_b128 v68, v[94:97] offset:4608
	s_waitcnt vmcnt(16)
	ds_write_b128 v68, v[126:129] offset:41472
	v_mfma_f32_32x32x16_bf16 v[0:15], v[166:169], v[162:165], v[0:15]
	global_load_dwordx4 v[94:97], v[70:71], off offset:3328
	global_load_dwordx4 v[126:129], v[82:83], off offset:1280
	s_waitcnt lgkmcnt(3)
	v_mfma_f32_32x32x16_bf16 v[48:63], v[150:153], v[158:161], v[48:63]
	s_waitcnt lgkmcnt(2)
	v_mfma_f32_32x32x16_bf16 v[32:47], v[150:153], v[174:177], v[32:47]
	v_mfma_f32_32x32x16_bf16 v[16:31], v[154:157], v[158:161], v[16:31]
	ds_read_b128 v[150:153], v66 offset:18528
	ds_read_b128 v[158:161], v66 offset:23136
	ds_read_b128 v[162:165], v64 offset:55392
	ds_read_b128 v[166:169], v64 offset:60000
	s_waitcnt vmcnt(17)
	ds_write_b128 v68, v[102:105] offset:9216
	s_waitcnt vmcnt(16)
	ds_write_b128 v68, v[130:133] offset:46080
	v_mfma_f32_32x32x16_bf16 v[0:15], v[154:157], v[174:177], v[0:15]
	global_load_dwordx4 v[102:105], v[72:73], off offset:3328
	global_load_dwordx4 v[130:133], v[80:81], off offset:1280
	s_waitcnt lgkmcnt(3)
	v_mfma_f32_32x32x16_bf16 v[48:63], v[150:153], v[162:165], v[48:63]
	s_waitcnt vmcnt(17)
	ds_write_b128 v68, v[90:93] offset:13824
	s_waitcnt vmcnt(16)
	ds_write_b128 v68, v[110:113] offset:50688
	s_waitcnt lgkmcnt(4)
	v_mfma_f32_32x32x16_bf16 v[32:47], v[150:153], v[166:169], v[32:47]
	v_mfma_f32_32x32x16_bf16 v[16:31], v[158:161], v[162:165], v[16:31]
	v_mfma_f32_32x32x16_bf16 v[0:15], v[158:161], v[166:169], v[0:15]
	s_waitcnt lgkmcnt(0)
	s_barrier
	ds_read_b128 v[90:93], v66
	ds_read_b128 v[110:113], v64 offset:36864
	ds_read_b128 v[150:153], v66 offset:32
	ds_read_b128 v[154:157], v64 offset:36896
	ds_read_b128 v[158:161], v64 offset:41472
	ds_read_b128 v[162:165], v64 offset:41504
	s_waitcnt lgkmcnt(4)
	v_mfma_f32_32x32x16_bf16 v[48:63], v[90:93], v[110:113], v[48:63]
	s_waitcnt lgkmcnt(1)
	v_mfma_f32_32x32x16_bf16 v[32:47], v[90:93], v[158:161], v[32:47]
	ds_read_b128 v[90:93], v66 offset:4608
	ds_read_b128 v[166:169], v66 offset:4640
	s_waitcnt lgkmcnt(1)
	v_mfma_f32_32x32x16_bf16 v[16:31], v[90:93], v[110:113], v[16:31]
	global_load_dwordx4 v[110:113], v[76:77], off offset:3456
	global_load_dwordx4 v[174:177], v[78:79], off offset:1408
	s_waitcnt vmcnt(17)
	ds_write_b128 v68, v[134:137] offset:18432
	s_waitcnt vmcnt(16)
	ds_write_b128 v68, v[170:173] offset:55296
	v_mfma_f32_32x32x16_bf16 v[0:15], v[90:93], v[158:161], v[0:15]
	global_load_dwordx4 v[90:93], v[74:75], off offset:3456
	global_load_dwordx4 v[134:137], v[84:85], off offset:1408
	v_mfma_f32_32x32x16_bf16 v[48:63], v[150:153], v[154:157], v[48:63]
	v_mfma_f32_32x32x16_bf16 v[32:47], v[150:153], v[162:165], v[32:47]
	s_waitcnt lgkmcnt(2)
	v_mfma_f32_32x32x16_bf16 v[16:31], v[166:169], v[154:157], v[16:31]
	ds_read_b128 v[150:153], v66 offset:64
	ds_read_b128 v[154:157], v66 offset:4672
	ds_read_b128 v[158:161], v64 offset:36928
	ds_read_b128 v[170:173], v64 offset:41536
	s_waitcnt vmcnt(17)
	ds_write_b128 v68, v[98:101] offset:23040
	s_waitcnt vmcnt(16)
	ds_write_b128 v68, v[138:141] offset:59904
	v_mfma_f32_32x32x16_bf16 v[0:15], v[166:169], v[162:165], v[0:15]
	global_load_dwordx4 v[98:101], v[70:71], off offset:3456
	global_load_dwordx4 v[138:141], v[82:83], off offset:1408
	s_waitcnt lgkmcnt(3)
	v_mfma_f32_32x32x16_bf16 v[48:63], v[150:153], v[158:161], v[48:63]
	s_waitcnt lgkmcnt(2)
	v_mfma_f32_32x32x16_bf16 v[32:47], v[150:153], v[170:173], v[32:47]
	v_mfma_f32_32x32x16_bf16 v[16:31], v[154:157], v[158:161], v[16:31]
	ds_read_b128 v[150:153], v66 offset:96
	ds_read_b128 v[158:161], v66 offset:4704
	ds_read_b128 v[162:165], v64 offset:36960
	ds_read_b128 v[166:169], v64 offset:41568
	s_waitcnt vmcnt(17)
	ds_write_b128 v68, v[106:109] offset:27648
	s_waitcnt vmcnt(16)
	ds_write_b128 v68, v[142:145] offset:64512
	v_mfma_f32_32x32x16_bf16 v[0:15], v[154:157], v[170:173], v[0:15]
	global_load_dwordx4 v[106:109], v[72:73], off offset:3456
	global_load_dwordx4 v[142:145], v[80:81], off offset:1408
	s_waitcnt lgkmcnt(3)
	v_mfma_f32_32x32x16_bf16 v[48:63], v[150:153], v[162:165], v[48:63]
	s_waitcnt vmcnt(17)
	ds_write_b128 v68, v[114:117] offset:32256
	s_waitcnt vmcnt(16)
	ds_write_b128 v67, v[146:149] offset:32256
	s_waitcnt lgkmcnt(4)
	v_mfma_f32_32x32x16_bf16 v[32:47], v[150:153], v[166:169], v[32:47]
	v_mfma_f32_32x32x16_bf16 v[16:31], v[158:161], v[162:165], v[16:31]
	v_mfma_f32_32x32x16_bf16 v[0:15], v[158:161], v[166:169], v[0:15]
	s_waitcnt lgkmcnt(0)
	s_barrier
; #define G_LOAD(S, kt_) do { G_LD1(S##a0, S##b0, 0, kt_); G_LD1(S##a1, S##b1, 1, kt_); G_LD1(S##a2, S##b2, 2, kt_); G_LD1(S##a3, S##b3, 3, kt_); } while (0)
; #define G_STORE(S, buf_) do { G_ST1(S##a0, S##b0, 0, buf_); G_ST1(S##a1, S##b1, 1, buf_); G_ST1(S##a2, S##b2, 2, buf_); G_ST1(S##a3, S##b3, 3, buf_); } while (0)
; template <class AL, class BL>
; DI void gemm_core(AL al, BL bl, int m0, int n0, int K, char* smem, f32x16 (&acc)[2][2]) {
;     ...
;   G_LOAD(x, 0);
;   G_STORE(x, 0);
;   G_LOAD(x, 1);
;   G_LOAD(y, (nk > 2) ? 2 : 1);
;   __syncthreads();
;   for (int kt = 0; kt < nk; kt += 2) {
;     G_TILE(0, x, true, (kt + 3 < nk), kt + 3);
;     __syncthreads();
;     G_TILE(1, y, (kt + 2 < nk), (kt + 4 < nk), kt + 4);
;     __syncthreads();
;   }
	ds_read_b128 v[114:117], v66 offset:18432
	ds_read_b128 v[146:149], v64 offset:55296
	ds_read_b128 v[150:153], v66 offset:18464
	ds_read_b128 v[154:157], v64 offset:55328
	ds_read_b128 v[158:161], v64 offset:59904
	ds_read_b128 v[162:165], v64 offset:59936
	s_waitcnt lgkmcnt(4)
	v_mfma_f32_32x32x16_bf16 v[48:63], v[114:117], v[146:149], v[48:63]
	s_waitcnt lgkmcnt(1)
	v_mfma_f32_32x32x16_bf16 v[32:47], v[114:117], v[158:161], v[32:47]
	ds_read_b128 v[114:117], v66 offset:23040
	ds_read_b128 v[166:169], v66 offset:23072
	s_waitcnt lgkmcnt(1)
	v_mfma_f32_32x32x16_bf16 v[16:31], v[114:117], v[146:149], v[16:31]
	global_load_dwordx4 v[146:149], v[76:77], off offset:3584
	global_load_dwordx4 v[170:173], v[78:79], off offset:1536
	s_waitcnt vmcnt(17)
	ds_write_b128 v68, v[118:121]
	s_waitcnt vmcnt(16)
	ds_write_b128 v68, v[178:181] offset:36864
	v_mfma_f32_32x32x16_bf16 v[0:15], v[114:117], v[158:161], v[0:15]
	global_load_dwordx4 v[114:117], v[74:75], off offset:3584
	global_load_dwordx4 v[118:121], v[84:85], off offset:1536
	v_mfma_f32_32x32x16_bf16 v[48:63], v[150:153], v[154:157], v[48:63]
	v_mfma_f32_32x32x16_bf16 v[32:47], v[150:153], v[162:165], v[32:47]
	s_waitcnt lgkmcnt(2)
	v_mfma_f32_32x32x16_bf16 v[16:31], v[166:169], v[154:157], v[16:31]
	ds_read_b128 v[150:153], v66 offset:18496
	ds_read_b128 v[154:157], v66 offset:23104
	ds_read_b128 v[158:161], v64 offset:55360
	ds_read_b128 v[178:181], v64 offset:59968
	s_waitcnt vmcnt(17)
	ds_write_b128 v68, v[86:89] offset:4608
	s_waitcnt vmcnt(16)
	ds_write_b128 v68, v[122:125] offset:41472
	v_mfma_f32_32x32x16_bf16 v[0:15], v[166:169], v[162:165], v[0:15]
	global_load_dwordx4 v[86:89], v[70:71], off offset:3584
	global_load_dwordx4 v[122:125], v[82:83], off offset:1536
	s_waitcnt lgkmcnt(3)
	v_mfma_f32_32x32x16_bf16 v[48:63], v[150:153], v[158:161], v[48:63]
	s_waitcnt lgkmcnt(2)
	v_mfma_f32_32x32x16_bf16 v[32:47], v[150:153], v[178:181], v[32:47]
	v_mfma_f32_32x32x16_bf16 v[16:31], v[154:157], v[158:161], v[16:31]
	ds_read_b128 v[150:153], v66 offset:18528
	ds_read_b128 v[158:161], v66 offset:23136
	ds_read_b128 v[162:165], v64 offset:55392
	ds_read_b128 v[166:169], v64 offset:60000
	s_waitcnt vmcnt(17)
	ds_write_b128 v68, v[94:97] offset:9216
	s_waitcnt vmcnt(16)
	ds_write_b128 v68, v[126:129] offset:46080
	v_mfma_f32_32x32x16_bf16 v[0:15], v[154:157], v[178:181], v[0:15]
	global_load_dwordx4 v[94:97], v[72:73], off offset:3584
	global_load_dwordx4 v[126:129], v[80:81], off offset:1536
	s_waitcnt lgkmcnt(3)
	v_mfma_f32_32x32x16_bf16 v[48:63], v[150:153], v[162:165], v[48:63]
	s_waitcnt vmcnt(17)
	ds_write_b128 v68, v[102:105] offset:13824
	s_waitcnt vmcnt(16)
	ds_write_b128 v68, v[130:133] offset:50688
	s_waitcnt lgkmcnt(4)
	v_mfma_f32_32x32x16_bf16 v[32:47], v[150:153], v[166:169], v[32:47]
	v_mfma_f32_32x32x16_bf16 v[16:31], v[158:161], v[162:165], v[16:31]
	v_mfma_f32_32x32x16_bf16 v[0:15], v[158:161], v[166:169], v[0:15]
	s_waitcnt lgkmcnt(0)
	s_barrier
	ds_read_b128 v[102:105], v66
	ds_read_b128 v[130:133], v64 offset:36864
	ds_read_b128 v[150:153], v66 offset:32
	ds_read_b128 v[154:157], v64 offset:36896
	ds_read_b128 v[158:161], v64 offset:41472
	ds_read_b128 v[162:165], v64 offset:41504
	s_waitcnt lgkmcnt(4)
	v_mfma_f32_32x32x16_bf16 v[48:63], v[102:105], v[130:133], v[48:63]
	s_waitcnt lgkmcnt(1)
	v_mfma_f32_32x32x16_bf16 v[32:47], v[102:105], v[158:161], v[32:47]
	ds_read_b128 v[102:105], v66 offset:4608
	ds_read_b128 v[166:169], v66 offset:4640
	s_waitcnt lgkmcnt(1)
	v_mfma_f32_32x32x16_bf16 v[16:31], v[102:105], v[130:133], v[16:31]
	global_load_dwordx4 v[130:133], v[76:77], off offset:3712
	global_load_dwordx4 v[178:181], v[78:79], off offset:1664
	s_waitcnt vmcnt(17)
	ds_write_b128 v68, v[110:113] offset:18432
	s_waitcnt vmcnt(16)
	ds_write_b128 v68, v[174:177] offset:55296
	v_mfma_f32_32x32x16_bf16 v[0:15], v[102:105], v[158:161], v[0:15]
	global_load_dwordx4 v[102:105], v[74:75], off offset:3712
	global_load_dwordx4 v[110:113], v[84:85], off offset:1664
	v_mfma_f32_32x32x16_bf16 v[48:63], v[150:153], v[154:157], v[48:63]
	v_mfma_f32_32x32x16_bf16 v[32:47], v[150:153], v[162:165], v[32:47]
	s_waitcnt lgkmcnt(2)
	v_mfma_f32_32x32x16_bf16 v[16:31], v[166:169], v[154:157], v[16:31]
	ds_read_b128 v[150:153], v66 offset:64
	ds_read_b128 v[154:157], v66 offset:4672
	ds_read_b128 v[158:161], v64 offset:36928
	ds_read_b128 v[174:177], v64 offset:41536
	s_waitcnt vmcnt(17)
	ds_write_b128 v68, v[90:93] offset:23040
	s_waitcnt vmcnt(16)
	ds_write_b128 v68, v[134:137] offset:59904
	v_mfma_f32_32x32x16_bf16 v[0:15], v[166:169], v[162:165], v[0:15]
	global_load_dwordx4 v[90:93], v[70:71], off offset:3712
	global_load_dwordx4 v[134:137], v[82:83], off offset:1664
	s_waitcnt lgkmcnt(3)
	v_mfma_f32_32x32x16_bf16 v[48:63], v[150:153], v[158:161], v[48:63]
	s_waitcnt lgkmcnt(2)
	v_mfma_f32_32x32x16_bf16 v[32:47], v[150:153], v[174:177], v[32:47]
	v_mfma_f32_32x32x16_bf16 v[16:31], v[154:157], v[158:161], v[16:31]
	ds_read_b128 v[150:153], v66 offset:96
	ds_read_b128 v[158:161], v66 offset:4704
	ds_read_b128 v[162:165], v64 offset:36960
	ds_read_b128 v[166:169], v64 offset:41568
	s_waitcnt vmcnt(17)
	ds_write_b128 v68, v[98:101] offset:27648
	s_waitcnt vmcnt(16)
	ds_write_b128 v68, v[138:141] offset:64512
	v_mfma_f32_32x32x16_bf16 v[0:15], v[154:157], v[174:177], v[0:15]
	global_load_dwordx4 v[98:101], v[72:73], off offset:3712
	global_load_dwordx4 v[138:141], v[80:81], off offset:1664
	s_waitcnt lgkmcnt(3)
	v_mfma_f32_32x32x16_bf16 v[48:63], v[150:153], v[162:165], v[48:63]
	s_waitcnt vmcnt(17)
	ds_write_b128 v68, v[106:109] offset:32256
	s_waitcnt vmcnt(16)
	ds_write_b128 v67, v[142:145] offset:32256
	s_waitcnt lgkmcnt(4)
	v_mfma_f32_32x32x16_bf16 v[32:47], v[150:153], v[166:169], v[32:47]
	v_mfma_f32_32x32x16_bf16 v[16:31], v[158:161], v[162:165], v[16:31]
	v_mfma_f32_32x32x16_bf16 v[0:15], v[158:161], v[166:169], v[0:15]
	s_waitcnt lgkmcnt(0)
	s_barrier
; #define G_LOAD(S, kt_) do { G_LD1(S##a0, S##b0, 0, kt_); G_LD1(S##a1, S##b1, 1, kt_); G_LD1(S##a2, S##b2, 2, kt_); G_LD1(S##a3, S##b3, 3, kt_); } while (0)
; #define G_STORE(S, buf_) do { G_ST1(S##a0, S##b0, 0, buf_); G_ST1(S##a1, S##b1, 1, buf_); G_ST1(S##a2, S##b2, 2, buf_); G_ST1(S##a3, S##b3, 3, buf_); } while (0)
; template <class AL, class BL>
; DI void gemm_core(AL al, BL bl, int m0, int n0, int K, char* smem, f32x16 (&acc)[2][2]) {
;     ...
;   G_LOAD(x, 0);
;   G_STORE(x, 0);
;   G_LOAD(x, 1);
;   G_LOAD(y, (nk > 2) ? 2 : 1);
;   __syncthreads();
;   for (int kt = 0; kt < nk; kt += 2) {
;     G_TILE(0, x, true, (kt + 3 < nk), kt + 3);
;     __syncthreads();
;     G_TILE(1, y, (kt + 2 < nk), (kt + 4 < nk), kt + 4);
;     __syncthreads();
;   }
	ds_read_b128 v[106:109], v66 offset:18432
	ds_read_b128 v[142:145], v64 offset:55296
	ds_read_b128 v[150:153], v66 offset:18464
	ds_read_b128 v[154:157], v64 offset:55328
	ds_read_b128 v[158:161], v64 offset:59904
	ds_read_b128 v[162:165], v64 offset:59936
	s_waitcnt lgkmcnt(4)
	v_mfma_f32_32x32x16_bf16 v[48:63], v[106:109], v[142:145], v[48:63]
	s_waitcnt lgkmcnt(1)
	v_mfma_f32_32x32x16_bf16 v[32:47], v[106:109], v[158:161], v[32:47]
	ds_read_b128 v[106:109], v66 offset:23040
	ds_read_b128 v[166:169], v66 offset:23072
	s_waitcnt lgkmcnt(1)
	v_mfma_f32_32x32x16_bf16 v[16:31], v[106:109], v[142:145], v[16:31]
	global_load_dwordx4 v[142:145], v[76:77], off offset:3840
	global_load_dwordx4 v[174:177], v[78:79], off offset:1792
	s_waitcnt vmcnt(17)
	ds_write_b128 v68, v[146:149]
	s_waitcnt vmcnt(16)
	ds_write_b128 v68, v[170:173] offset:36864
	v_mfma_f32_32x32x16_bf16 v[0:15], v[106:109], v[158:161], v[0:15]
	global_load_dwordx4 v[106:109], v[74:75], off offset:3840
	global_load_dwordx4 v[146:149], v[84:85], off offset:1792
	v_mfma_f32_32x32x16_bf16 v[48:63], v[150:153], v[154:157], v[48:63]
	v_mfma_f32_32x32x16_bf16 v[32:47], v[150:153], v[162:165], v[32:47]
	s_waitcnt lgkmcnt(2)
	v_mfma_f32_32x32x16_bf16 v[16:31], v[166:169], v[154:157], v[16:31]
	ds_read_b128 v[150:153], v66 offset:18496
	ds_read_b128 v[154:157], v66 offset:23104
	ds_read_b128 v[158:161], v64 offset:55360
	ds_read_b128 v[170:173], v64 offset:59968
	s_waitcnt vmcnt(17)
	ds_write_b128 v68, v[114:117] offset:4608
	s_waitcnt vmcnt(16)
	ds_write_b128 v68, v[118:121] offset:41472
	v_mfma_f32_32x32x16_bf16 v[0:15], v[166:169], v[162:165], v[0:15]
	global_load_dwordx4 v[114:117], v[70:71], off offset:3840
	global_load_dwordx4 v[118:121], v[82:83], off offset:1792
	s_waitcnt lgkmcnt(3)
	v_mfma_f32_32x32x16_bf16 v[48:63], v[150:153], v[158:161], v[48:63]
	s_waitcnt lgkmcnt(2)
	v_mfma_f32_32x32x16_bf16 v[32:47], v[150:153], v[170:173], v[32:47]
	v_mfma_f32_32x32x16_bf16 v[16:31], v[154:157], v[158:161], v[16:31]
	ds_read_b128 v[150:153], v66 offset:18528
	ds_read_b128 v[158:161], v66 offset:23136
	ds_read_b128 v[162:165], v64 offset:55392
	ds_read_b128 v[166:169], v64 offset:60000
	s_waitcnt vmcnt(17)
	ds_write_b128 v68, v[86:89] offset:9216
	s_waitcnt vmcnt(16)
	ds_write_b128 v68, v[122:125] offset:46080
	v_mfma_f32_32x32x16_bf16 v[0:15], v[154:157], v[170:173], v[0:15]
	global_load_dwordx4 v[86:89], v[72:73], off offset:3840
	global_load_dwordx4 v[122:125], v[80:81], off offset:1792
	s_waitcnt lgkmcnt(3)
	v_mfma_f32_32x32x16_bf16 v[48:63], v[150:153], v[162:165], v[48:63]
	s_waitcnt vmcnt(17)
	ds_write_b128 v68, v[94:97] offset:13824
	s_waitcnt vmcnt(16)
	ds_write_b128 v68, v[126:129] offset:50688
	s_waitcnt lgkmcnt(4)
	v_mfma_f32_32x32x16_bf16 v[32:47], v[150:153], v[166:169], v[32:47]
	v_mfma_f32_32x32x16_bf16 v[16:31], v[158:161], v[162:165], v[16:31]
	v_mfma_f32_32x32x16_bf16 v[0:15], v[158:161], v[166:169], v[0:15]
	s_waitcnt lgkmcnt(0)
	s_barrier
	ds_read_b128 v[94:97], v66
	ds_read_b128 v[126:129], v64 offset:36864
	ds_read_b128 v[150:153], v66 offset:32
	ds_read_b128 v[154:157], v64 offset:36896
	ds_read_b128 v[158:161], v64 offset:41472
	ds_read_b128 v[162:165], v64 offset:41504
	s_waitcnt lgkmcnt(4)
	v_mfma_f32_32x32x16_bf16 v[48:63], v[94:97], v[126:129], v[48:63]
	s_waitcnt lgkmcnt(1)
	v_mfma_f32_32x32x16_bf16 v[32:47], v[94:97], v[158:161], v[32:47]
	ds_read_b128 v[94:97], v66 offset:4608
	ds_read_b128 v[166:169], v66 offset:4640
	s_waitcnt lgkmcnt(1)
	v_mfma_f32_32x32x16_bf16 v[16:31], v[94:97], v[126:129], v[16:31]
	global_load_dwordx4 v[126:129], v[76:77], off offset:3968
	s_nop 0
	global_load_dwordx4 v[76:79], v[78:79], off offset:1920
	s_waitcnt vmcnt(17)
	ds_write_b128 v68, v[130:133] offset:18432
	s_waitcnt vmcnt(16)
	ds_write_b128 v68, v[178:181] offset:55296
	v_mfma_f32_32x32x16_bf16 v[0:15], v[94:97], v[158:161], v[0:15]
	global_load_dwordx4 v[94:97], v[74:75], off offset:3968
	global_load_dwordx4 v[130:133], v[84:85], off offset:1920
	v_mfma_f32_32x32x16_bf16 v[48:63], v[150:153], v[154:157], v[48:63]
	v_mfma_f32_32x32x16_bf16 v[32:47], v[150:153], v[162:165], v[32:47]
	s_waitcnt lgkmcnt(2)
	v_mfma_f32_32x32x16_bf16 v[16:31], v[166:169], v[154:157], v[16:31]
	ds_read_b128 v[150:153], v66 offset:64
	ds_read_b128 v[154:157], v66 offset:4672
	ds_read_b128 v[158:161], v64 offset:36928
	ds_read_b128 v[170:173], v64 offset:41536
	s_waitcnt vmcnt(17)
	ds_write_b128 v68, v[102:105] offset:23040
	s_waitcnt vmcnt(16)
	ds_write_b128 v68, v[110:113] offset:59904
	v_mfma_f32_32x32x16_bf16 v[0:15], v[166:169], v[162:165], v[0:15]
	global_load_dwordx4 v[102:105], v[70:71], off offset:3968
	s_nop 0
	global_load_dwordx4 v[82:85], v[82:83], off offset:1920
	s_waitcnt lgkmcnt(3)
	v_mfma_f32_32x32x16_bf16 v[48:63], v[150:153], v[158:161], v[48:63]
	s_waitcnt lgkmcnt(2)
	v_mfma_f32_32x32x16_bf16 v[32:47], v[150:153], v[170:173], v[32:47]
	v_mfma_f32_32x32x16_bf16 v[16:31], v[154:157], v[158:161], v[16:31]
	ds_read_b128 v[110:113], v66 offset:96
	ds_read_b128 v[150:153], v66 offset:4704
	ds_read_b128 v[158:161], v64 offset:36960
	ds_read_b128 v[162:165], v64 offset:41568
	s_waitcnt vmcnt(17)
	ds_write_b128 v68, v[90:93] offset:27648
	s_waitcnt vmcnt(16)
	ds_write_b128 v68, v[134:137] offset:64512
	v_mfma_f32_32x32x16_bf16 v[0:15], v[154:157], v[170:173], v[0:15]
	global_load_dwordx4 v[70:73], v[72:73], off offset:3968
	s_nop 0
	global_load_dwordx4 v[90:93], v[80:81], off offset:1920
	s_waitcnt lgkmcnt(3)
	v_mfma_f32_32x32x16_bf16 v[48:63], v[110:113], v[158:161], v[48:63]
	s_waitcnt vmcnt(17)
	ds_write_b128 v68, v[98:101] offset:32256
	s_waitcnt vmcnt(16)
	ds_write_b128 v67, v[138:141] offset:32256
	s_waitcnt lgkmcnt(4)
	v_mfma_f32_32x32x16_bf16 v[32:47], v[110:113], v[162:165], v[32:47]
	v_mfma_f32_32x32x16_bf16 v[16:31], v[150:153], v[158:161], v[16:31]
	v_mfma_f32_32x32x16_bf16 v[0:15], v[150:153], v[162:165], v[0:15]
	s_waitcnt lgkmcnt(0)
	s_barrier
; #define G_LOAD(S, kt_) do { G_LD1(S##a0, S##b0, 0, kt_); G_LD1(S##a1, S##b1, 1, kt_); G_LD1(S##a2, S##b2, 2, kt_); G_LD1(S##a3, S##b3, 3, kt_); } while (0)
; #define G_STORE(S, buf_) do { G_ST1(S##a0, S##b0, 0, buf_); G_ST1(S##a1, S##b1, 1, buf_); G_ST1(S##a2, S##b2, 2, buf_); G_ST1(S##a3, S##b3, 3, buf_); } while (0)
; template <class AL, class BL>
; DI void gemm_core(AL al, BL bl, int m0, int n0, int K, char* smem, f32x16 (&acc)[2][2]) {
;     ...
;   G_LOAD(x, 0);
;   G_STORE(x, 0);
;   G_LOAD(x, 1);
;   G_LOAD(y, (nk > 2) ? 2 : 1);
;   __syncthreads();
;   for (int kt = 0; kt < nk; kt += 2) {
;     G_TILE(0, x, true, (kt + 3 < nk), kt + 3);
;     __syncthreads();
;     G_TILE(1, y, (kt + 2 < nk), (kt + 4 < nk), kt + 4);
;     __syncthreads();
;   }
	ds_read_b128 v[98:101], v66 offset:18432
	ds_read_b128 v[110:113], v64 offset:55296
	ds_read_b128 v[134:137], v66 offset:18464
	ds_read_b128 v[138:141], v64 offset:55328
	ds_read_b128 v[150:153], v64 offset:59904
	ds_read_b128 v[154:157], v64 offset:59936
	s_waitcnt lgkmcnt(4)
	v_mfma_f32_32x32x16_bf16 v[48:63], v[98:101], v[110:113], v[48:63]
	s_waitcnt lgkmcnt(1)
	v_mfma_f32_32x32x16_bf16 v[32:47], v[98:101], v[150:153], v[32:47]
	ds_read_b128 v[98:101], v66 offset:23040
	ds_read_b128 v[158:161], v66 offset:23072
	s_waitcnt vmcnt(15)
	ds_write_b128 v68, v[142:145]
	s_waitcnt vmcnt(14)
	ds_write_b128 v68, v[174:177] offset:36864
	s_waitcnt lgkmcnt(3)
	v_mfma_f32_32x32x16_bf16 v[16:31], v[98:101], v[110:113], v[16:31]
	v_mfma_f32_32x32x16_bf16 v[0:15], v[98:101], v[150:153], v[0:15]
	v_mfma_f32_32x32x16_bf16 v[48:63], v[134:137], v[138:141], v[48:63]
	v_mfma_f32_32x32x16_bf16 v[32:47], v[134:137], v[154:157], v[32:47]
	s_waitcnt lgkmcnt(2)
	v_mfma_f32_32x32x16_bf16 v[16:31], v[158:161], v[138:141], v[16:31]
	ds_read_b128 v[98:101], v66 offset:18496
	ds_read_b128 v[110:113], v66 offset:23104
	ds_read_b128 v[134:137], v64 offset:55360
	ds_read_b128 v[138:141], v64 offset:59968
	s_waitcnt vmcnt(13)
	ds_write_b128 v68, v[106:109] offset:4608
	s_waitcnt vmcnt(12)
	ds_write_b128 v68, v[146:149] offset:41472
	v_mfma_f32_32x32x16_bf16 v[0:15], v[158:161], v[154:157], v[0:15]
	s_waitcnt lgkmcnt(3)
	v_mfma_f32_32x32x16_bf16 v[48:63], v[98:101], v[134:137], v[48:63]
	s_waitcnt lgkmcnt(2)
	v_mfma_f32_32x32x16_bf16 v[32:47], v[98:101], v[138:141], v[32:47]
	v_mfma_f32_32x32x16_bf16 v[16:31], v[110:113], v[134:137], v[16:31]
	ds_read_b128 v[98:101], v66 offset:18528
	ds_read_b128 v[106:109], v66 offset:23136
	ds_read_b128 v[134:137], v64 offset:55392
	ds_read_b128 v[142:145], v64 offset:60000
	s_waitcnt vmcnt(11)
	ds_write_b128 v68, v[114:117] offset:9216
	s_waitcnt vmcnt(10)
	ds_write_b128 v68, v[118:121] offset:46080
	v_mfma_f32_32x32x16_bf16 v[0:15], v[110:113], v[138:141], v[0:15]
	s_waitcnt lgkmcnt(3)
	v_mfma_f32_32x32x16_bf16 v[48:63], v[98:101], v[134:137], v[48:63]
	s_waitcnt vmcnt(9)
	ds_write_b128 v68, v[86:89] offset:13824
	s_waitcnt vmcnt(8)
	ds_write_b128 v68, v[122:125] offset:50688
	s_waitcnt lgkmcnt(4)
	v_mfma_f32_32x32x16_bf16 v[32:47], v[98:101], v[142:145], v[32:47]
	v_mfma_f32_32x32x16_bf16 v[16:31], v[106:109], v[134:137], v[16:31]
	v_mfma_f32_32x32x16_bf16 v[0:15], v[106:109], v[142:145], v[0:15]
	s_waitcnt lgkmcnt(0)
	s_barrier
	ds_read_b128 v[86:89], v66
	ds_read_b128 v[98:101], v64 offset:36864
	ds_read_b128 v[106:109], v66 offset:32
	ds_read_b128 v[110:113], v64 offset:36896
	ds_read_b128 v[114:117], v64 offset:41472
	ds_read_b128 v[118:121], v64 offset:41504
	s_waitcnt lgkmcnt(4)
	v_mfma_f32_32x32x16_bf16 v[48:63], v[86:89], v[98:101], v[48:63]
	s_waitcnt lgkmcnt(1)
	v_mfma_f32_32x32x16_bf16 v[32:47], v[86:89], v[114:117], v[32:47]
	ds_read_b128 v[86:89], v66 offset:4608
	ds_read_b128 v[122:125], v66 offset:4640
	s_waitcnt vmcnt(7)
	ds_write_b128 v68, v[126:129] offset:18432
	s_waitcnt vmcnt(6)
	ds_write_b128 v68, v[76:79] offset:55296
	s_waitcnt lgkmcnt(3)
	v_mfma_f32_32x32x16_bf16 v[16:31], v[86:89], v[98:101], v[16:31]
	v_mfma_f32_32x32x16_bf16 v[0:15], v[86:89], v[114:117], v[0:15]
	ds_read_b128 v[74:77], v66 offset:64
	ds_read_b128 v[78:81], v66 offset:4672
	ds_read_b128 v[86:89], v64 offset:36928
	ds_read_b128 v[98:101], v64 offset:41536
	v_mfma_f32_32x32x16_bf16 v[48:63], v[106:109], v[110:113], v[48:63]
	s_waitcnt vmcnt(5)
	ds_write_b128 v68, v[94:97] offset:23040
	s_waitcnt vmcnt(4)
	ds_write_b128 v68, v[130:133] offset:59904
	v_mfma_f32_32x32x16_bf16 v[32:47], v[106:109], v[118:121], v[32:47]
	s_waitcnt lgkmcnt(8)
	v_mfma_f32_32x32x16_bf16 v[16:31], v[122:125], v[110:113], v[16:31]
	v_mfma_f32_32x32x16_bf16 v[0:15], v[122:125], v[118:121], v[0:15]
	s_waitcnt lgkmcnt(3)
	v_mfma_f32_32x32x16_bf16 v[48:63], v[74:77], v[86:89], v[48:63]
	s_waitcnt lgkmcnt(2)
	v_mfma_f32_32x32x16_bf16 v[32:47], v[74:77], v[98:101], v[32:47]
	v_mfma_f32_32x32x16_bf16 v[16:31], v[78:81], v[86:89], v[16:31]
	ds_read_b128 v[74:77], v66 offset:96
	ds_read_b128 v[86:89], v66 offset:4704
	ds_read_b128 v[94:97], v64 offset:36960
	ds_read_b128 v[106:109], v64 offset:41568
	s_waitcnt vmcnt(3)
	ds_write_b128 v68, v[102:105] offset:27648
	s_waitcnt vmcnt(2)
	ds_write_b128 v68, v[82:85] offset:64512
	v_mfma_f32_32x32x16_bf16 v[0:15], v[78:81], v[98:101], v[0:15]
	s_waitcnt lgkmcnt(3)
	v_mfma_f32_32x32x16_bf16 v[48:63], v[74:77], v[94:97], v[48:63]
	s_waitcnt vmcnt(1)
	ds_write_b128 v68, v[70:73] offset:32256
	s_waitcnt vmcnt(0)
	ds_write_b128 v67, v[90:93] offset:32256
	s_waitcnt lgkmcnt(4)
	v_mfma_f32_32x32x16_bf16 v[32:47], v[74:77], v[106:109], v[32:47]
	v_mfma_f32_32x32x16_bf16 v[16:31], v[86:89], v[94:97], v[16:31]
	v_mfma_f32_32x32x16_bf16 v[0:15], v[86:89], v[106:109], v[0:15]
	s_waitcnt lgkmcnt(0)
	s_barrier
; DI u16 f2bf(float x) { return (u16)(pack2(x, 0.f) & 0xffffu); }
; DI int opaque_tid() { int t = threadIdx.x; asm volatile("" : "+v"(t)); return t; }
; DI int crow(int i, int h) { return (i & 3) + 8 * (i >> 2) + 4 * h; }
; template <class AL, class BL>
; DI void gemm_core(AL al, BL bl, int m0, int n0, int K, char* smem, f32x16 (&acc)[2][2]) {
;     ...
;   for (int kt = 0; kt < nk; kt += 2) {
;     G_TILE(0, x, true, (kt + 3 < nk), kt + 3);
;     __syncthreads();
;     G_TILE(1, y, (kt + 2 < nk), (kt + 4 < nk), kt + 4);
;     __syncthreads();
;   }
; template <class F>
; DI void epi_bf16_tile(const f32x16 (&acc)[2][2], int m0, int n0, u16* dst0, long ld, char* smem, F f) {
;   const int tid = opaque_tid(), lane = tid & 63, w = tid >> 6, wm = w >> 1, wn = w & 1, h = lane >> 5;
;   u16* T = (u16*)smem;
; #pragma unroll
;   for (int mt = 0; mt < 2; mt++)
; #pragma unroll
;     for (int nt = 0; nt < 2; nt++)
; #pragma unroll
;       for (int i = 0; i < 16; i++) {
;         const int ml = wm * 64 + mt * 32 + crow(i, h), nl = wn * 64 + nt * 32 + (lane & 31);
;         T[ml * 136 + nl] = f2bf(f(m0 + ml, n0 + nl, acc[mt][nt][i]));
;       }
;   __syncthreads();
; #pragma unroll
;   for (int j = 0; j < 8; j++) {
;     const int idx = tid + 256 * j, row = idx >> 4, ch = idx & 15;
;     *(uint4*)(dst0 + (long)row * ld + ch * 8) = *(const uint4*)(T + row * 136 + ch * 8);
	ds_read_b128 v[68:71], v66 offset:18432
	ds_read_b128 v[72:75], v64 offset:55296
	ds_read_b128 v[76:79], v66 offset:18464
	ds_read_b128 v[80:83], v64 offset:55328
	ds_read_b128 v[84:87], v64 offset:59904
	ds_read_b128 v[88:91], v64 offset:59936
	s_waitcnt lgkmcnt(4)
	v_mfma_f32_32x32x16_bf16 v[48:63], v[68:71], v[72:75], v[48:63]
	s_waitcnt lgkmcnt(1)
	v_mfma_f32_32x32x16_bf16 v[32:47], v[68:71], v[84:87], v[32:47]
	ds_read_b128 v[68:71], v66 offset:23040
	ds_read_b128 v[92:95], v66 offset:23072
	s_waitcnt lgkmcnt(1)
	v_mfma_f32_32x32x16_bf16 v[16:31], v[68:71], v[72:75], v[16:31]
	v_mfma_f32_32x32x16_bf16 v[0:15], v[68:71], v[84:87], v[0:15]
	v_mfma_f32_32x32x16_bf16 v[48:63], v[76:79], v[80:83], v[48:63]
	v_mfma_f32_32x32x16_bf16 v[32:47], v[76:79], v[88:91], v[32:47]
	s_waitcnt lgkmcnt(0)
	v_mfma_f32_32x32x16_bf16 v[16:31], v[92:95], v[80:83], v[16:31]
	ds_read_b128 v[68:71], v66 offset:18496
	ds_read_b128 v[72:75], v66 offset:23104
	ds_read_b128 v[76:79], v64 offset:55360
	ds_read_b128 v[80:83], v64 offset:59968
	v_mfma_f32_32x32x16_bf16 v[0:15], v[92:95], v[88:91], v[0:15]
	s_waitcnt lgkmcnt(1)
	v_mfma_f32_32x32x16_bf16 v[48:63], v[68:71], v[76:79], v[48:63]
	s_waitcnt lgkmcnt(0)
	v_mfma_f32_32x32x16_bf16 v[32:47], v[68:71], v[80:83], v[32:47]
	v_mfma_f32_32x32x16_bf16 v[16:31], v[72:75], v[76:79], v[16:31]
	ds_read_b128 v[68:71], v66 offset:18528
	ds_read_b128 v[76:79], v66 offset:23136
	ds_read_b128 v[84:87], v64 offset:55392
	ds_read_b128 v[88:91], v64 offset:60000
	v_mfma_f32_32x32x16_bf16 v[0:15], v[72:75], v[80:83], v[0:15]
	s_waitcnt lgkmcnt(1)
	v_mfma_f32_32x32x16_bf16 v[48:63], v[68:71], v[84:87], v[48:63]
	s_waitcnt lgkmcnt(0)
	v_mfma_f32_32x32x16_bf16 v[32:47], v[68:71], v[88:91], v[32:47]
	v_mfma_f32_32x32x16_bf16 v[16:31], v[76:79], v[84:87], v[16:31]
	v_mfma_f32_32x32x16_bf16 v[0:15], v[76:79], v[88:91], v[0:15]
	v_mov_b32_e32 v64, v202
	s_barrier
	s_ashr_i32 s21, s20, 31
	s_lshl_b64 s[2:3], s[20:21], 13
	v_ashrrev_i32_e32 v66, 1, v64
	v_lshrrev_b32_e32 v67, 3, v64
	v_lshlrev_b32_e32 v69, 4, v64
	v_lshlrev_b32_e32 v68, 1, v64
	v_ashrrev_i32_e32 v70, 4, v64
	v_add_u32_e32 v72, 0x100, v64
	v_add_u32_e32 v73, 0x200, v64
	v_add_u32_e32 v74, 0x300, v64
	v_add_u32_e32 v75, 0x400, v64
	v_add_u32_e32 v76, 0x500, v64
	v_add_u32_e32 v77, 0x600, v64
	v_add_u32_e32 v78, 0x700, v64
	v_and_b32_e32 v98, 0xffffffc0, v66
	v_and_b32_e32 v99, 4, v67
	v_and_b32_e32 v64, 0xf0, v69
	s_add_u32 s2, s22, s2
	v_or_b32_e32 v82, v99, v98
	v_mad_u64_u32 v[66:67], s[20:21], v70, s31, v[64:65]
	s_addc_u32 s35, s23, s3
	s_ashr_i32 s1, s0, 31
	v_subrev_u32_e32 v67, s34, v82
	s_lshl_b64 s[0:1], s[0:1], 1
	v_add_u32_e32 v162, s24, v67
	v_and_b32_e32 v114, 0xbe, v68
	v_ashrrev_i32_e32 v71, 31, v70
	v_ashrrev_i32_e32 v84, 4, v72
	v_ashrrev_i32_e32 v86, 4, v73
	v_ashrrev_i32_e32 v88, 4, v74
	v_ashrrev_i32_e32 v90, 4, v75
	v_ashrrev_i32_e32 v92, 4, v76
	v_ashrrev_i32_e32 v94, 4, v77
	v_ashrrev_i32_e32 v96, 4, v78
	v_or_b32_e32 v115, 27, v99
	s_add_u32 s0, s2, s0
	v_subrev_u32_e32 v166, 48, v162
	v_subrev_u32_e32 v168, 40, v162
	v_subrev_u32_e32 v170, 32, v162
	v_subrev_u32_e32 v172, 24, v162
	v_add_u32_e32 v174, -16, v162
	v_add_u32_e32 v176, -8, v162
	v_add_u32_e32 v178, 8, v162
	v_or_b32_e32 v100, 1, v99
	v_or_b32_e32 v101, 2, v99
	v_or_b32_e32 v102, 3, v99
	v_or_b32_e32 v103, 8, v99
	v_or_b32_e32 v104, 9, v99
	v_or_b32_e32 v105, 10, v99
	v_or_b32_e32 v106, 11, v99
	v_or_b32_e32 v107, 16, v99
	v_or_b32_e32 v108, 17, v99
	v_or_b32_e32 v109, 18, v99
	v_or_b32_e32 v110, 19, v99
	v_or_b32_e32 v111, 24, v99
	v_or_b32_e32 v112, 25, v99
	v_or_b32_e32 v113, 26, v99
	v_or_b32_e32 v118, 32, v98
	v_lshlrev_b64 v[116:117], 13, v[70:71]
	v_mad_u64_u32 v[68:69], s[20:21], v84, s31, v[64:65]
	v_ashrrev_i32_e32 v85, 31, v84
	v_mad_u64_u32 v[70:71], s[20:21], v86, s31, v[64:65]
	v_ashrrev_i32_e32 v87, 31, v86
	v_mad_u64_u32 v[72:73], s[20:21], v88, s31, v[64:65]
	v_ashrrev_i32_e32 v89, 31, v88
	v_mad_u64_u32 v[74:75], s[20:21], v90, s31, v[64:65]
	v_ashrrev_i32_e32 v91, 31, v90
	v_mad_u64_u32 v[76:77], s[20:21], v92, s31, v[64:65]
	v_ashrrev_i32_e32 v93, 31, v92
	v_mad_u64_u32 v[78:79], s[20:21], v94, s31, v[64:65]
	v_ashrrev_i32_e32 v95, 31, v94
	v_mad_u64_u32 v[80:81], s[20:21], v96, s31, v[64:65]
	v_ashrrev_i32_e32 v97, 31, v96
	v_mad_u64_u32 v[82:83], s[2:3], v82, s31, v[114:115]
	s_addc_u32 s1, s35, s1
	v_ashrrev_i32_e32 v163, 31, v162
	v_ashrrev_i32_e32 v167, 31, v166
	v_ashrrev_i32_e32 v169, 31, v168
	v_ashrrev_i32_e32 v171, 31, v170
	v_ashrrev_i32_e32 v173, 31, v172
	v_ashrrev_i32_e32 v175, 31, v174
	v_ashrrev_i32_e32 v177, 31, v176
	v_ashrrev_i32_e32 v179, 31, v178
	v_or_b32_e32 v69, v100, v98
	v_or_b32_e32 v71, v101, v98
	v_or_b32_e32 v73, v102, v98
	v_or_b32_e32 v75, v103, v98
	v_or_b32_e32 v77, v104, v98
	v_or_b32_e32 v79, v105, v98
	v_or_b32_e32 v81, v106, v98
	v_or_b32_e32 v83, v107, v98
	v_or_b32_e32 v148, v108, v98
	v_or_b32_e32 v150, v109, v98
	v_or_b32_e32 v152, v110, v98
	v_or_b32_e32 v154, v111, v98
	v_or_b32_e32 v156, v112, v98
	v_or_b32_e32 v158, v113, v98
	v_or_b32_e32 v98, v115, v98
	v_or_b32_e32 v99, v118, v99
	v_or_b32_e32 v100, v100, v118
	v_or_b32_e32 v101, v101, v118
	v_or_b32_e32 v102, v102, v118
	v_or_b32_e32 v103, v103, v118
	v_or_b32_e32 v104, v104, v118
	v_or_b32_e32 v105, v105, v118
	v_or_b32_e32 v106, v106, v118
	v_or_b32_e32 v107, v107, v118
	v_or_b32_e32 v108, v108, v118
	v_or_b32_e32 v109, v109, v118
	v_or_b32_e32 v110, v110, v118
	v_or_b32_e32 v111, v111, v118
	v_or_b32_e32 v112, v112, v118
	v_or_b32_e32 v113, v113, v118
	v_or_b32_e32 v115, v115, v118
	v_lshlrev_b64 v[118:119], 13, v[84:85]
	v_lshlrev_b64 v[120:121], 13, v[86:87]
; DI u16 f2bf(float x) { return (u16)(pack2(x, 0.f) & 0xffffu); }
; DI int opaque_tid() { int t = threadIdx.x; asm volatile("" : "+v"(t)); return t; }
; DI int crow(int i, int h) { return (i & 3) + 8 * (i >> 2) + 4 * h; }
; template <class F>
; DI void epi_bf16_tile(const f32x16 (&acc)[2][2], int m0, int n0, u16* dst0, long ld, char* smem, F f) {
;   const int tid = opaque_tid(), lane = tid & 63, w = tid >> 6, wm = w >> 1, wn = w & 1, h = lane >> 5;
;   u16* T = (u16*)smem;
; #pragma unroll
;   for (int mt = 0; mt < 2; mt++)
; #pragma unroll
;     for (int nt = 0; nt < 2; nt++)
; #pragma unroll
;       for (int i = 0; i < 16; i++) {
;         const int ml = wm * 64 + mt * 32 + crow(i, h), nl = wn * 64 + nt * 32 + (lane & 31);
;         T[ml * 136 + nl] = f2bf(f(m0 + ml, n0 + nl, acc[mt][nt][i]));
; DI void ffn_up_phase(const Params& p, const u16* xb, int ldx, const u16* wupT, u16* hid, char* smem) {
;     ...
;              [=](const f32x16 (&acc)[2][2], int m0, int n0) {
;                epi_bf16_tile(acc, m0, n0, hid + (long)m0 * 4096 + n0, 4096, smem, [=](int m, int n, float v) {
;                  const float a = fmaxf(v * rs[m], 0.f);
;                  return a * a;
	v_lshlrev_b64 v[122:123], 13, v[88:89]
	v_lshlrev_b64 v[124:125], 13, v[90:91]
	v_lshlrev_b64 v[126:127], 13, v[92:93]
	v_lshlrev_b64 v[128:129], 13, v[94:95]
	v_lshlrev_b64 v[130:131], 13, v[96:97]
	v_lshl_add_u64 v[164:165], s[0:1], 0, v[64:65]
	v_lshl_add_u64 v[162:163], v[162:163], 2, s[14:15]
	v_lshl_add_u64 v[166:167], v[166:167], 2, s[14:15]
	v_lshl_add_u64 v[180:181], v[168:169], 2, s[14:15]
	v_lshl_add_u64 v[182:183], v[170:171], 2, s[14:15]
	v_lshl_add_u64 v[184:185], v[172:173], 2, s[14:15]
	v_lshl_add_u64 v[186:187], v[174:175], 2, s[14:15]
	v_lshl_add_u64 v[188:189], v[176:177], 2, s[14:15]
	v_lshl_add_u64 v[190:191], v[178:179], 2, s[14:15]
	v_lshl_add_u64 v[116:117], v[164:165], 0, v[116:117]
	v_lshl_add_u64 v[118:119], v[164:165], 0, v[118:119]
	v_lshl_add_u64 v[120:121], v[164:165], 0, v[120:121]
	v_lshl_add_u64 v[122:123], v[164:165], 0, v[122:123]
	v_lshl_add_u64 v[124:125], v[164:165], 0, v[124:125]
	v_lshl_add_u64 v[126:127], v[164:165], 0, v[126:127]
	v_lshl_add_u64 v[128:129], v[164:165], 0, v[128:129]
	v_lshl_add_u64 v[130:131], v[164:165], 0, v[130:131]
	global_load_dwordx4 v[162:165], v[162:163], off
	s_nop 0
	global_load_dwordx4 v[166:169], v[166:167], off
	s_nop 0
	global_load_dwordx4 v[170:173], v[180:181], off
	global_load_dwordx4 v[174:177], v[182:183], off
	s_nop 0
	global_load_dwordx4 v[178:181], v[184:185], off
	s_nop 0
	global_load_dwordx4 v[182:185], v[186:187], off
	s_nop 0
	global_load_dwordx4 v[186:189], v[188:189], off
	s_nop 0
	global_load_dwordx4 v[190:193], v[190:191], off
	v_mad_u64_u32 v[132:133], s[2:3], v69, s31, v[114:115]
	v_mad_u64_u32 v[134:135], s[2:3], v71, s31, v[114:115]
	v_mad_u64_u32 v[136:137], s[2:3], v73, s31, v[114:115]
	v_mad_u64_u32 v[138:139], s[2:3], v75, s31, v[114:115]
	v_mad_u64_u32 v[140:141], s[2:3], v77, s31, v[114:115]
	v_mad_u64_u32 v[142:143], s[2:3], v79, s31, v[114:115]
	v_mad_u64_u32 v[144:145], s[2:3], v81, s31, v[114:115]
	v_mad_u64_u32 v[146:147], s[2:3], v83, s31, v[114:115]
	v_mad_u64_u32 v[148:149], s[2:3], v148, s31, v[114:115]
	v_mad_u64_u32 v[150:151], s[2:3], v150, s31, v[114:115]
	v_mad_u64_u32 v[152:153], s[2:3], v152, s31, v[114:115]
	v_mad_u64_u32 v[154:155], s[2:3], v154, s31, v[114:115]
	v_mad_u64_u32 v[156:157], s[2:3], v156, s31, v[114:115]
	v_mad_u64_u32 v[158:159], s[2:3], v158, s31, v[114:115]
	v_mad_u64_u32 v[160:161], s[2:3], v98, s31, v[114:115]
	v_mad_u64_u32 v[84:85], s[2:3], v99, s31, v[114:115]
	v_mad_u64_u32 v[86:87], s[2:3], v100, s31, v[114:115]
	v_mad_u64_u32 v[88:89], s[2:3], v101, s31, v[114:115]
	v_mad_u64_u32 v[90:91], s[2:3], v102, s31, v[114:115]
	v_mad_u64_u32 v[92:93], s[2:3], v103, s31, v[114:115]
	v_mad_u64_u32 v[94:95], s[2:3], v104, s31, v[114:115]
	v_mad_u64_u32 v[96:97], s[2:3], v105, s31, v[114:115]
	v_mad_u64_u32 v[98:99], s[2:3], v106, s31, v[114:115]
	v_mad_u64_u32 v[100:101], s[2:3], v107, s31, v[114:115]
	v_mad_u64_u32 v[102:103], s[2:3], v108, s31, v[114:115]
	v_mad_u64_u32 v[104:105], s[2:3], v109, s31, v[114:115]
	v_mad_u64_u32 v[106:107], s[2:3], v110, s31, v[114:115]
	v_mad_u64_u32 v[108:109], s[2:3], v111, s31, v[114:115]
	v_mad_u64_u32 v[110:111], s[2:3], v112, s31, v[114:115]
	v_mad_u64_u32 v[112:113], s[2:3], v113, s31, v[114:115]
	v_mad_u64_u32 v[114:115], s[2:3], v115, s31, v[114:115]
	s_add_i32 s33, s33, s50
	s_add_i32 s24, s24, s25
	s_cmpk_lt_i32 s33, 0x1200
	s_waitcnt vmcnt(6)
	v_mul_f32_e32 v48, v48, v166
	v_mul_f32_e32 v49, v49, v167
	v_mul_f32_e32 v50, v50, v168
	v_mul_f32_e32 v51, v51, v169
	s_waitcnt vmcnt(2)
	v_mul_f32_e32 v16, v16, v182
	v_mul_f32_e32 v24, v24, v162
	v_mul_f32_e32 v25, v25, v163
	v_mul_f32_e32 v26, v26, v164
	v_mul_f32_e32 v27, v27, v165
	v_mul_f32_e32 v8, v8, v162
	v_mul_f32_e32 v9, v9, v163
	v_mul_f32_e32 v10, v10, v164
	v_mul_f32_e32 v11, v11, v165
	v_mul_f32_e32 v17, v17, v183
	v_mul_f32_e32 v18, v18, v184
	v_mul_f32_e32 v19, v19, v185
	s_waitcnt vmcnt(1)
	v_mul_f32_e32 v20, v20, v186
	v_mul_f32_e32 v21, v21, v187
	v_mul_f32_e32 v22, v22, v188
	v_mul_f32_e32 v23, v23, v189
	s_waitcnt vmcnt(0)
	v_mul_f32_e32 v28, v28, v190
	v_mul_f32_e32 v29, v29, v191
	v_mul_f32_e32 v30, v30, v192
	v_mul_f32_e32 v31, v31, v193
	v_mul_f32_e32 v0, v0, v182
	v_mul_f32_e32 v1, v1, v183
	v_mul_f32_e32 v2, v2, v184
	v_mul_f32_e32 v3, v3, v185
	v_mul_f32_e32 v4, v4, v186
	v_mul_f32_e32 v5, v5, v187
	v_mul_f32_e32 v6, v6, v188
	v_mul_f32_e32 v7, v7, v189
	v_mul_f32_e32 v12, v12, v190
	v_mul_f32_e32 v13, v13, v191
	v_mul_f32_e32 v14, v14, v192
	v_mul_f32_e32 v15, v15, v193
	v_mul_f32_e32 v52, v52, v170
	v_mul_f32_e32 v53, v53, v171
	v_mul_f32_e32 v54, v54, v172
	v_mul_f32_e32 v55, v55, v173
	v_mul_f32_e32 v56, v56, v174
	v_mul_f32_e32 v57, v57, v175
	v_mul_f32_e32 v58, v58, v176
	v_mul_f32_e32 v59, v59, v177
	v_mul_f32_e32 v60, v60, v178
	v_mul_f32_e32 v61, v61, v179
	v_mul_f32_e32 v62, v62, v180
	v_mul_f32_e32 v63, v63, v181
	v_mul_f32_e32 v32, v32, v166
	v_mul_f32_e32 v33, v33, v167
	v_mul_f32_e32 v34, v34, v168
	v_mul_f32_e32 v35, v35, v169
	v_mul_f32_e32 v36, v36, v170
	v_mul_f32_e32 v37, v37, v171
	v_mul_f32_e32 v38, v38, v172
	v_mul_f32_e32 v39, v39, v173
	v_mul_f32_e32 v40, v40, v174
	v_mul_f32_e32 v41, v41, v175
	v_mul_f32_e32 v42, v42, v176
	v_mul_f32_e32 v43, v43, v177
	v_mul_f32_e32 v44, v44, v178
	v_mul_f32_e32 v45, v45, v179
	v_mul_f32_e32 v46, v46, v180
	v_mul_f32_e32 v47, v47, v181
	v_max_f32_e32 v24, 0, v24
	v_max_f32_e32 v25, 0, v25
	v_max_f32_e32 v26, 0, v26
	v_max_f32_e32 v27, 0, v27
	v_max_f32_e32 v8, 0, v8
	v_max_f32_e32 v9, 0, v9
	v_max_f32_e32 v10, 0, v10
	v_max_f32_e32 v11, 0, v11
	v_max_f32_e32 v48, 0, v48
	v_max_f32_e32 v16, 0, v16
	v_max_f32_e32 v17, 0, v17
; DI void ffn_up_phase(const Params& p, const u16* xb, int ldx, const u16* wupT, u16* hid, char* smem) {
;     ...
;                epi_bf16_tile(acc, m0, n0, hid + (long)m0 * 4096 + n0, 4096, smem, [=](int m, int n, float v) {
;                  const float a = fmaxf(v * rs[m], 0.f);
;                  return a * a;
	v_max_f32_e32 v18, 0, v18
	v_max_f32_e32 v19, 0, v19
	v_max_f32_e32 v20, 0, v20
	v_max_f32_e32 v21, 0, v21
	v_max_f32_e32 v22, 0, v22
	v_max_f32_e32 v23, 0, v23
	v_max_f32_e32 v28, 0, v28
	v_max_f32_e32 v29, 0, v29
	v_max_f32_e32 v30, 0, v30
	v_max_f32_e32 v31, 0, v31
	v_max_f32_e32 v0, 0, v0
	v_max_f32_e32 v1, 0, v1
	v_max_f32_e32 v2, 0, v2
	v_max_f32_e32 v3, 0, v3
	v_max_f32_e32 v4, 0, v4
	v_max_f32_e32 v5, 0, v5
	v_max_f32_e32 v6, 0, v6
	v_max_f32_e32 v7, 0, v7
	v_max_f32_e32 v12, 0, v12
	v_max_f32_e32 v13, 0, v13
	v_max_f32_e32 v14, 0, v14
	v_max_f32_e32 v15, 0, v15
	v_max_f32_e32 v49, 0, v49
	v_max_f32_e32 v50, 0, v50
	v_max_f32_e32 v51, 0, v51
	v_max_f32_e32 v52, 0, v52
	v_max_f32_e32 v53, 0, v53
	v_max_f32_e32 v54, 0, v54
	v_max_f32_e32 v55, 0, v55
	v_max_f32_e32 v56, 0, v56
	v_max_f32_e32 v57, 0, v57
	v_max_f32_e32 v58, 0, v58
	v_max_f32_e32 v59, 0, v59
	v_max_f32_e32 v60, 0, v60
	v_max_f32_e32 v61, 0, v61
	v_max_f32_e32 v62, 0, v62
	v_max_f32_e32 v63, 0, v63
	v_max_f32_e32 v32, 0, v32
	v_max_f32_e32 v33, 0, v33
	v_max_f32_e32 v34, 0, v34
	v_max_f32_e32 v35, 0, v35
	v_max_f32_e32 v36, 0, v36
	v_max_f32_e32 v37, 0, v37
	v_max_f32_e32 v38, 0, v38
	v_max_f32_e32 v39, 0, v39
	v_max_f32_e32 v40, 0, v40
	v_max_f32_e32 v41, 0, v41
	v_max_f32_e32 v42, 0, v42
	v_max_f32_e32 v43, 0, v43
	v_max_f32_e32 v44, 0, v44
	v_max_f32_e32 v45, 0, v45
	v_max_f32_e32 v46, 0, v46
	v_max_f32_e32 v47, 0, v47
	v_mul_f32_e32 v24, v24, v24
	v_mul_f32_e32 v25, v25, v25
	v_mul_f32_e32 v26, v26, v26
	v_mul_f32_e32 v27, v27, v27
	v_mul_f32_e32 v8, v8, v8
	v_mul_f32_e32 v9, v9, v9
	v_mul_f32_e32 v10, v10, v10
	v_mul_f32_e32 v11, v11, v11
	v_mul_f32_e32 v48, v48, v48
	v_mul_f32_e32 v16, v16, v16
	v_mul_f32_e32 v17, v17, v17
	v_mul_f32_e32 v18, v18, v18
	v_mul_f32_e32 v19, v19, v19
	v_mul_f32_e32 v20, v20, v20
	v_mul_f32_e32 v21, v21, v21
	v_mul_f32_e32 v22, v22, v22
	v_mul_f32_e32 v23, v23, v23
	v_mul_f32_e32 v28, v28, v28
	v_mul_f32_e32 v29, v29, v29
	v_mul_f32_e32 v30, v30, v30
	v_mul_f32_e32 v31, v31, v31
	v_mul_f32_e32 v0, v0, v0
	v_mul_f32_e32 v1, v1, v1
	v_mul_f32_e32 v2, v2, v2
	v_mul_f32_e32 v3, v3, v3
	v_mul_f32_e32 v4, v4, v4
	v_mul_f32_e32 v5, v5, v5
	v_mul_f32_e32 v6, v6, v6
	v_mul_f32_e32 v7, v7, v7
	v_mul_f32_e32 v12, v12, v12
	v_mul_f32_e32 v13, v13, v13
	v_mul_f32_e32 v14, v14, v14
	v_mul_f32_e32 v15, v15, v15
	v_mul_f32_e32 v49, v49, v49
	v_mul_f32_e32 v50, v50, v50
	v_mul_f32_e32 v51, v51, v51
	v_mul_f32_e32 v52, v52, v52
	v_mul_f32_e32 v53, v53, v53
	v_mul_f32_e32 v54, v54, v54
	v_mul_f32_e32 v55, v55, v55
	v_mul_f32_e32 v56, v56, v56
	v_mul_f32_e32 v57, v57, v57
	v_mul_f32_e32 v58, v58, v58
	v_mul_f32_e32 v59, v59, v59
	v_mul_f32_e32 v60, v60, v60
	v_mul_f32_e32 v61, v61, v61
	v_mul_f32_e32 v62, v62, v62
	v_mul_f32_e32 v63, v63, v63
	v_mul_f32_e32 v32, v32, v32
	v_mul_f32_e32 v33, v33, v33
	v_mul_f32_e32 v34, v34, v34
	v_mul_f32_e32 v35, v35, v35
	v_mul_f32_e32 v36, v36, v36
	v_mul_f32_e32 v37, v37, v37
	v_mul_f32_e32 v38, v38, v38
	v_mul_f32_e32 v39, v39, v39
	v_mul_f32_e32 v40, v40, v40
	v_mul_f32_e32 v41, v41, v41
	v_mul_f32_e32 v42, v42, v42
	v_mul_f32_e32 v43, v43, v43
	v_mul_f32_e32 v44, v44, v44
	v_mul_f32_e32 v45, v45, v45
	v_mul_f32_e32 v46, v46, v46
	v_mul_f32_e32 v47, v47, v47
	v_cvt_pk_bf16_f32 v24, v24, s0
	v_cvt_pk_bf16_f32 v25, v25, s0
	v_cvt_pk_bf16_f32 v26, v26, s0
	v_cvt_pk_bf16_f32 v27, v27, s0
	v_cvt_pk_bf16_f32 v8, v8, s0
	v_cvt_pk_bf16_f32 v9, v9, s0
	v_cvt_pk_bf16_f32 v10, v10, s0
	v_cvt_pk_bf16_f32 v11, v11, s0
	v_cvt_pk_bf16_f32 v48, v48, s0
	v_cvt_pk_bf16_f32 v16, v16, s0
	v_cvt_pk_bf16_f32 v17, v17, s0
	v_cvt_pk_bf16_f32 v18, v18, s0
	v_cvt_pk_bf16_f32 v19, v19, s0
	v_cvt_pk_bf16_f32 v20, v20, s0
	v_cvt_pk_bf16_f32 v21, v21, s0
	v_cvt_pk_bf16_f32 v22, v22, s0
	v_cvt_pk_bf16_f32 v23, v23, s0
	v_cvt_pk_bf16_f32 v28, v28, s0
	v_cvt_pk_bf16_f32 v29, v29, s0
	v_cvt_pk_bf16_f32 v30, v30, s0
	v_cvt_pk_bf16_f32 v31, v31, s0
	v_cvt_pk_bf16_f32 v0, v0, s0
	v_cvt_pk_bf16_f32 v1, v1, s0
	v_cvt_pk_bf16_f32 v2, v2, s0
	v_cvt_pk_bf16_f32 v3, v3, s0
	v_cvt_pk_bf16_f32 v4, v4, s0
	v_cvt_pk_bf16_f32 v5, v5, s0
	v_cvt_pk_bf16_f32 v6, v6, s0
	v_cvt_pk_bf16_f32 v7, v7, s0
	v_cvt_pk_bf16_f32 v12, v12, s0
	v_cvt_pk_bf16_f32 v13, v13, s0
	v_cvt_pk_bf16_f32 v14, v14, s0
	v_cvt_pk_bf16_f32 v15, v15, s0
	v_cvt_pk_bf16_f32 v49, v49, s0
	v_cvt_pk_bf16_f32 v50, v50, s0
	v_cvt_pk_bf16_f32 v51, v51, s0
	v_cvt_pk_bf16_f32 v52, v52, s0
; DI u16 f2bf(float x) { return (u16)(pack2(x, 0.f) & 0xffffu); }
; DI int opaque_tid() { int t = threadIdx.x; asm volatile("" : "+v"(t)); return t; }
; DI int crow(int i, int h) { return (i & 3) + 8 * (i >> 2) + 4 * h; }
; template <class F>
; DI void epi_bf16_tile(const f32x16 (&acc)[2][2], int m0, int n0, u16* dst0, long ld, char* smem, F f) {
;   const int tid = opaque_tid(), lane = tid & 63, w = tid >> 6, wm = w >> 1, wn = w & 1, h = lane >> 5;
;   u16* T = (u16*)smem;
; #pragma unroll
;   for (int mt = 0; mt < 2; mt++)
; #pragma unroll
;     for (int nt = 0; nt < 2; nt++)
; #pragma unroll
;       for (int i = 0; i < 16; i++) {
;         const int ml = wm * 64 + mt * 32 + crow(i, h), nl = wn * 64 + nt * 32 + (lane & 31);
;         T[ml * 136 + nl] = f2bf(f(m0 + ml, n0 + nl, acc[mt][nt][i]));
;       }
;   __syncthreads();
; #pragma unroll
;   for (int j = 0; j < 8; j++) {
;     const int idx = tid + 256 * j, row = idx >> 4, ch = idx & 15;
;     *(uint4*)(dst0 + (long)row * ld + ch * 8) = *(const uint4*)(T + row * 136 + ch * 8);
;   }
;   __syncthreads();
; }
; template <class AL, class BL, class EP>
; DI void gemm_phase(int MT, int NTL, int K, AL al, BL bl, EP ep, char* smem) {
;   for (int t = blockIdx.x; t < MT * NTL; t += gridDim.x) {
;     const int tm = t % MT, tn = t / MT;
;     f32x16 acc[2][2];
;     gemm_core(al, bl, tm * 128, tn * 128, K, smem, acc);
;     ep(acc, tm * 128, tn * 128);
;   }
	v_cvt_pk_bf16_f32 v53, v53, s0
	v_cvt_pk_bf16_f32 v54, v54, s0
	v_cvt_pk_bf16_f32 v55, v55, s0
	v_cvt_pk_bf16_f32 v56, v56, s0
	v_cvt_pk_bf16_f32 v57, v57, s0
	v_cvt_pk_bf16_f32 v58, v58, s0
	v_cvt_pk_bf16_f32 v59, v59, s0
	v_cvt_pk_bf16_f32 v60, v60, s0
	v_cvt_pk_bf16_f32 v61, v61, s0
	v_cvt_pk_bf16_f32 v62, v62, s0
	v_cvt_pk_bf16_f32 v63, v63, s0
	v_cvt_pk_bf16_f32 v32, v32, s0
	v_cvt_pk_bf16_f32 v33, v33, s0
	v_cvt_pk_bf16_f32 v34, v34, s0
	v_cvt_pk_bf16_f32 v35, v35, s0
	v_cvt_pk_bf16_f32 v36, v36, s0
	v_cvt_pk_bf16_f32 v37, v37, s0
	v_cvt_pk_bf16_f32 v38, v38, s0
	v_cvt_pk_bf16_f32 v39, v39, s0
	v_cvt_pk_bf16_f32 v40, v40, s0
	v_cvt_pk_bf16_f32 v41, v41, s0
	v_cvt_pk_bf16_f32 v42, v42, s0
	v_cvt_pk_bf16_f32 v43, v43, s0
	v_cvt_pk_bf16_f32 v44, v44, s0
	v_cvt_pk_bf16_f32 v45, v45, s0
	v_cvt_pk_bf16_f32 v46, v46, s0
	v_cvt_pk_bf16_f32 v47, v47, s0
	ds_write_b16 v82, v48
	ds_write_b16 v132, v49
	ds_write_b16 v134, v50
	ds_write_b16 v136, v51
	ds_write_b16 v138, v52
	ds_write_b16 v140, v53
	ds_write_b16 v142, v54
	ds_write_b16 v144, v55
	ds_write_b16 v146, v56
	ds_write_b16 v148, v57
	ds_write_b16 v150, v58
	ds_write_b16 v152, v59
	ds_write_b16 v154, v60
	ds_write_b16 v156, v61
	ds_write_b16 v158, v62
	ds_write_b16 v160, v63
	ds_write_b16 v82, v32 offset:64
	ds_write_b16 v132, v33 offset:64
	ds_write_b16 v134, v34 offset:64
	ds_write_b16 v136, v35 offset:64
	ds_write_b16 v138, v36 offset:64
	ds_write_b16 v140, v37 offset:64
	ds_write_b16 v142, v38 offset:64
	ds_write_b16 v144, v39 offset:64
	ds_write_b16 v146, v40 offset:64
	ds_write_b16 v148, v41 offset:64
	ds_write_b16 v150, v42 offset:64
	ds_write_b16 v152, v43 offset:64
	ds_write_b16 v154, v44 offset:64
	ds_write_b16 v156, v45 offset:64
	ds_write_b16 v158, v46 offset:64
	ds_write_b16 v160, v47 offset:64
	ds_write_b16 v84, v16
	ds_write_b16 v86, v17
	ds_write_b16 v88, v18
	ds_write_b16 v90, v19
	ds_write_b16 v92, v20
	ds_write_b16 v94, v21
	ds_write_b16 v96, v22
	ds_write_b16 v98, v23
	ds_write_b16 v100, v24
	ds_write_b16 v102, v25
	ds_write_b16 v104, v26
	ds_write_b16 v106, v27
	ds_write_b16 v108, v28
	ds_write_b16 v110, v29
	ds_write_b16 v112, v30
	ds_write_b16 v114, v31
	ds_write_b16 v84, v0 offset:64
	ds_write_b16 v86, v1 offset:64
	ds_write_b16 v88, v2 offset:64
	ds_write_b16 v90, v3 offset:64
	ds_write_b16 v92, v4 offset:64
	ds_write_b16 v94, v5 offset:64
	ds_write_b16 v96, v6 offset:64
	ds_write_b16 v98, v7 offset:64
	ds_write_b16 v100, v8 offset:64
	ds_write_b16 v102, v9 offset:64
	ds_write_b16 v104, v10 offset:64
	ds_write_b16 v106, v11 offset:64
	ds_write_b16 v108, v12 offset:64
	ds_write_b16 v110, v13 offset:64
	ds_write_b16 v112, v14 offset:64
	ds_write_b16 v114, v15 offset:64
	s_waitcnt lgkmcnt(0)
	s_barrier
	ds_read_b128 v[0:3], v66
	ds_read_b128 v[4:7], v68
	ds_read_b128 v[8:11], v70
	ds_read_b128 v[12:15], v72
	ds_read_b128 v[16:19], v74
	ds_read_b128 v[20:23], v76
	ds_read_b128 v[24:27], v78
	ds_read_b128 v[28:31], v80
	s_waitcnt lgkmcnt(7)
	global_store_dwordx4 v[116:117], v[0:3], off
	s_waitcnt lgkmcnt(6)
	global_store_dwordx4 v[118:119], v[4:7], off
	s_waitcnt lgkmcnt(5)
	global_store_dwordx4 v[120:121], v[8:11], off
	s_waitcnt lgkmcnt(4)
	global_store_dwordx4 v[122:123], v[12:15], off
	s_waitcnt lgkmcnt(3)
	global_store_dwordx4 v[124:125], v[16:19], off
	s_waitcnt lgkmcnt(2)
	global_store_dwordx4 v[126:127], v[20:23], off
	s_waitcnt lgkmcnt(1)
	global_store_dwordx4 v[128:129], v[24:27], off
	s_waitcnt lgkmcnt(0)
	global_store_dwordx4 v[130:131], v[28:31], off
	s_barrier
	s_cbranch_scc0 .Lfu0_exit
	s_cmp_lg_u32 s99, 0
	s_cbranch_scc0 .LBB0_978
.Lfu0_exit:
	s_mov_b64 s[2:3], s[48:49]
.LBB0_980:
	s_getreg_b32 s8, hwreg(HW_REG_XCC_ID, 0, 4)
	s_waitcnt vmcnt(0)
	s_barrier
	s_and_saveexec_b64 s[0:1], s[4:5]
	s_cbranch_execz .LBB0_1032
	v_mov_b32_e32 v0, 0x12000
	s_waitcnt vmcnt(0) expcnt(0) lgkmcnt(0)
	ds_read_b32 v2, v0
	v_mov_b32_e32 v0, 0x12004
	ds_read_b32 v0, v0
	s_and_b32 s24, s8, 15
	s_waitcnt lgkmcnt(1)
	v_cmp_ne_u32_e32 vcc, 0, v2
	s_cbranch_vccnz .LBB0_996
	v_readlane_b32 s8, v226, 0
	v_readlane_b32 s9, v226, 1
	s_load_dwordx2 s[14:15], s[8:9], 0x4
	s_add_u32 s8, s2, 0x1000
	s_addc_u32 s9, s3, 0
	s_add_u32 s12, s2, 0x1100
	s_addc_u32 s13, s3, 0
	s_waitcnt lgkmcnt(0)
	s_mul_i32 s25, s14, s50
	s_add_u32 s14, s2, 0x1200
	s_mul_i32 s25, s25, s15
	s_addc_u32 s15, s3, 0
	s_add_u32 s16, s2, 0x1300
	s_addc_u32 s17, s3, 0
	s_mov_b32 s26, 1
	v_mov_b32_e32 v16, 0
	s_branch .LBB0_984

; template <class AL, class BL, class EP>
; DI void gemm_phase(int MT, int NTL, int K, AL al, BL bl, EP ep, char* smem) {
;   for (int t = blockIdx.x; t < MT * NTL; t += gridDim.x) {
;     const int tm = t % MT, tn = t / MT;
;     f32x16 acc[2][2];
;     gemm_core(al, bl, tm * 128, tn * 128, K, smem, acc);
;     ep(acc, tm * 128, tn * 128);
;   }
; DI void ffn_up_phase(const Params& p, const u16* xb, int ldx, const u16* wupT, u16* hid, char* smem) {
;   const float* rs = (const float*)(p.ws + W_RS);
;   gemm_phase(NT / 128, 32, 1024,
;              [=](int m, int k) { return xb + (long)m * ldx + k; },
;              [=](int n, int k) { return wupT + (long)n * 1024 + k; },
;              [=](const f32x16 (&acc)[2][2], int m0, int n0) {
;                epi_bf16_tile(acc, m0, n0, hid + (long)m0 * 4096 + n0, 4096, smem, [=](int m, int n, float v) {
;                  const float a = fmaxf(v * rs[m], 0.f);
;                  return a * a;
;                });
;              }, smem);
.LBB0_1672:
	s_or_b64 exec, exec, s[0:1]
	s_andn2_b64 vcc, exec, s[58:59]
	s_waitcnt lgkmcnt(0)
	s_barrier
	s_cbranch_vccnz .LBB0_1676
	s_add_u32 s6, s70, 0x7000000
	s_addc_u32 s7, s71, 0
	s_add_u32 s20, s70, 0x8000000
	s_addc_u32 s21, s71, 0
	s_add_u32 s12, s70, 0x10000
	s_mov_b64 s[10:11], 0x10000
	s_addc_u32 s13, s71, 0
	s_add_i32 s22, s67, 48
	s_lshl_b32 s23, s50, 7
	v_mov_b32_e32 v65, 0
	s_mov_b32 s24, 0x10000
	s_mov_b64 s[14:15], 0x20000
	s_mov_b32 s25, 0x20000
	s_mov_b64 s[16:17], 0x30000
	s_mov_b32 s26, 0x30000
	s_movk_i32 s27, 0x90
	s_mov_b32 s28, 0xfffffc0
	s_movk_i32 s29, 0x110
	s_mov_b32 s30, s78
	s_mov_b32 s99, 0
	s_cmpk_eq_u32 s50, 0x200
	s_cbranch_scc0 .Lfu1_fallback
	s_mov_b32 s99, 1
	v_bfe_u32 v62, v202, 5, 1
	v_and_b32_e32 v63, 31, v202
	v_lshrrev_b32_e32 v64, 7, v202
	v_bfe_u32 v254, v202, 6, 1
	v_lshlrev_b32_e32 v253, 2, v62
	v_lshl_add_u32 v253, v64, 6, v253
	v_mul_u32_u24_e32 v59, 528, v253
	v_lshlrev_b32_e32 v252, 2, v253
	v_lshl_add_u32 v253, v254, 7, v63
	v_lshl_add_u32 v59, v253, 1, v59
	v_mul_u32_u24_e32 v57, 80, v253
	v_lshl_add_u32 v57, v62, 4, v57
	v_add_u32_e32 v57, 10240, v57
	v_lshl_add_u32 v253, v64, 6, v63
	v_mul_u32_u24_e32 v56, 80, v253
	v_lshl_add_u32 v56, v62, 4, v56
	v_lshrrev_b32_e32 v253, 5, v202
	v_mul_u32_u24_e32 v60, 528, v253
	v_lshl_add_u32 v60, v63, 4, v60
	v_mul_u32_u24_e32 v227, 8192, v253
	v_lshl_add_u32 v227, v63, 4, v227
	v_lshrrev_b32_e32 v253, 2, v202
	v_and_b32_e32 v254, 3, v202
	v_lshlrev_b32_e32 v254, 4, v254
	v_mov_b32_e32 v255, 0
	v_mul_u32_u24_e32 v58, 80, v253
	v_add_u32_e32 v58, v58, v254
	s_mov_b32 s98, s78
	s_cmpk_lt_u32 s98, 2016
	s_cbranch_scc1 .Lfu1_m0
	s_sub_u32 s31, s98, 2016
	s_mov_b32 s33, 14
	s_branch .Lfu1_g0

; DI int opaque_tid() { int t = threadIdx.x; asm volatile("" : "+v"(t)); return t; }
; #define G_LOAD(S, kt_) do { G_LD1(S##a0, S##b0, 0, kt_); G_LD1(S##a1, S##b1, 1, kt_); G_LD1(S##a2, S##b2, 2, kt_); G_LD1(S##a3, S##b3, 3, kt_); } while (0)
; #define G_STORE(S, buf_) do { G_ST1(S##a0, S##b0, 0, buf_); G_ST1(S##a1, S##b1, 1, buf_); G_ST1(S##a2, S##b2, 2, buf_); G_ST1(S##a3, S##b3, 3, buf_); } while (0)
; template <class AL, class BL>
; DI void gemm_core(AL al, BL bl, int m0, int n0, int K, char* smem, f32x16 (&acc)[2][2]) {
;   const int tid = opaque_tid(), lane = tid & 63, w = tid >> 6, wm = w >> 1, wn = w & 1;
;   u16* As = (u16*)smem;
;   u16* Bs = As + 2 * 128 * 72;
;   uint4 xa0, xa1, xa2, xa3, xb0, xb1, xb2, xb3, ya0, ya1, ya2, ya3, yb0, yb1, yb2, yb3;
;   const int nk = K / 64;
; #pragma unroll
;   for (int mt = 0; mt < 2; mt++)
; #pragma unroll
;     for (int nt = 0; nt < 2; nt++)
; #pragma unroll
;       for (int i = 0; i < 16; i++) acc[mt][nt][i] = 0.f;
;   const int srow = tid >> 3, sch = tid & 7;
;     ...
;   G_LOAD(x, 0);
;   G_STORE(x, 0);
;   G_LOAD(x, 1);
;   G_LOAD(y, (nk > 2) ? 2 : 1);
;   __syncthreads();
;   for (int kt = 0; kt < nk; kt += 2) {
;     G_TILE(0, x, true, (kt + 3 < nk), kt + 3);
;     __syncthreads();
;     G_TILE(1, y, (kt + 2 < nk), (kt + 4 < nk), kt + 4);
;     __syncthreads();
;   }
.Lfu1_fallback:
.LBB0_1674:
	s_mul_hi_i32 s0, s30, 0x38e38e39
	s_lshr_b32 s1, s0, 31
	s_ashr_i32 s0, s0, 5
	s_add_i32 s1, s0, s1
	v_mov_b32_e32 v32, v202
	s_lshl_b32 s0, s1, 7
	s_mul_i32 s31, s1, 0x4800
	v_ashrrev_i32_e32 v33, 3, v32
	v_add_u32_e32 v4, s0, v33
	v_ashrrev_i32_e32 v5, 31, v4
	v_lshlrev_b32_e32 v2, 4, v32
	v_lshlrev_b64 v[4:5], 11, v[4:5]
	v_and_b32_e32 v64, 0x70, v2
	v_lshl_add_u64 v[4:5], s[6:7], 0, v[4:5]
	v_lshl_add_u64 v[78:79], v[4:5], 0, v[64:65]
	v_subrev_u32_e32 v0, s31, v33
	v_add_co_u32_e32 v12, vcc, s24, v78
	v_add_u32_e32 v24, s22, v0
	s_nop 0
	v_addc_co_u32_e32 v13, vcc, 0, v79, vcc
	v_subrev_u32_e32 v0, 48, v24
	v_add_co_u32_e32 v20, vcc, s25, v78
	v_ashrrev_i32_e32 v1, 31, v0
	global_load_dwordx4 v[4:7], v[78:79], off
	v_add_u32_e32 v8, -16, v24
	v_addc_co_u32_e32 v21, vcc, 0, v79, vcc
	v_lshlrev_b64 v[0:1], 12, v[0:1]
	v_ashrrev_i32_e32 v9, 31, v8
	global_load_dwordx4 v[12:15], v[12:13], off
	v_add_u32_e32 v16, 16, v24
	v_add_u32_e32 v28, 48, v24
	v_add_co_u32_e32 v24, vcc, s26, v78
	v_lshl_add_u64 v[0:1], s[68:69], 0, v[0:1]
	v_lshlrev_b64 v[8:9], 12, v[8:9]
	v_ashrrev_i32_e32 v17, 31, v16
	global_load_dwordx4 v[20:23], v[20:21], off
	v_addc_co_u32_e32 v25, vcc, 0, v79, vcc
	v_lshl_add_u64 v[76:77], v[0:1], 0, v[64:65]
	v_lshl_add_u64 v[8:9], s[68:69], 0, v[8:9]
	v_lshlrev_b64 v[16:17], 12, v[16:17]
	v_ashrrev_i32_e32 v29, 31, v28
	global_load_dwordx4 v[24:27], v[24:25], off
	v_lshl_add_u64 v[74:75], v[8:9], 0, v[64:65]
	global_load_dwordx4 v[0:3], v[76:77], off offset:2048
	global_load_dwordx4 v[8:11], v[74:75], off offset:2048
	v_lshl_add_u64 v[16:17], s[68:69], 0, v[16:17]
	v_lshlrev_b64 v[28:29], 12, v[28:29]
	v_lshl_add_u64 v[70:71], v[16:17], 0, v[64:65]
	v_lshl_add_u64 v[28:29], s[68:69], 0, v[28:29]
	global_load_dwordx4 v[16:19], v[70:71], off offset:2048
	v_lshl_add_u64 v[72:73], v[28:29], 0, v[64:65]
	global_load_dwordx4 v[28:31], v[72:73], off offset:2048
	v_lshrrev_b32_e32 v34, 1, v32
	v_and_b32_e32 v35, 31, v32
	v_mad_u64_u32 v[68:69], s[2:3], v33, s27, v[64:65]
	v_lshl_add_u64 v[84:85], v[78:79], 0, s[10:11]
	v_lshl_add_u64 v[82:83], v[78:79], 0, s[14:15]
	v_lshl_add_u64 v[80:81], v[78:79], 0, s[16:17]
	global_load_dwordx4 v[86:89], v[78:79], off offset:128
	global_load_dwordx4 v[90:93], v[78:79], off offset:256
	global_load_dwordx4 v[94:97], v[84:85], off offset:128
	global_load_dwordx4 v[98:101], v[84:85], off offset:256
	global_load_dwordx4 v[102:105], v[82:83], off offset:128
	global_load_dwordx4 v[106:109], v[82:83], off offset:256
	global_load_dwordx4 v[110:113], v[80:81], off offset:128
	global_load_dwordx4 v[114:117], v[80:81], off offset:256
	global_load_dwordx4 v[118:121], v[76:77], off offset:2176
	global_load_dwordx4 v[122:125], v[74:75], off offset:2176
	global_load_dwordx4 v[126:129], v[70:71], off offset:2176
	global_load_dwordx4 v[130:133], v[72:73], off offset:2176
	global_load_dwordx4 v[134:137], v[76:77], off offset:2304
	global_load_dwordx4 v[138:141], v[74:75], off offset:2304
	global_load_dwordx4 v[142:145], v[70:71], off offset:2304
	global_load_dwordx4 v[146:149], v[72:73], off offset:2304
	s_mulk_i32 s1, 0xb800
	s_add_i32 s1, s22, s1
	s_sub_i32 s18, s1, 48
	s_waitcnt vmcnt(23)
	ds_write_b128 v68, v[4:7] offset:36864
	s_waitcnt vmcnt(22)
	ds_write_b128 v68, v[12:15] offset:41472
	s_waitcnt vmcnt(21)
	ds_write_b128 v68, v[20:23] offset:46080
	s_waitcnt vmcnt(20)
	ds_write_b128 v68, v[24:27] offset:50688
	s_waitcnt vmcnt(19)
	ds_write_b128 v68, v[0:3]
	s_waitcnt vmcnt(18)
	ds_write_b128 v68, v[8:11] offset:4608
	s_waitcnt vmcnt(17)
	ds_write_b128 v68, v[16:19] offset:9216
	s_waitcnt vmcnt(16)
	ds_write_b128 v68, v[28:31] offset:13824
	v_and_or_b32 v0, v34, s28, v35
	v_and_b32_e32 v4, 16, v34
	v_mad_u64_u32 v[66:67], s[2:3], v0, s27, v[4:5]
	s_waitcnt lgkmcnt(0)
	s_barrier
	ds_read_b128 v[0:3], v66
	v_and_b32_e32 v5, 0x5f, v32
	v_mul_u32_u24_e32 v5, 0x48, v5
	v_lshl_add_u32 v64, v5, 1, v4
	ds_read_b128 v[4:7], v64 offset:36864
	ds_read_b128 v[150:153], v66 offset:32
	ds_read_b128 v[154:157], v64 offset:36896
	ds_read_b128 v[8:11], v64 offset:41472
	ds_read_b128 v[158:161], v64 offset:41504
	s_waitcnt lgkmcnt(4)
	v_mfma_f32_32x32x16_bf16 v[48:63], v[0:3], v[4:7], 0
	v_add_u32_e32 v67, 0x9000, v68
	s_waitcnt lgkmcnt(1)
	v_mfma_f32_32x32x16_bf16 v[32:47], v[0:3], v[8:11], 0
	ds_read_b128 v[0:3], v66 offset:4608
	ds_read_b128 v[162:165], v66 offset:4640
	global_load_dwordx4 v[166:169], v[76:77], off offset:2432
	global_load_dwordx4 v[170:173], v[78:79], off offset:384
	s_waitcnt vmcnt(9)
	ds_write_b128 v68, v[118:121] offset:18432
	ds_write_b128 v68, v[86:89] offset:55296
	s_waitcnt lgkmcnt(3)
	v_mfma_f32_32x32x16_bf16 v[16:31], v[0:3], v[4:7], 0
	v_mfma_f32_32x32x16_bf16 v[0:15], v[0:3], v[8:11], 0
	global_load_dwordx4 v[86:89], v[74:75], off offset:2432
	global_load_dwordx4 v[118:121], v[84:85], off offset:384
	v_mfma_f32_32x32x16_bf16 v[48:63], v[150:153], v[154:157], v[48:63]
	v_mfma_f32_32x32x16_bf16 v[32:47], v[150:153], v[158:161], v[32:47]
	s_waitcnt lgkmcnt(2)
	v_mfma_f32_32x32x16_bf16 v[16:31], v[162:165], v[154:157], v[16:31]
	ds_read_b128 v[150:153], v66 offset:64
	ds_read_b128 v[154:157], v66 offset:4672
	ds_read_b128 v[174:177], v64 offset:36928
	ds_read_b128 v[178:181], v64 offset:41536
	s_waitcnt vmcnt(10)
	ds_write_b128 v68, v[122:125] offset:23040
	ds_write_b128 v68, v[94:97] offset:59904
	v_mfma_f32_32x32x16_bf16 v[0:15], v[162:165], v[158:161], v[0:15]
	global_load_dwordx4 v[94:97], v[70:71], off offset:2432
	global_load_dwordx4 v[122:125], v[82:83], off offset:384
	s_waitcnt lgkmcnt(3)
	v_mfma_f32_32x32x16_bf16 v[48:63], v[150:153], v[174:177], v[48:63]
	s_waitcnt lgkmcnt(2)
	v_mfma_f32_32x32x16_bf16 v[32:47], v[150:153], v[178:181], v[32:47]
	v_mfma_f32_32x32x16_bf16 v[16:31], v[154:157], v[174:177], v[16:31]
	ds_read_b128 v[150:153], v66 offset:96
	ds_read_b128 v[158:161], v66 offset:4704
	ds_read_b128 v[162:165], v64 offset:36960
	ds_read_b128 v[174:177], v64 offset:41568
	s_waitcnt vmcnt(11)
	ds_write_b128 v68, v[126:129] offset:27648
	ds_write_b128 v68, v[102:105] offset:64512
	v_mfma_f32_32x32x16_bf16 v[0:15], v[154:157], v[178:181], v[0:15]
	global_load_dwordx4 v[102:105], v[72:73], off offset:2432
	global_load_dwordx4 v[126:129], v[80:81], off offset:384
	s_waitcnt lgkmcnt(3)
	v_mfma_f32_32x32x16_bf16 v[48:63], v[150:153], v[162:165], v[48:63]
	s_waitcnt vmcnt(12)
	ds_write_b128 v68, v[130:133] offset:32256
	ds_write_b128 v67, v[110:113] offset:32256
	s_waitcnt lgkmcnt(4)
	v_mfma_f32_32x32x16_bf16 v[32:47], v[150:153], v[174:177], v[32:47]
	v_mfma_f32_32x32x16_bf16 v[16:31], v[158:161], v[162:165], v[16:31]
	v_mfma_f32_32x32x16_bf16 v[0:15], v[158:161], v[174:177], v[0:15]
	s_waitcnt lgkmcnt(0)
	s_barrier
; #define G_LOAD(S, kt_) do { G_LD1(S##a0, S##b0, 0, kt_); G_LD1(S##a1, S##b1, 1, kt_); G_LD1(S##a2, S##b2, 2, kt_); G_LD1(S##a3, S##b3, 3, kt_); } while (0)
; #define G_STORE(S, buf_) do { G_ST1(S##a0, S##b0, 0, buf_); G_ST1(S##a1, S##b1, 1, buf_); G_ST1(S##a2, S##b2, 2, buf_); G_ST1(S##a3, S##b3, 3, buf_); } while (0)
; template <class AL, class BL>
; DI void gemm_core(AL al, BL bl, int m0, int n0, int K, char* smem, f32x16 (&acc)[2][2]) {
;     ...
;   G_LOAD(x, 0);
;   G_STORE(x, 0);
;   G_LOAD(x, 1);
;   G_LOAD(y, (nk > 2) ? 2 : 1);
;   __syncthreads();
;   for (int kt = 0; kt < nk; kt += 2) {
;     G_TILE(0, x, true, (kt + 3 < nk), kt + 3);
;     __syncthreads();
;     G_TILE(1, y, (kt + 2 < nk), (kt + 4 < nk), kt + 4);
;     __syncthreads();
;   }
	ds_read_b128 v[110:113], v66 offset:18432
	ds_read_b128 v[130:133], v64 offset:55296
	ds_read_b128 v[150:153], v66 offset:18464
	ds_read_b128 v[154:157], v64 offset:55328
	ds_read_b128 v[158:161], v64 offset:59904
	ds_read_b128 v[162:165], v64 offset:59936
	s_waitcnt lgkmcnt(4)
	v_mfma_f32_32x32x16_bf16 v[48:63], v[110:113], v[130:133], v[48:63]
	s_waitcnt lgkmcnt(1)
	v_mfma_f32_32x32x16_bf16 v[32:47], v[110:113], v[158:161], v[32:47]
	ds_read_b128 v[110:113], v66 offset:23040
	ds_read_b128 v[174:177], v66 offset:23072
	s_waitcnt lgkmcnt(1)
	v_mfma_f32_32x32x16_bf16 v[16:31], v[110:113], v[130:133], v[16:31]
	global_load_dwordx4 v[130:133], v[76:77], off offset:2560
	global_load_dwordx4 v[178:181], v[78:79], off offset:512
	s_waitcnt vmcnt(13)
	ds_write_b128 v68, v[134:137]
	ds_write_b128 v68, v[90:93] offset:36864
	v_mfma_f32_32x32x16_bf16 v[0:15], v[110:113], v[158:161], v[0:15]
	global_load_dwordx4 v[90:93], v[74:75], off offset:2560
	global_load_dwordx4 v[110:113], v[84:85], off offset:512
	v_mfma_f32_32x32x16_bf16 v[48:63], v[150:153], v[154:157], v[48:63]
	v_mfma_f32_32x32x16_bf16 v[32:47], v[150:153], v[162:165], v[32:47]
	s_waitcnt lgkmcnt(2)
	v_mfma_f32_32x32x16_bf16 v[16:31], v[174:177], v[154:157], v[16:31]
	ds_read_b128 v[134:137], v66 offset:18496
	ds_read_b128 v[150:153], v66 offset:23104
	ds_read_b128 v[154:157], v64 offset:55360
	ds_read_b128 v[158:161], v64 offset:59968
	s_waitcnt vmcnt(14)
	ds_write_b128 v68, v[138:141] offset:4608
	ds_write_b128 v68, v[98:101] offset:41472
	v_mfma_f32_32x32x16_bf16 v[0:15], v[174:177], v[162:165], v[0:15]
	s_waitcnt lgkmcnt(3)
	v_mfma_f32_32x32x16_bf16 v[48:63], v[134:137], v[154:157], v[48:63]
	s_waitcnt lgkmcnt(2)
	v_mfma_f32_32x32x16_bf16 v[32:47], v[134:137], v[158:161], v[32:47]
	global_load_dwordx4 v[98:101], v[70:71], off offset:2560
	global_load_dwordx4 v[134:137], v[82:83], off offset:512
	v_mfma_f32_32x32x16_bf16 v[16:31], v[150:153], v[154:157], v[16:31]
	ds_read_b128 v[138:141], v66 offset:18528
	ds_read_b128 v[154:157], v66 offset:23136
	ds_read_b128 v[162:165], v64 offset:55392
	ds_read_b128 v[174:177], v64 offset:60000
	s_waitcnt vmcnt(15)
	ds_write_b128 v68, v[142:145] offset:9216
	ds_write_b128 v68, v[106:109] offset:46080
	v_mfma_f32_32x32x16_bf16 v[0:15], v[150:153], v[158:161], v[0:15]
	s_waitcnt lgkmcnt(3)
	v_mfma_f32_32x32x16_bf16 v[48:63], v[138:141], v[162:165], v[48:63]
	s_waitcnt lgkmcnt(2)
	v_mfma_f32_32x32x16_bf16 v[32:47], v[138:141], v[174:177], v[32:47]
	global_load_dwordx4 v[106:109], v[72:73], off offset:2560
	global_load_dwordx4 v[138:141], v[80:81], off offset:512
	s_waitcnt vmcnt(16)
	ds_write_b128 v68, v[146:149] offset:13824
	ds_write_b128 v68, v[114:117] offset:50688
	v_mfma_f32_32x32x16_bf16 v[16:31], v[154:157], v[162:165], v[16:31]
	v_mfma_f32_32x32x16_bf16 v[0:15], v[154:157], v[174:177], v[0:15]
	s_waitcnt lgkmcnt(0)
	s_barrier
	ds_read_b128 v[114:117], v66
	ds_read_b128 v[142:145], v64 offset:36864
	ds_read_b128 v[146:149], v66 offset:32
	ds_read_b128 v[150:153], v64 offset:36896
	ds_read_b128 v[154:157], v64 offset:41472
	ds_read_b128 v[158:161], v64 offset:41504
	s_waitcnt lgkmcnt(4)
	v_mfma_f32_32x32x16_bf16 v[48:63], v[114:117], v[142:145], v[48:63]
	s_waitcnt lgkmcnt(1)
	v_mfma_f32_32x32x16_bf16 v[32:47], v[114:117], v[154:157], v[32:47]
	ds_read_b128 v[114:117], v66 offset:4608
	ds_read_b128 v[162:165], v66 offset:4640
	s_waitcnt lgkmcnt(1)
	v_mfma_f32_32x32x16_bf16 v[16:31], v[114:117], v[142:145], v[16:31]
	global_load_dwordx4 v[142:145], v[76:77], off offset:2688
	global_load_dwordx4 v[174:177], v[78:79], off offset:640
	s_waitcnt vmcnt(17)
	ds_write_b128 v68, v[166:169] offset:18432
	s_waitcnt vmcnt(16)
	ds_write_b128 v68, v[170:173] offset:55296
	v_mfma_f32_32x32x16_bf16 v[0:15], v[114:117], v[154:157], v[0:15]
	v_mfma_f32_32x32x16_bf16 v[48:63], v[146:149], v[150:153], v[48:63]
	v_mfma_f32_32x32x16_bf16 v[32:47], v[146:149], v[158:161], v[32:47]
	global_load_dwordx4 v[114:117], v[74:75], off offset:2688
	global_load_dwordx4 v[146:149], v[84:85], off offset:640
	s_waitcnt lgkmcnt(2)
	v_mfma_f32_32x32x16_bf16 v[16:31], v[162:165], v[150:153], v[16:31]
	ds_read_b128 v[150:153], v66 offset:64
	ds_read_b128 v[154:157], v66 offset:4672
	ds_read_b128 v[166:169], v64 offset:36928
	ds_read_b128 v[170:173], v64 offset:41536
	s_waitcnt vmcnt(17)
	ds_write_b128 v68, v[86:89] offset:23040
	s_waitcnt vmcnt(16)
	ds_write_b128 v68, v[118:121] offset:59904
	v_mfma_f32_32x32x16_bf16 v[0:15], v[162:165], v[158:161], v[0:15]
	global_load_dwordx4 v[86:89], v[70:71], off offset:2688
	global_load_dwordx4 v[118:121], v[82:83], off offset:640
	s_waitcnt lgkmcnt(3)
	v_mfma_f32_32x32x16_bf16 v[48:63], v[150:153], v[166:169], v[48:63]
	s_waitcnt lgkmcnt(2)
	v_mfma_f32_32x32x16_bf16 v[32:47], v[150:153], v[170:173], v[32:47]
	v_mfma_f32_32x32x16_bf16 v[16:31], v[154:157], v[166:169], v[16:31]
	ds_read_b128 v[150:153], v66 offset:96
	ds_read_b128 v[158:161], v66 offset:4704
	ds_read_b128 v[162:165], v64 offset:36960
	ds_read_b128 v[166:169], v64 offset:41568
	s_waitcnt vmcnt(17)
	ds_write_b128 v68, v[94:97] offset:27648
	s_waitcnt vmcnt(16)
	ds_write_b128 v68, v[122:125] offset:64512
	v_mfma_f32_32x32x16_bf16 v[0:15], v[154:157], v[170:173], v[0:15]
	global_load_dwordx4 v[94:97], v[72:73], off offset:2688
	global_load_dwordx4 v[122:125], v[80:81], off offset:640
	s_waitcnt lgkmcnt(3)
	v_mfma_f32_32x32x16_bf16 v[48:63], v[150:153], v[162:165], v[48:63]
	s_waitcnt vmcnt(17)
	ds_write_b128 v68, v[102:105] offset:32256
	s_waitcnt vmcnt(16)
	ds_write_b128 v67, v[126:129] offset:32256
	s_waitcnt lgkmcnt(4)
	v_mfma_f32_32x32x16_bf16 v[32:47], v[150:153], v[166:169], v[32:47]
	v_mfma_f32_32x32x16_bf16 v[16:31], v[158:161], v[162:165], v[16:31]
	v_mfma_f32_32x32x16_bf16 v[0:15], v[158:161], v[166:169], v[0:15]
	s_waitcnt lgkmcnt(0)
	s_barrier
; #define G_LOAD(S, kt_) do { G_LD1(S##a0, S##b0, 0, kt_); G_LD1(S##a1, S##b1, 1, kt_); G_LD1(S##a2, S##b2, 2, kt_); G_LD1(S##a3, S##b3, 3, kt_); } while (0)
; #define G_STORE(S, buf_) do { G_ST1(S##a0, S##b0, 0, buf_); G_ST1(S##a1, S##b1, 1, buf_); G_ST1(S##a2, S##b2, 2, buf_); G_ST1(S##a3, S##b3, 3, buf_); } while (0)
; template <class AL, class BL>
; DI void gemm_core(AL al, BL bl, int m0, int n0, int K, char* smem, f32x16 (&acc)[2][2]) {
;     ...
;   G_LOAD(x, 0);
;   G_STORE(x, 0);
;   G_LOAD(x, 1);
;   G_LOAD(y, (nk > 2) ? 2 : 1);
;   __syncthreads();
;   for (int kt = 0; kt < nk; kt += 2) {
;     G_TILE(0, x, true, (kt + 3 < nk), kt + 3);
;     __syncthreads();
;     G_TILE(1, y, (kt + 2 < nk), (kt + 4 < nk), kt + 4);
;     __syncthreads();
;   }
	ds_read_b128 v[102:105], v66 offset:18432
	ds_read_b128 v[126:129], v64 offset:55296
	ds_read_b128 v[150:153], v66 offset:18464
	ds_read_b128 v[154:157], v64 offset:55328
	ds_read_b128 v[158:161], v64 offset:59904
	ds_read_b128 v[162:165], v64 offset:59936
	s_waitcnt lgkmcnt(4)
	v_mfma_f32_32x32x16_bf16 v[48:63], v[102:105], v[126:129], v[48:63]
	s_waitcnt lgkmcnt(1)
	v_mfma_f32_32x32x16_bf16 v[32:47], v[102:105], v[158:161], v[32:47]
	ds_read_b128 v[102:105], v66 offset:23040
	ds_read_b128 v[166:169], v66 offset:23072
	s_waitcnt lgkmcnt(1)
	v_mfma_f32_32x32x16_bf16 v[16:31], v[102:105], v[126:129], v[16:31]
	global_load_dwordx4 v[126:129], v[76:77], off offset:2816
	global_load_dwordx4 v[170:173], v[78:79], off offset:768
	s_waitcnt vmcnt(17)
	ds_write_b128 v68, v[130:133]
	s_waitcnt vmcnt(16)
	ds_write_b128 v68, v[178:181] offset:36864
	v_mfma_f32_32x32x16_bf16 v[0:15], v[102:105], v[158:161], v[0:15]
	global_load_dwordx4 v[102:105], v[74:75], off offset:2816
	global_load_dwordx4 v[130:133], v[84:85], off offset:768
	v_mfma_f32_32x32x16_bf16 v[48:63], v[150:153], v[154:157], v[48:63]
	v_mfma_f32_32x32x16_bf16 v[32:47], v[150:153], v[162:165], v[32:47]
	s_waitcnt lgkmcnt(2)
	v_mfma_f32_32x32x16_bf16 v[16:31], v[166:169], v[154:157], v[16:31]
	ds_read_b128 v[150:153], v66 offset:18496
	ds_read_b128 v[154:157], v66 offset:23104
	ds_read_b128 v[158:161], v64 offset:55360
	ds_read_b128 v[178:181], v64 offset:59968
	s_waitcnt vmcnt(17)
	ds_write_b128 v68, v[90:93] offset:4608
	s_waitcnt vmcnt(16)
	ds_write_b128 v68, v[110:113] offset:41472
	v_mfma_f32_32x32x16_bf16 v[0:15], v[166:169], v[162:165], v[0:15]
	global_load_dwordx4 v[90:93], v[70:71], off offset:2816
	global_load_dwordx4 v[110:113], v[82:83], off offset:768
	s_waitcnt lgkmcnt(3)
	v_mfma_f32_32x32x16_bf16 v[48:63], v[150:153], v[158:161], v[48:63]
	s_waitcnt lgkmcnt(2)
	v_mfma_f32_32x32x16_bf16 v[32:47], v[150:153], v[178:181], v[32:47]
	v_mfma_f32_32x32x16_bf16 v[16:31], v[154:157], v[158:161], v[16:31]
	ds_read_b128 v[150:153], v66 offset:18528
	ds_read_b128 v[158:161], v66 offset:23136
	ds_read_b128 v[162:165], v64 offset:55392
	ds_read_b128 v[166:169], v64 offset:60000
	s_waitcnt vmcnt(17)
	ds_write_b128 v68, v[98:101] offset:9216
	s_waitcnt vmcnt(16)
	ds_write_b128 v68, v[134:137] offset:46080
	v_mfma_f32_32x32x16_bf16 v[0:15], v[154:157], v[178:181], v[0:15]
	global_load_dwordx4 v[98:101], v[72:73], off offset:2816
	global_load_dwordx4 v[134:137], v[80:81], off offset:768
	s_waitcnt lgkmcnt(3)
	v_mfma_f32_32x32x16_bf16 v[48:63], v[150:153], v[162:165], v[48:63]
	s_waitcnt vmcnt(17)
	ds_write_b128 v68, v[106:109] offset:13824
	s_waitcnt vmcnt(16)
	ds_write_b128 v68, v[138:141] offset:50688
	s_waitcnt lgkmcnt(4)
	v_mfma_f32_32x32x16_bf16 v[32:47], v[150:153], v[166:169], v[32:47]
	v_mfma_f32_32x32x16_bf16 v[16:31], v[158:161], v[162:165], v[16:31]
	v_mfma_f32_32x32x16_bf16 v[0:15], v[158:161], v[166:169], v[0:15]
	s_waitcnt lgkmcnt(0)
	s_barrier
	ds_read_b128 v[106:109], v66
	ds_read_b128 v[138:141], v64 offset:36864
	ds_read_b128 v[150:153], v66 offset:32
	ds_read_b128 v[154:157], v64 offset:36896
	ds_read_b128 v[158:161], v64 offset:41472
	ds_read_b128 v[162:165], v64 offset:41504
	s_waitcnt lgkmcnt(4)
	v_mfma_f32_32x32x16_bf16 v[48:63], v[106:109], v[138:141], v[48:63]
	s_waitcnt lgkmcnt(1)
	v_mfma_f32_32x32x16_bf16 v[32:47], v[106:109], v[158:161], v[32:47]
	ds_read_b128 v[106:109], v66 offset:4608
	ds_read_b128 v[166:169], v66 offset:4640
	s_waitcnt lgkmcnt(1)
	v_mfma_f32_32x32x16_bf16 v[16:31], v[106:109], v[138:141], v[16:31]
	global_load_dwordx4 v[138:141], v[76:77], off offset:2944
	global_load_dwordx4 v[178:181], v[78:79], off offset:896
	s_waitcnt vmcnt(17)
	ds_write_b128 v68, v[142:145] offset:18432
	s_waitcnt vmcnt(16)
	ds_write_b128 v68, v[174:177] offset:55296
	v_mfma_f32_32x32x16_bf16 v[0:15], v[106:109], v[158:161], v[0:15]
	global_load_dwordx4 v[106:109], v[74:75], off offset:2944
	global_load_dwordx4 v[142:145], v[84:85], off offset:896
	v_mfma_f32_32x32x16_bf16 v[48:63], v[150:153], v[154:157], v[48:63]
	v_mfma_f32_32x32x16_bf16 v[32:47], v[150:153], v[162:165], v[32:47]
	s_waitcnt lgkmcnt(2)
	v_mfma_f32_32x32x16_bf16 v[16:31], v[166:169], v[154:157], v[16:31]
	ds_read_b128 v[150:153], v66 offset:64
	ds_read_b128 v[154:157], v66 offset:4672
	ds_read_b128 v[158:161], v64 offset:36928
	ds_read_b128 v[174:177], v64 offset:41536
	s_waitcnt vmcnt(17)
	ds_write_b128 v68, v[114:117] offset:23040
	s_waitcnt vmcnt(16)
	ds_write_b128 v68, v[146:149] offset:59904
	v_mfma_f32_32x32x16_bf16 v[0:15], v[166:169], v[162:165], v[0:15]
	global_load_dwordx4 v[114:117], v[70:71], off offset:2944
	global_load_dwordx4 v[146:149], v[82:83], off offset:896
	s_waitcnt lgkmcnt(3)
	v_mfma_f32_32x32x16_bf16 v[48:63], v[150:153], v[158:161], v[48:63]
	s_waitcnt lgkmcnt(2)
	v_mfma_f32_32x32x16_bf16 v[32:47], v[150:153], v[174:177], v[32:47]
	v_mfma_f32_32x32x16_bf16 v[16:31], v[154:157], v[158:161], v[16:31]
	ds_read_b128 v[150:153], v66 offset:96
	ds_read_b128 v[158:161], v66 offset:4704
	ds_read_b128 v[162:165], v64 offset:36960
	ds_read_b128 v[166:169], v64 offset:41568
	s_waitcnt vmcnt(17)
	ds_write_b128 v68, v[86:89] offset:27648
	s_waitcnt vmcnt(16)
	ds_write_b128 v68, v[118:121] offset:64512
	v_mfma_f32_32x32x16_bf16 v[0:15], v[154:157], v[174:177], v[0:15]
	global_load_dwordx4 v[86:89], v[72:73], off offset:2944
	global_load_dwordx4 v[118:121], v[80:81], off offset:896
	s_waitcnt lgkmcnt(3)
	v_mfma_f32_32x32x16_bf16 v[48:63], v[150:153], v[162:165], v[48:63]
	s_waitcnt vmcnt(17)
	ds_write_b128 v68, v[94:97] offset:32256
	s_waitcnt vmcnt(16)
	ds_write_b128 v67, v[122:125] offset:32256
	s_waitcnt lgkmcnt(4)
	v_mfma_f32_32x32x16_bf16 v[32:47], v[150:153], v[166:169], v[32:47]
	v_mfma_f32_32x32x16_bf16 v[16:31], v[158:161], v[162:165], v[16:31]
	v_mfma_f32_32x32x16_bf16 v[0:15], v[158:161], v[166:169], v[0:15]
	s_waitcnt lgkmcnt(0)
	s_barrier
; #define G_LOAD(S, kt_) do { G_LD1(S##a0, S##b0, 0, kt_); G_LD1(S##a1, S##b1, 1, kt_); G_LD1(S##a2, S##b2, 2, kt_); G_LD1(S##a3, S##b3, 3, kt_); } while (0)
; #define G_STORE(S, buf_) do { G_ST1(S##a0, S##b0, 0, buf_); G_ST1(S##a1, S##b1, 1, buf_); G_ST1(S##a2, S##b2, 2, buf_); G_ST1(S##a3, S##b3, 3, buf_); } while (0)
; template <class AL, class BL>
; DI void gemm_core(AL al, BL bl, int m0, int n0, int K, char* smem, f32x16 (&acc)[2][2]) {
;     ...
;   G_LOAD(x, 0);
;   G_STORE(x, 0);
;   G_LOAD(x, 1);
;   G_LOAD(y, (nk > 2) ? 2 : 1);
;   __syncthreads();
;   for (int kt = 0; kt < nk; kt += 2) {
;     G_TILE(0, x, true, (kt + 3 < nk), kt + 3);
;     __syncthreads();
;     G_TILE(1, y, (kt + 2 < nk), (kt + 4 < nk), kt + 4);
;     __syncthreads();
;   }
	ds_read_b128 v[94:97], v66 offset:18432
	ds_read_b128 v[122:125], v64 offset:55296
	ds_read_b128 v[150:153], v66 offset:18464
	ds_read_b128 v[154:157], v64 offset:55328
	ds_read_b128 v[158:161], v64 offset:59904
	ds_read_b128 v[162:165], v64 offset:59936
	s_waitcnt lgkmcnt(4)
	v_mfma_f32_32x32x16_bf16 v[48:63], v[94:97], v[122:125], v[48:63]
	s_waitcnt lgkmcnt(1)
	v_mfma_f32_32x32x16_bf16 v[32:47], v[94:97], v[158:161], v[32:47]
	ds_read_b128 v[94:97], v66 offset:23040
	ds_read_b128 v[166:169], v66 offset:23072
	s_waitcnt lgkmcnt(1)
	v_mfma_f32_32x32x16_bf16 v[16:31], v[94:97], v[122:125], v[16:31]
	global_load_dwordx4 v[122:125], v[76:77], off offset:3072
	global_load_dwordx4 v[174:177], v[78:79], off offset:1024
	s_waitcnt vmcnt(17)
	ds_write_b128 v68, v[126:129]
	s_waitcnt vmcnt(16)
	ds_write_b128 v68, v[170:173] offset:36864
	v_mfma_f32_32x32x16_bf16 v[0:15], v[94:97], v[158:161], v[0:15]
	global_load_dwordx4 v[94:97], v[74:75], off offset:3072
	global_load_dwordx4 v[126:129], v[84:85], off offset:1024
	v_mfma_f32_32x32x16_bf16 v[48:63], v[150:153], v[154:157], v[48:63]
	v_mfma_f32_32x32x16_bf16 v[32:47], v[150:153], v[162:165], v[32:47]
	s_waitcnt lgkmcnt(2)
	v_mfma_f32_32x32x16_bf16 v[16:31], v[166:169], v[154:157], v[16:31]
	ds_read_b128 v[150:153], v66 offset:18496
	ds_read_b128 v[154:157], v66 offset:23104
	ds_read_b128 v[158:161], v64 offset:55360
	ds_read_b128 v[170:173], v64 offset:59968
	s_waitcnt vmcnt(17)
	ds_write_b128 v68, v[102:105] offset:4608
	s_waitcnt vmcnt(16)
	ds_write_b128 v68, v[130:133] offset:41472
	v_mfma_f32_32x32x16_bf16 v[0:15], v[166:169], v[162:165], v[0:15]
	global_load_dwordx4 v[102:105], v[70:71], off offset:3072
	global_load_dwordx4 v[130:133], v[82:83], off offset:1024
	s_waitcnt lgkmcnt(3)
	v_mfma_f32_32x32x16_bf16 v[48:63], v[150:153], v[158:161], v[48:63]
	s_waitcnt lgkmcnt(2)
	v_mfma_f32_32x32x16_bf16 v[32:47], v[150:153], v[170:173], v[32:47]
	v_mfma_f32_32x32x16_bf16 v[16:31], v[154:157], v[158:161], v[16:31]
	ds_read_b128 v[150:153], v66 offset:18528
	ds_read_b128 v[158:161], v66 offset:23136
	ds_read_b128 v[162:165], v64 offset:55392
	ds_read_b128 v[166:169], v64 offset:60000
	s_waitcnt vmcnt(17)
	ds_write_b128 v68, v[90:93] offset:9216
	s_waitcnt vmcnt(16)
	ds_write_b128 v68, v[110:113] offset:46080
	v_mfma_f32_32x32x16_bf16 v[0:15], v[154:157], v[170:173], v[0:15]
	global_load_dwordx4 v[90:93], v[72:73], off offset:3072
	global_load_dwordx4 v[110:113], v[80:81], off offset:1024
	s_waitcnt lgkmcnt(3)
	v_mfma_f32_32x32x16_bf16 v[48:63], v[150:153], v[162:165], v[48:63]
	s_waitcnt vmcnt(17)
	ds_write_b128 v68, v[98:101] offset:13824
	s_waitcnt vmcnt(16)
	ds_write_b128 v68, v[134:137] offset:50688
	s_waitcnt lgkmcnt(4)
	v_mfma_f32_32x32x16_bf16 v[32:47], v[150:153], v[166:169], v[32:47]
	v_mfma_f32_32x32x16_bf16 v[16:31], v[158:161], v[162:165], v[16:31]
	v_mfma_f32_32x32x16_bf16 v[0:15], v[158:161], v[166:169], v[0:15]
	s_waitcnt lgkmcnt(0)
	s_barrier
	ds_read_b128 v[98:101], v66
	ds_read_b128 v[134:137], v64 offset:36864
	ds_read_b128 v[150:153], v66 offset:32
	ds_read_b128 v[154:157], v64 offset:36896
	ds_read_b128 v[158:161], v64 offset:41472
	ds_read_b128 v[162:165], v64 offset:41504
	s_waitcnt lgkmcnt(4)
	v_mfma_f32_32x32x16_bf16 v[48:63], v[98:101], v[134:137], v[48:63]
	s_waitcnt lgkmcnt(1)
	v_mfma_f32_32x32x16_bf16 v[32:47], v[98:101], v[158:161], v[32:47]
	ds_read_b128 v[98:101], v66 offset:4608
	ds_read_b128 v[166:169], v66 offset:4640
	s_waitcnt lgkmcnt(1)
	v_mfma_f32_32x32x16_bf16 v[16:31], v[98:101], v[134:137], v[16:31]
	global_load_dwordx4 v[134:137], v[76:77], off offset:3200
	global_load_dwordx4 v[170:173], v[78:79], off offset:1152
	s_waitcnt vmcnt(17)
	ds_write_b128 v68, v[138:141] offset:18432
	s_waitcnt vmcnt(16)
	ds_write_b128 v68, v[178:181] offset:55296
	v_mfma_f32_32x32x16_bf16 v[0:15], v[98:101], v[158:161], v[0:15]
	global_load_dwordx4 v[98:101], v[74:75], off offset:3200
	global_load_dwordx4 v[138:141], v[84:85], off offset:1152
	v_mfma_f32_32x32x16_bf16 v[48:63], v[150:153], v[154:157], v[48:63]
	v_mfma_f32_32x32x16_bf16 v[32:47], v[150:153], v[162:165], v[32:47]
	s_waitcnt lgkmcnt(2)
	v_mfma_f32_32x32x16_bf16 v[16:31], v[166:169], v[154:157], v[16:31]
	ds_read_b128 v[150:153], v66 offset:64
	ds_read_b128 v[154:157], v66 offset:4672
	ds_read_b128 v[158:161], v64 offset:36928
	ds_read_b128 v[178:181], v64 offset:41536
	s_waitcnt vmcnt(17)
	ds_write_b128 v68, v[106:109] offset:23040
	s_waitcnt vmcnt(16)
	ds_write_b128 v68, v[142:145] offset:59904
	v_mfma_f32_32x32x16_bf16 v[0:15], v[166:169], v[162:165], v[0:15]
	global_load_dwordx4 v[106:109], v[70:71], off offset:3200
	global_load_dwordx4 v[142:145], v[82:83], off offset:1152
	s_waitcnt lgkmcnt(3)
	v_mfma_f32_32x32x16_bf16 v[48:63], v[150:153], v[158:161], v[48:63]
	s_waitcnt lgkmcnt(2)
	v_mfma_f32_32x32x16_bf16 v[32:47], v[150:153], v[178:181], v[32:47]
	v_mfma_f32_32x32x16_bf16 v[16:31], v[154:157], v[158:161], v[16:31]
	ds_read_b128 v[150:153], v66 offset:96
	ds_read_b128 v[158:161], v66 offset:4704
	ds_read_b128 v[162:165], v64 offset:36960
	ds_read_b128 v[166:169], v64 offset:41568
	s_waitcnt vmcnt(17)
	ds_write_b128 v68, v[114:117] offset:27648
	s_waitcnt vmcnt(16)
	ds_write_b128 v68, v[146:149] offset:64512
	v_mfma_f32_32x32x16_bf16 v[0:15], v[154:157], v[178:181], v[0:15]
	global_load_dwordx4 v[114:117], v[72:73], off offset:3200
	global_load_dwordx4 v[146:149], v[80:81], off offset:1152
	s_waitcnt lgkmcnt(3)
	v_mfma_f32_32x32x16_bf16 v[48:63], v[150:153], v[162:165], v[48:63]
	s_waitcnt vmcnt(17)
	ds_write_b128 v68, v[86:89] offset:32256
	s_waitcnt vmcnt(16)
	ds_write_b128 v67, v[118:121] offset:32256
	s_waitcnt lgkmcnt(4)
	v_mfma_f32_32x32x16_bf16 v[32:47], v[150:153], v[166:169], v[32:47]
	v_mfma_f32_32x32x16_bf16 v[16:31], v[158:161], v[162:165], v[16:31]
	v_mfma_f32_32x32x16_bf16 v[0:15], v[158:161], v[166:169], v[0:15]
	s_waitcnt lgkmcnt(0)
	s_barrier
; #define G_LOAD(S, kt_) do { G_LD1(S##a0, S##b0, 0, kt_); G_LD1(S##a1, S##b1, 1, kt_); G_LD1(S##a2, S##b2, 2, kt_); G_LD1(S##a3, S##b3, 3, kt_); } while (0)
; #define G_STORE(S, buf_) do { G_ST1(S##a0, S##b0, 0, buf_); G_ST1(S##a1, S##b1, 1, buf_); G_ST1(S##a2, S##b2, 2, buf_); G_ST1(S##a3, S##b3, 3, buf_); } while (0)
; template <class AL, class BL>
; DI void gemm_core(AL al, BL bl, int m0, int n0, int K, char* smem, f32x16 (&acc)[2][2]) {
;     ...
;   G_LOAD(x, 0);
;   G_STORE(x, 0);
;   G_LOAD(x, 1);
;   G_LOAD(y, (nk > 2) ? 2 : 1);
;   __syncthreads();
;   for (int kt = 0; kt < nk; kt += 2) {
;     G_TILE(0, x, true, (kt + 3 < nk), kt + 3);
;     __syncthreads();
;     G_TILE(1, y, (kt + 2 < nk), (kt + 4 < nk), kt + 4);
;     __syncthreads();
;   }
	ds_read_b128 v[86:89], v66 offset:18432
	ds_read_b128 v[118:121], v64 offset:55296
	ds_read_b128 v[150:153], v66 offset:18464
	ds_read_b128 v[154:157], v64 offset:55328
	ds_read_b128 v[158:161], v64 offset:59904
	ds_read_b128 v[162:165], v64 offset:59936
	s_waitcnt lgkmcnt(4)
	v_mfma_f32_32x32x16_bf16 v[48:63], v[86:89], v[118:121], v[48:63]
	s_waitcnt lgkmcnt(1)
	v_mfma_f32_32x32x16_bf16 v[32:47], v[86:89], v[158:161], v[32:47]
	ds_read_b128 v[86:89], v66 offset:23040
	ds_read_b128 v[166:169], v66 offset:23072
	s_waitcnt lgkmcnt(1)
	v_mfma_f32_32x32x16_bf16 v[16:31], v[86:89], v[118:121], v[16:31]
	global_load_dwordx4 v[118:121], v[76:77], off offset:3328
	global_load_dwordx4 v[178:181], v[78:79], off offset:1280
	s_waitcnt vmcnt(17)
	ds_write_b128 v68, v[122:125]
	s_waitcnt vmcnt(16)
	ds_write_b128 v68, v[174:177] offset:36864
	v_mfma_f32_32x32x16_bf16 v[0:15], v[86:89], v[158:161], v[0:15]
	global_load_dwordx4 v[86:89], v[74:75], off offset:3328
	global_load_dwordx4 v[122:125], v[84:85], off offset:1280
	v_mfma_f32_32x32x16_bf16 v[48:63], v[150:153], v[154:157], v[48:63]
	v_mfma_f32_32x32x16_bf16 v[32:47], v[150:153], v[162:165], v[32:47]
	s_waitcnt lgkmcnt(2)
	v_mfma_f32_32x32x16_bf16 v[16:31], v[166:169], v[154:157], v[16:31]
	ds_read_b128 v[150:153], v66 offset:18496
	ds_read_b128 v[154:157], v66 offset:23104
	ds_read_b128 v[158:161], v64 offset:55360
	ds_read_b128 v[174:177], v64 offset:59968
	s_waitcnt vmcnt(17)
	ds_write_b128 v68, v[94:97] offset:4608
	s_waitcnt vmcnt(16)
	ds_write_b128 v68, v[126:129] offset:41472
	v_mfma_f32_32x32x16_bf16 v[0:15], v[166:169], v[162:165], v[0:15]
	global_load_dwordx4 v[94:97], v[70:71], off offset:3328
	global_load_dwordx4 v[126:129], v[82:83], off offset:1280
	s_waitcnt lgkmcnt(3)
	v_mfma_f32_32x32x16_bf16 v[48:63], v[150:153], v[158:161], v[48:63]
	s_waitcnt lgkmcnt(2)
	v_mfma_f32_32x32x16_bf16 v[32:47], v[150:153], v[174:177], v[32:47]
	v_mfma_f32_32x32x16_bf16 v[16:31], v[154:157], v[158:161], v[16:31]
	ds_read_b128 v[150:153], v66 offset:18528
	ds_read_b128 v[158:161], v66 offset:23136
	ds_read_b128 v[162:165], v64 offset:55392
	ds_read_b128 v[166:169], v64 offset:60000
	s_waitcnt vmcnt(17)
	ds_write_b128 v68, v[102:105] offset:9216
	s_waitcnt vmcnt(16)
	ds_write_b128 v68, v[130:133] offset:46080
	v_mfma_f32_32x32x16_bf16 v[0:15], v[154:157], v[174:177], v[0:15]
	global_load_dwordx4 v[102:105], v[72:73], off offset:3328
	global_load_dwordx4 v[130:133], v[80:81], off offset:1280
	s_waitcnt lgkmcnt(3)
	v_mfma_f32_32x32x16_bf16 v[48:63], v[150:153], v[162:165], v[48:63]
	s_waitcnt vmcnt(17)
	ds_write_b128 v68, v[90:93] offset:13824
	s_waitcnt vmcnt(16)
	ds_write_b128 v68, v[110:113] offset:50688
	s_waitcnt lgkmcnt(4)
	v_mfma_f32_32x32x16_bf16 v[32:47], v[150:153], v[166:169], v[32:47]
	v_mfma_f32_32x32x16_bf16 v[16:31], v[158:161], v[162:165], v[16:31]
	v_mfma_f32_32x32x16_bf16 v[0:15], v[158:161], v[166:169], v[0:15]
	s_waitcnt lgkmcnt(0)
	s_barrier
	ds_read_b128 v[90:93], v66
	ds_read_b128 v[110:113], v64 offset:36864
	ds_read_b128 v[150:153], v66 offset:32
	ds_read_b128 v[154:157], v64 offset:36896
	ds_read_b128 v[158:161], v64 offset:41472
	ds_read_b128 v[162:165], v64 offset:41504
	s_waitcnt lgkmcnt(4)
	v_mfma_f32_32x32x16_bf16 v[48:63], v[90:93], v[110:113], v[48:63]
	s_waitcnt lgkmcnt(1)
	v_mfma_f32_32x32x16_bf16 v[32:47], v[90:93], v[158:161], v[32:47]
	ds_read_b128 v[90:93], v66 offset:4608
	ds_read_b128 v[166:169], v66 offset:4640
	s_waitcnt lgkmcnt(1)
	v_mfma_f32_32x32x16_bf16 v[16:31], v[90:93], v[110:113], v[16:31]
	global_load_dwordx4 v[110:113], v[76:77], off offset:3456
	global_load_dwordx4 v[174:177], v[78:79], off offset:1408
	s_waitcnt vmcnt(17)
	ds_write_b128 v68, v[134:137] offset:18432
	s_waitcnt vmcnt(16)
	ds_write_b128 v68, v[170:173] offset:55296
	v_mfma_f32_32x32x16_bf16 v[0:15], v[90:93], v[158:161], v[0:15]
	global_load_dwordx4 v[90:93], v[74:75], off offset:3456
	global_load_dwordx4 v[134:137], v[84:85], off offset:1408
	v_mfma_f32_32x32x16_bf16 v[48:63], v[150:153], v[154:157], v[48:63]
	v_mfma_f32_32x32x16_bf16 v[32:47], v[150:153], v[162:165], v[32:47]
	s_waitcnt lgkmcnt(2)
	v_mfma_f32_32x32x16_bf16 v[16:31], v[166:169], v[154:157], v[16:31]
	ds_read_b128 v[150:153], v66 offset:64
	ds_read_b128 v[154:157], v66 offset:4672
	ds_read_b128 v[158:161], v64 offset:36928
	ds_read_b128 v[170:173], v64 offset:41536
	s_waitcnt vmcnt(17)
	ds_write_b128 v68, v[98:101] offset:23040
	s_waitcnt vmcnt(16)
	ds_write_b128 v68, v[138:141] offset:59904
	v_mfma_f32_32x32x16_bf16 v[0:15], v[166:169], v[162:165], v[0:15]
	global_load_dwordx4 v[98:101], v[70:71], off offset:3456
	global_load_dwordx4 v[138:141], v[82:83], off offset:1408
	s_waitcnt lgkmcnt(3)
	v_mfma_f32_32x32x16_bf16 v[48:63], v[150:153], v[158:161], v[48:63]
	s_waitcnt lgkmcnt(2)
	v_mfma_f32_32x32x16_bf16 v[32:47], v[150:153], v[170:173], v[32:47]
	v_mfma_f32_32x32x16_bf16 v[16:31], v[154:157], v[158:161], v[16:31]
	ds_read_b128 v[150:153], v66 offset:96
	ds_read_b128 v[158:161], v66 offset:4704
	ds_read_b128 v[162:165], v64 offset:36960
	ds_read_b128 v[166:169], v64 offset:41568
	s_waitcnt vmcnt(17)
	ds_write_b128 v68, v[106:109] offset:27648
	s_waitcnt vmcnt(16)
	ds_write_b128 v68, v[142:145] offset:64512
	v_mfma_f32_32x32x16_bf16 v[0:15], v[154:157], v[170:173], v[0:15]
	global_load_dwordx4 v[106:109], v[72:73], off offset:3456
	global_load_dwordx4 v[142:145], v[80:81], off offset:1408
	s_waitcnt lgkmcnt(3)
	v_mfma_f32_32x32x16_bf16 v[48:63], v[150:153], v[162:165], v[48:63]
	s_waitcnt vmcnt(17)
	ds_write_b128 v68, v[114:117] offset:32256
	s_waitcnt vmcnt(16)
	ds_write_b128 v67, v[146:149] offset:32256
	s_waitcnt lgkmcnt(4)
	v_mfma_f32_32x32x16_bf16 v[32:47], v[150:153], v[166:169], v[32:47]
	v_mfma_f32_32x32x16_bf16 v[16:31], v[158:161], v[162:165], v[16:31]
	v_mfma_f32_32x32x16_bf16 v[0:15], v[158:161], v[166:169], v[0:15]
	s_waitcnt lgkmcnt(0)
	s_barrier
; #define G_LOAD(S, kt_) do { G_LD1(S##a0, S##b0, 0, kt_); G_LD1(S##a1, S##b1, 1, kt_); G_LD1(S##a2, S##b2, 2, kt_); G_LD1(S##a3, S##b3, 3, kt_); } while (0)
; #define G_STORE(S, buf_) do { G_ST1(S##a0, S##b0, 0, buf_); G_ST1(S##a1, S##b1, 1, buf_); G_ST1(S##a2, S##b2, 2, buf_); G_ST1(S##a3, S##b3, 3, buf_); } while (0)
; template <class AL, class BL>
; DI void gemm_core(AL al, BL bl, int m0, int n0, int K, char* smem, f32x16 (&acc)[2][2]) {
;     ...
;   G_LOAD(x, 0);
;   G_STORE(x, 0);
;   G_LOAD(x, 1);
;   G_LOAD(y, (nk > 2) ? 2 : 1);
;   __syncthreads();
;   for (int kt = 0; kt < nk; kt += 2) {
;     G_TILE(0, x, true, (kt + 3 < nk), kt + 3);
;     __syncthreads();
;     G_TILE(1, y, (kt + 2 < nk), (kt + 4 < nk), kt + 4);
;     __syncthreads();
;   }
	ds_read_b128 v[114:117], v66 offset:18432
	ds_read_b128 v[146:149], v64 offset:55296
	ds_read_b128 v[150:153], v66 offset:18464
	ds_read_b128 v[154:157], v64 offset:55328
	ds_read_b128 v[158:161], v64 offset:59904
	ds_read_b128 v[162:165], v64 offset:59936
	s_waitcnt lgkmcnt(4)
	v_mfma_f32_32x32x16_bf16 v[48:63], v[114:117], v[146:149], v[48:63]
	s_waitcnt lgkmcnt(1)
	v_mfma_f32_32x32x16_bf16 v[32:47], v[114:117], v[158:161], v[32:47]
	ds_read_b128 v[114:117], v66 offset:23040
	ds_read_b128 v[166:169], v66 offset:23072
	s_waitcnt lgkmcnt(1)
	v_mfma_f32_32x32x16_bf16 v[16:31], v[114:117], v[146:149], v[16:31]
	global_load_dwordx4 v[146:149], v[76:77], off offset:3584
	global_load_dwordx4 v[170:173], v[78:79], off offset:1536
	s_waitcnt vmcnt(17)
	ds_write_b128 v68, v[118:121]
	s_waitcnt vmcnt(16)
	ds_write_b128 v68, v[178:181] offset:36864
	v_mfma_f32_32x32x16_bf16 v[0:15], v[114:117], v[158:161], v[0:15]
	global_load_dwordx4 v[114:117], v[74:75], off offset:3584
	global_load_dwordx4 v[118:121], v[84:85], off offset:1536
	v_mfma_f32_32x32x16_bf16 v[48:63], v[150:153], v[154:157], v[48:63]
	v_mfma_f32_32x32x16_bf16 v[32:47], v[150:153], v[162:165], v[32:47]
	s_waitcnt lgkmcnt(2)
	v_mfma_f32_32x32x16_bf16 v[16:31], v[166:169], v[154:157], v[16:31]
	ds_read_b128 v[150:153], v66 offset:18496
	ds_read_b128 v[154:157], v66 offset:23104
	ds_read_b128 v[158:161], v64 offset:55360
	ds_read_b128 v[178:181], v64 offset:59968
	s_waitcnt vmcnt(17)
	ds_write_b128 v68, v[86:89] offset:4608
	s_waitcnt vmcnt(16)
	ds_write_b128 v68, v[122:125] offset:41472
	v_mfma_f32_32x32x16_bf16 v[0:15], v[166:169], v[162:165], v[0:15]
	global_load_dwordx4 v[86:89], v[70:71], off offset:3584
	global_load_dwordx4 v[122:125], v[82:83], off offset:1536
	s_waitcnt lgkmcnt(3)
	v_mfma_f32_32x32x16_bf16 v[48:63], v[150:153], v[158:161], v[48:63]
	s_waitcnt lgkmcnt(2)
	v_mfma_f32_32x32x16_bf16 v[32:47], v[150:153], v[178:181], v[32:47]
	v_mfma_f32_32x32x16_bf16 v[16:31], v[154:157], v[158:161], v[16:31]
	ds_read_b128 v[150:153], v66 offset:18528
	ds_read_b128 v[158:161], v66 offset:23136
	ds_read_b128 v[162:165], v64 offset:55392
	ds_read_b128 v[166:169], v64 offset:60000
	s_waitcnt vmcnt(17)
	ds_write_b128 v68, v[94:97] offset:9216
	s_waitcnt vmcnt(16)
	ds_write_b128 v68, v[126:129] offset:46080
	v_mfma_f32_32x32x16_bf16 v[0:15], v[154:157], v[178:181], v[0:15]
	global_load_dwordx4 v[94:97], v[72:73], off offset:3584
	global_load_dwordx4 v[126:129], v[80:81], off offset:1536
	s_waitcnt lgkmcnt(3)
	v_mfma_f32_32x32x16_bf16 v[48:63], v[150:153], v[162:165], v[48:63]
	s_waitcnt vmcnt(17)
	ds_write_b128 v68, v[102:105] offset:13824
	s_waitcnt vmcnt(16)
	ds_write_b128 v68, v[130:133] offset:50688
	s_waitcnt lgkmcnt(4)
	v_mfma_f32_32x32x16_bf16 v[32:47], v[150:153], v[166:169], v[32:47]
	v_mfma_f32_32x32x16_bf16 v[16:31], v[158:161], v[162:165], v[16:31]
	v_mfma_f32_32x32x16_bf16 v[0:15], v[158:161], v[166:169], v[0:15]
	s_waitcnt lgkmcnt(0)
	s_barrier
	ds_read_b128 v[102:105], v66
	ds_read_b128 v[130:133], v64 offset:36864
	ds_read_b128 v[150:153], v66 offset:32
	ds_read_b128 v[154:157], v64 offset:36896
	ds_read_b128 v[158:161], v64 offset:41472
	ds_read_b128 v[162:165], v64 offset:41504
	s_waitcnt lgkmcnt(4)
	v_mfma_f32_32x32x16_bf16 v[48:63], v[102:105], v[130:133], v[48:63]
	s_waitcnt lgkmcnt(1)
	v_mfma_f32_32x32x16_bf16 v[32:47], v[102:105], v[158:161], v[32:47]
	ds_read_b128 v[102:105], v66 offset:4608
	ds_read_b128 v[166:169], v66 offset:4640
	s_waitcnt lgkmcnt(1)
	v_mfma_f32_32x32x16_bf16 v[16:31], v[102:105], v[130:133], v[16:31]
	global_load_dwordx4 v[130:133], v[76:77], off offset:3712
	global_load_dwordx4 v[178:181], v[78:79], off offset:1664
	s_waitcnt vmcnt(17)
	ds_write_b128 v68, v[110:113] offset:18432
	s_waitcnt vmcnt(16)
	ds_write_b128 v68, v[174:177] offset:55296
	v_mfma_f32_32x32x16_bf16 v[0:15], v[102:105], v[158:161], v[0:15]
	global_load_dwordx4 v[102:105], v[74:75], off offset:3712
	global_load_dwordx4 v[110:113], v[84:85], off offset:1664
	v_mfma_f32_32x32x16_bf16 v[48:63], v[150:153], v[154:157], v[48:63]
	v_mfma_f32_32x32x16_bf16 v[32:47], v[150:153], v[162:165], v[32:47]
	s_waitcnt lgkmcnt(2)
	v_mfma_f32_32x32x16_bf16 v[16:31], v[166:169], v[154:157], v[16:31]
	ds_read_b128 v[150:153], v66 offset:64
	ds_read_b128 v[154:157], v66 offset:4672
	ds_read_b128 v[158:161], v64 offset:36928
	ds_read_b128 v[174:177], v64 offset:41536
	s_waitcnt vmcnt(17)
	ds_write_b128 v68, v[90:93] offset:23040
	s_waitcnt vmcnt(16)
	ds_write_b128 v68, v[134:137] offset:59904
	v_mfma_f32_32x32x16_bf16 v[0:15], v[166:169], v[162:165], v[0:15]
	global_load_dwordx4 v[90:93], v[70:71], off offset:3712
	global_load_dwordx4 v[134:137], v[82:83], off offset:1664
	s_waitcnt lgkmcnt(3)
	v_mfma_f32_32x32x16_bf16 v[48:63], v[150:153], v[158:161], v[48:63]
	s_waitcnt lgkmcnt(2)
	v_mfma_f32_32x32x16_bf16 v[32:47], v[150:153], v[174:177], v[32:47]
	v_mfma_f32_32x32x16_bf16 v[16:31], v[154:157], v[158:161], v[16:31]
	ds_read_b128 v[150:153], v66 offset:96
	ds_read_b128 v[158:161], v66 offset:4704
	ds_read_b128 v[162:165], v64 offset:36960
	ds_read_b128 v[166:169], v64 offset:41568
	s_waitcnt vmcnt(17)
	ds_write_b128 v68, v[98:101] offset:27648
	s_waitcnt vmcnt(16)
	ds_write_b128 v68, v[138:141] offset:64512
	v_mfma_f32_32x32x16_bf16 v[0:15], v[154:157], v[174:177], v[0:15]
	global_load_dwordx4 v[98:101], v[72:73], off offset:3712
	global_load_dwordx4 v[138:141], v[80:81], off offset:1664
	s_waitcnt lgkmcnt(3)
	v_mfma_f32_32x32x16_bf16 v[48:63], v[150:153], v[162:165], v[48:63]
	s_waitcnt vmcnt(17)
	ds_write_b128 v68, v[106:109] offset:32256
	s_waitcnt vmcnt(16)
	ds_write_b128 v67, v[142:145] offset:32256
	s_waitcnt lgkmcnt(4)
	v_mfma_f32_32x32x16_bf16 v[32:47], v[150:153], v[166:169], v[32:47]
	v_mfma_f32_32x32x16_bf16 v[16:31], v[158:161], v[162:165], v[16:31]
	v_mfma_f32_32x32x16_bf16 v[0:15], v[158:161], v[166:169], v[0:15]
	s_waitcnt lgkmcnt(0)
	s_barrier
; #define G_LOAD(S, kt_) do { G_LD1(S##a0, S##b0, 0, kt_); G_LD1(S##a1, S##b1, 1, kt_); G_LD1(S##a2, S##b2, 2, kt_); G_LD1(S##a3, S##b3, 3, kt_); } while (0)
; #define G_STORE(S, buf_) do { G_ST1(S##a0, S##b0, 0, buf_); G_ST1(S##a1, S##b1, 1, buf_); G_ST1(S##a2, S##b2, 2, buf_); G_ST1(S##a3, S##b3, 3, buf_); } while (0)
; template <class AL, class BL>
; DI void gemm_core(AL al, BL bl, int m0, int n0, int K, char* smem, f32x16 (&acc)[2][2]) {
;     ...
;   G_LOAD(x, 0);
;   G_STORE(x, 0);
;   G_LOAD(x, 1);
;   G_LOAD(y, (nk > 2) ? 2 : 1);
;   __syncthreads();
;   for (int kt = 0; kt < nk; kt += 2) {
;     G_TILE(0, x, true, (kt + 3 < nk), kt + 3);
;     __syncthreads();
;     G_TILE(1, y, (kt + 2 < nk), (kt + 4 < nk), kt + 4);
;     __syncthreads();
;   }
	ds_read_b128 v[106:109], v66 offset:18432
	ds_read_b128 v[142:145], v64 offset:55296
	ds_read_b128 v[150:153], v66 offset:18464
	ds_read_b128 v[154:157], v64 offset:55328
	ds_read_b128 v[158:161], v64 offset:59904
	ds_read_b128 v[162:165], v64 offset:59936
	s_waitcnt lgkmcnt(4)
	v_mfma_f32_32x32x16_bf16 v[48:63], v[106:109], v[142:145], v[48:63]
	s_waitcnt lgkmcnt(1)
	v_mfma_f32_32x32x16_bf16 v[32:47], v[106:109], v[158:161], v[32:47]
	ds_read_b128 v[106:109], v66 offset:23040
	ds_read_b128 v[166:169], v66 offset:23072
	s_waitcnt lgkmcnt(1)
	v_mfma_f32_32x32x16_bf16 v[16:31], v[106:109], v[142:145], v[16:31]
	global_load_dwordx4 v[142:145], v[76:77], off offset:3840
	global_load_dwordx4 v[174:177], v[78:79], off offset:1792
	s_waitcnt vmcnt(17)
	ds_write_b128 v68, v[146:149]
	s_waitcnt vmcnt(16)
	ds_write_b128 v68, v[170:173] offset:36864
	v_mfma_f32_32x32x16_bf16 v[0:15], v[106:109], v[158:161], v[0:15]
	global_load_dwordx4 v[106:109], v[74:75], off offset:3840
	global_load_dwordx4 v[146:149], v[84:85], off offset:1792
	v_mfma_f32_32x32x16_bf16 v[48:63], v[150:153], v[154:157], v[48:63]
	v_mfma_f32_32x32x16_bf16 v[32:47], v[150:153], v[162:165], v[32:47]
	s_waitcnt lgkmcnt(2)
	v_mfma_f32_32x32x16_bf16 v[16:31], v[166:169], v[154:157], v[16:31]
	ds_read_b128 v[150:153], v66 offset:18496
	ds_read_b128 v[154:157], v66 offset:23104
	ds_read_b128 v[158:161], v64 offset:55360
	ds_read_b128 v[170:173], v64 offset:59968
	s_waitcnt vmcnt(17)
	ds_write_b128 v68, v[114:117] offset:4608
	s_waitcnt vmcnt(16)
	ds_write_b128 v68, v[118:121] offset:41472
	v_mfma_f32_32x32x16_bf16 v[0:15], v[166:169], v[162:165], v[0:15]
	global_load_dwordx4 v[114:117], v[70:71], off offset:3840
	global_load_dwordx4 v[118:121], v[82:83], off offset:1792
	s_waitcnt lgkmcnt(3)
	v_mfma_f32_32x32x16_bf16 v[48:63], v[150:153], v[158:161], v[48:63]
	s_waitcnt lgkmcnt(2)
	v_mfma_f32_32x32x16_bf16 v[32:47], v[150:153], v[170:173], v[32:47]
	v_mfma_f32_32x32x16_bf16 v[16:31], v[154:157], v[158:161], v[16:31]
	ds_read_b128 v[150:153], v66 offset:18528
	ds_read_b128 v[158:161], v66 offset:23136
	ds_read_b128 v[162:165], v64 offset:55392
	ds_read_b128 v[166:169], v64 offset:60000
	s_waitcnt vmcnt(17)
	ds_write_b128 v68, v[86:89] offset:9216
	s_waitcnt vmcnt(16)
	ds_write_b128 v68, v[122:125] offset:46080
	v_mfma_f32_32x32x16_bf16 v[0:15], v[154:157], v[170:173], v[0:15]
	global_load_dwordx4 v[86:89], v[72:73], off offset:3840
	global_load_dwordx4 v[122:125], v[80:81], off offset:1792
	s_waitcnt lgkmcnt(3)
	v_mfma_f32_32x32x16_bf16 v[48:63], v[150:153], v[162:165], v[48:63]
	s_waitcnt vmcnt(17)
	ds_write_b128 v68, v[94:97] offset:13824
	s_waitcnt vmcnt(16)
	ds_write_b128 v68, v[126:129] offset:50688
	s_waitcnt lgkmcnt(4)
	v_mfma_f32_32x32x16_bf16 v[32:47], v[150:153], v[166:169], v[32:47]
	v_mfma_f32_32x32x16_bf16 v[16:31], v[158:161], v[162:165], v[16:31]
	v_mfma_f32_32x32x16_bf16 v[0:15], v[158:161], v[166:169], v[0:15]
	s_waitcnt lgkmcnt(0)
	s_barrier
	ds_read_b128 v[94:97], v66
	ds_read_b128 v[126:129], v64 offset:36864
	ds_read_b128 v[150:153], v66 offset:32
	ds_read_b128 v[154:157], v64 offset:36896
	ds_read_b128 v[158:161], v64 offset:41472
	ds_read_b128 v[162:165], v64 offset:41504
	s_waitcnt lgkmcnt(4)
	v_mfma_f32_32x32x16_bf16 v[48:63], v[94:97], v[126:129], v[48:63]
	s_waitcnt lgkmcnt(1)
	v_mfma_f32_32x32x16_bf16 v[32:47], v[94:97], v[158:161], v[32:47]
	ds_read_b128 v[94:97], v66 offset:4608
	ds_read_b128 v[166:169], v66 offset:4640
	s_waitcnt lgkmcnt(1)
	v_mfma_f32_32x32x16_bf16 v[16:31], v[94:97], v[126:129], v[16:31]
	global_load_dwordx4 v[126:129], v[76:77], off offset:3968
	s_nop 0
	global_load_dwordx4 v[76:79], v[78:79], off offset:1920
	s_waitcnt vmcnt(17)
	ds_write_b128 v68, v[130:133] offset:18432
	s_waitcnt vmcnt(16)
	ds_write_b128 v68, v[178:181] offset:55296
	v_mfma_f32_32x32x16_bf16 v[0:15], v[94:97], v[158:161], v[0:15]
	global_load_dwordx4 v[94:97], v[74:75], off offset:3968
	global_load_dwordx4 v[130:133], v[84:85], off offset:1920
	v_mfma_f32_32x32x16_bf16 v[48:63], v[150:153], v[154:157], v[48:63]
	v_mfma_f32_32x32x16_bf16 v[32:47], v[150:153], v[162:165], v[32:47]
	s_waitcnt lgkmcnt(2)
	v_mfma_f32_32x32x16_bf16 v[16:31], v[166:169], v[154:157], v[16:31]
	ds_read_b128 v[150:153], v66 offset:64
	ds_read_b128 v[154:157], v66 offset:4672
	ds_read_b128 v[158:161], v64 offset:36928
	ds_read_b128 v[170:173], v64 offset:41536
	s_waitcnt vmcnt(17)
	ds_write_b128 v68, v[102:105] offset:23040
	s_waitcnt vmcnt(16)
	ds_write_b128 v68, v[110:113] offset:59904
	v_mfma_f32_32x32x16_bf16 v[0:15], v[166:169], v[162:165], v[0:15]
	global_load_dwordx4 v[102:105], v[70:71], off offset:3968
	s_nop 0
	global_load_dwordx4 v[82:85], v[82:83], off offset:1920
	s_waitcnt lgkmcnt(3)
	v_mfma_f32_32x32x16_bf16 v[48:63], v[150:153], v[158:161], v[48:63]
	s_waitcnt lgkmcnt(2)
	v_mfma_f32_32x32x16_bf16 v[32:47], v[150:153], v[170:173], v[32:47]
	v_mfma_f32_32x32x16_bf16 v[16:31], v[154:157], v[158:161], v[16:31]
	ds_read_b128 v[110:113], v66 offset:96
	ds_read_b128 v[150:153], v66 offset:4704
	ds_read_b128 v[158:161], v64 offset:36960
	ds_read_b128 v[162:165], v64 offset:41568
	s_waitcnt vmcnt(17)
	ds_write_b128 v68, v[90:93] offset:27648
	s_waitcnt vmcnt(16)
	ds_write_b128 v68, v[134:137] offset:64512
	v_mfma_f32_32x32x16_bf16 v[0:15], v[154:157], v[170:173], v[0:15]
	global_load_dwordx4 v[70:73], v[72:73], off offset:3968
	s_nop 0
	global_load_dwordx4 v[90:93], v[80:81], off offset:1920
	s_waitcnt lgkmcnt(3)
	v_mfma_f32_32x32x16_bf16 v[48:63], v[110:113], v[158:161], v[48:63]
	s_waitcnt vmcnt(17)
	ds_write_b128 v68, v[98:101] offset:32256
	s_waitcnt vmcnt(16)
	ds_write_b128 v67, v[138:141] offset:32256
	s_waitcnt lgkmcnt(4)
	v_mfma_f32_32x32x16_bf16 v[32:47], v[110:113], v[162:165], v[32:47]
	v_mfma_f32_32x32x16_bf16 v[16:31], v[150:153], v[158:161], v[16:31]
	v_mfma_f32_32x32x16_bf16 v[0:15], v[150:153], v[162:165], v[0:15]
	s_waitcnt lgkmcnt(0)
	s_barrier
; #define G_LOAD(S, kt_) do { G_LD1(S##a0, S##b0, 0, kt_); G_LD1(S##a1, S##b1, 1, kt_); G_LD1(S##a2, S##b2, 2, kt_); G_LD1(S##a3, S##b3, 3, kt_); } while (0)
; #define G_STORE(S, buf_) do { G_ST1(S##a0, S##b0, 0, buf_); G_ST1(S##a1, S##b1, 1, buf_); G_ST1(S##a2, S##b2, 2, buf_); G_ST1(S##a3, S##b3, 3, buf_); } while (0)
; template <class AL, class BL>
; DI void gemm_core(AL al, BL bl, int m0, int n0, int K, char* smem, f32x16 (&acc)[2][2]) {
;     ...
;   G_LOAD(x, 0);
;   G_STORE(x, 0);
;   G_LOAD(x, 1);
;   G_LOAD(y, (nk > 2) ? 2 : 1);
;   __syncthreads();
;   for (int kt = 0; kt < nk; kt += 2) {
;     G_TILE(0, x, true, (kt + 3 < nk), kt + 3);
;     __syncthreads();
;     G_TILE(1, y, (kt + 2 < nk), (kt + 4 < nk), kt + 4);
;     __syncthreads();
;   }
	ds_read_b128 v[98:101], v66 offset:18432
	ds_read_b128 v[110:113], v64 offset:55296
	ds_read_b128 v[134:137], v66 offset:18464
	ds_read_b128 v[138:141], v64 offset:55328
	ds_read_b128 v[150:153], v64 offset:59904
	ds_read_b128 v[154:157], v64 offset:59936
	s_waitcnt lgkmcnt(4)
	v_mfma_f32_32x32x16_bf16 v[48:63], v[98:101], v[110:113], v[48:63]
	s_waitcnt lgkmcnt(1)
	v_mfma_f32_32x32x16_bf16 v[32:47], v[98:101], v[150:153], v[32:47]
	ds_read_b128 v[98:101], v66 offset:23040
	ds_read_b128 v[158:161], v66 offset:23072
	s_waitcnt vmcnt(15)
	ds_write_b128 v68, v[142:145]
	s_waitcnt vmcnt(14)
	ds_write_b128 v68, v[174:177] offset:36864
	s_waitcnt lgkmcnt(3)
	v_mfma_f32_32x32x16_bf16 v[16:31], v[98:101], v[110:113], v[16:31]
	v_mfma_f32_32x32x16_bf16 v[0:15], v[98:101], v[150:153], v[0:15]
	v_mfma_f32_32x32x16_bf16 v[48:63], v[134:137], v[138:141], v[48:63]
	v_mfma_f32_32x32x16_bf16 v[32:47], v[134:137], v[154:157], v[32:47]
	s_waitcnt lgkmcnt(2)
	v_mfma_f32_32x32x16_bf16 v[16:31], v[158:161], v[138:141], v[16:31]
	ds_read_b128 v[98:101], v66 offset:18496
	ds_read_b128 v[110:113], v66 offset:23104
	ds_read_b128 v[134:137], v64 offset:55360
	ds_read_b128 v[138:141], v64 offset:59968
	s_waitcnt vmcnt(13)
	ds_write_b128 v68, v[106:109] offset:4608
	s_waitcnt vmcnt(12)
	ds_write_b128 v68, v[146:149] offset:41472
	v_mfma_f32_32x32x16_bf16 v[0:15], v[158:161], v[154:157], v[0:15]
	s_waitcnt lgkmcnt(3)
	v_mfma_f32_32x32x16_bf16 v[48:63], v[98:101], v[134:137], v[48:63]
	s_waitcnt lgkmcnt(2)
	v_mfma_f32_32x32x16_bf16 v[32:47], v[98:101], v[138:141], v[32:47]
	v_mfma_f32_32x32x16_bf16 v[16:31], v[110:113], v[134:137], v[16:31]
	ds_read_b128 v[98:101], v66 offset:18528
	ds_read_b128 v[106:109], v66 offset:23136
	ds_read_b128 v[134:137], v64 offset:55392
	ds_read_b128 v[142:145], v64 offset:60000
	s_waitcnt vmcnt(11)
	ds_write_b128 v68, v[114:117] offset:9216
	s_waitcnt vmcnt(10)
	ds_write_b128 v68, v[118:121] offset:46080
	v_mfma_f32_32x32x16_bf16 v[0:15], v[110:113], v[138:141], v[0:15]
	s_waitcnt lgkmcnt(3)
	v_mfma_f32_32x32x16_bf16 v[48:63], v[98:101], v[134:137], v[48:63]
	s_waitcnt vmcnt(9)
	ds_write_b128 v68, v[86:89] offset:13824
	s_waitcnt vmcnt(8)
	ds_write_b128 v68, v[122:125] offset:50688
	s_waitcnt lgkmcnt(4)
	v_mfma_f32_32x32x16_bf16 v[32:47], v[98:101], v[142:145], v[32:47]
	v_mfma_f32_32x32x16_bf16 v[16:31], v[106:109], v[134:137], v[16:31]
	v_mfma_f32_32x32x16_bf16 v[0:15], v[106:109], v[142:145], v[0:15]
	s_waitcnt lgkmcnt(0)
	s_barrier
	ds_read_b128 v[86:89], v66
	ds_read_b128 v[98:101], v64 offset:36864
	ds_read_b128 v[106:109], v66 offset:32
	ds_read_b128 v[110:113], v64 offset:36896
	ds_read_b128 v[114:117], v64 offset:41472
	ds_read_b128 v[118:121], v64 offset:41504
	s_waitcnt lgkmcnt(4)
	v_mfma_f32_32x32x16_bf16 v[48:63], v[86:89], v[98:101], v[48:63]
	s_waitcnt lgkmcnt(1)
	v_mfma_f32_32x32x16_bf16 v[32:47], v[86:89], v[114:117], v[32:47]
	ds_read_b128 v[86:89], v66 offset:4608
	ds_read_b128 v[122:125], v66 offset:4640
	s_waitcnt vmcnt(7)
	ds_write_b128 v68, v[126:129] offset:18432
	s_waitcnt vmcnt(6)
	ds_write_b128 v68, v[76:79] offset:55296
	s_waitcnt lgkmcnt(3)
	v_mfma_f32_32x32x16_bf16 v[16:31], v[86:89], v[98:101], v[16:31]
	v_mfma_f32_32x32x16_bf16 v[0:15], v[86:89], v[114:117], v[0:15]
	ds_read_b128 v[74:77], v66 offset:64
	ds_read_b128 v[78:81], v66 offset:4672
	ds_read_b128 v[86:89], v64 offset:36928
	ds_read_b128 v[98:101], v64 offset:41536
	v_mfma_f32_32x32x16_bf16 v[48:63], v[106:109], v[110:113], v[48:63]
	s_waitcnt vmcnt(5)
	ds_write_b128 v68, v[94:97] offset:23040
	s_waitcnt vmcnt(4)
	ds_write_b128 v68, v[130:133] offset:59904
	v_mfma_f32_32x32x16_bf16 v[32:47], v[106:109], v[118:121], v[32:47]
	s_waitcnt lgkmcnt(8)
	v_mfma_f32_32x32x16_bf16 v[16:31], v[122:125], v[110:113], v[16:31]
	v_mfma_f32_32x32x16_bf16 v[0:15], v[122:125], v[118:121], v[0:15]
	s_waitcnt lgkmcnt(3)
	v_mfma_f32_32x32x16_bf16 v[48:63], v[74:77], v[86:89], v[48:63]
	s_waitcnt lgkmcnt(2)
	v_mfma_f32_32x32x16_bf16 v[32:47], v[74:77], v[98:101], v[32:47]
	v_mfma_f32_32x32x16_bf16 v[16:31], v[78:81], v[86:89], v[16:31]
	ds_read_b128 v[74:77], v66 offset:96
	ds_read_b128 v[86:89], v66 offset:4704
	ds_read_b128 v[94:97], v64 offset:36960
	ds_read_b128 v[106:109], v64 offset:41568
	s_waitcnt vmcnt(3)
	ds_write_b128 v68, v[102:105] offset:27648
	s_waitcnt vmcnt(2)
	ds_write_b128 v68, v[82:85] offset:64512
	v_mfma_f32_32x32x16_bf16 v[0:15], v[78:81], v[98:101], v[0:15]
	s_waitcnt lgkmcnt(3)
	v_mfma_f32_32x32x16_bf16 v[48:63], v[74:77], v[94:97], v[48:63]
	s_waitcnt vmcnt(1)
	ds_write_b128 v68, v[70:73] offset:32256
	s_waitcnt vmcnt(0)
	ds_write_b128 v67, v[90:93] offset:32256
	s_waitcnt lgkmcnt(4)
	v_mfma_f32_32x32x16_bf16 v[32:47], v[74:77], v[106:109], v[32:47]
	v_mfma_f32_32x32x16_bf16 v[16:31], v[86:89], v[94:97], v[16:31]
	v_mfma_f32_32x32x16_bf16 v[0:15], v[86:89], v[106:109], v[0:15]
	s_waitcnt lgkmcnt(0)
	s_barrier
; DI u16 f2bf(float x) { return (u16)(pack2(x, 0.f) & 0xffffu); }
; DI int opaque_tid() { int t = threadIdx.x; asm volatile("" : "+v"(t)); return t; }
; DI int crow(int i, int h) { return (i & 3) + 8 * (i >> 2) + 4 * h; }
; template <class AL, class BL>
; DI void gemm_core(AL al, BL bl, int m0, int n0, int K, char* smem, f32x16 (&acc)[2][2]) {
;     ...
;   for (int kt = 0; kt < nk; kt += 2) {
;     G_TILE(0, x, true, (kt + 3 < nk), kt + 3);
;     __syncthreads();
;     G_TILE(1, y, (kt + 2 < nk), (kt + 4 < nk), kt + 4);
;     __syncthreads();
;   }
; template <class F>
; DI void epi_bf16_tile(const f32x16 (&acc)[2][2], int m0, int n0, u16* dst0, long ld, char* smem, F f) {
;   const int tid = opaque_tid(), lane = tid & 63, w = tid >> 6, wm = w >> 1, wn = w & 1, h = lane >> 5;
;   u16* T = (u16*)smem;
; #pragma unroll
;   for (int mt = 0; mt < 2; mt++)
; #pragma unroll
;     for (int nt = 0; nt < 2; nt++)
; #pragma unroll
;       for (int i = 0; i < 16; i++) {
;         const int ml = wm * 64 + mt * 32 + crow(i, h), nl = wn * 64 + nt * 32 + (lane & 31);
;         T[ml * 136 + nl] = f2bf(f(m0 + ml, n0 + nl, acc[mt][nt][i]));
	ds_read_b128 v[68:71], v66 offset:18432
	ds_read_b128 v[72:75], v64 offset:55296
	ds_read_b128 v[76:79], v66 offset:18464
	ds_read_b128 v[80:83], v64 offset:55328
	ds_read_b128 v[84:87], v64 offset:59904
	ds_read_b128 v[88:91], v64 offset:59936
	s_waitcnt lgkmcnt(4)
	v_mfma_f32_32x32x16_bf16 v[48:63], v[68:71], v[72:75], v[48:63]
	s_waitcnt lgkmcnt(1)
	v_mfma_f32_32x32x16_bf16 v[32:47], v[68:71], v[84:87], v[32:47]
	ds_read_b128 v[68:71], v66 offset:23040
	ds_read_b128 v[92:95], v66 offset:23072
	s_waitcnt lgkmcnt(1)
	v_mfma_f32_32x32x16_bf16 v[16:31], v[68:71], v[72:75], v[16:31]
	v_mfma_f32_32x32x16_bf16 v[0:15], v[68:71], v[84:87], v[0:15]
	v_mfma_f32_32x32x16_bf16 v[48:63], v[76:79], v[80:83], v[48:63]
	v_mfma_f32_32x32x16_bf16 v[32:47], v[76:79], v[88:91], v[32:47]
	s_waitcnt lgkmcnt(0)
	v_mfma_f32_32x32x16_bf16 v[16:31], v[92:95], v[80:83], v[16:31]
	ds_read_b128 v[68:71], v66 offset:18496
	ds_read_b128 v[72:75], v66 offset:23104
	ds_read_b128 v[76:79], v64 offset:55360
	ds_read_b128 v[80:83], v64 offset:59968
	v_mfma_f32_32x32x16_bf16 v[0:15], v[92:95], v[88:91], v[0:15]
	s_waitcnt lgkmcnt(1)
	v_mfma_f32_32x32x16_bf16 v[48:63], v[68:71], v[76:79], v[48:63]
	s_waitcnt lgkmcnt(0)
	v_mfma_f32_32x32x16_bf16 v[32:47], v[68:71], v[80:83], v[32:47]
	v_mfma_f32_32x32x16_bf16 v[16:31], v[72:75], v[76:79], v[16:31]
	ds_read_b128 v[68:71], v66 offset:18528
	ds_read_b128 v[76:79], v66 offset:23136
	ds_read_b128 v[84:87], v64 offset:55392
	ds_read_b128 v[88:91], v64 offset:60000
	v_mfma_f32_32x32x16_bf16 v[0:15], v[72:75], v[80:83], v[0:15]
	s_waitcnt lgkmcnt(1)
	v_mfma_f32_32x32x16_bf16 v[48:63], v[68:71], v[84:87], v[48:63]
	s_waitcnt lgkmcnt(0)
	v_mfma_f32_32x32x16_bf16 v[32:47], v[68:71], v[88:91], v[32:47]
	v_mfma_f32_32x32x16_bf16 v[16:31], v[76:79], v[84:87], v[16:31]
	v_mfma_f32_32x32x16_bf16 v[0:15], v[76:79], v[88:91], v[0:15]
	v_mov_b32_e32 v64, v202
	s_barrier
	s_ashr_i32 s19, s18, 31
	s_lshl_b64 s[2:3], s[18:19], 13
	v_ashrrev_i32_e32 v66, 1, v64
	v_lshrrev_b32_e32 v67, 3, v64
	v_lshlrev_b32_e32 v69, 4, v64
	v_lshlrev_b32_e32 v68, 1, v64
	v_ashrrev_i32_e32 v70, 4, v64
	v_add_u32_e32 v72, 0x100, v64
	v_add_u32_e32 v73, 0x200, v64
	v_add_u32_e32 v74, 0x300, v64
	v_add_u32_e32 v75, 0x400, v64
	v_add_u32_e32 v76, 0x500, v64
	v_add_u32_e32 v77, 0x600, v64
	v_add_u32_e32 v78, 0x700, v64
	v_and_b32_e32 v98, 0xffffffc0, v66
	v_and_b32_e32 v99, 4, v67
	v_and_b32_e32 v64, 0xf0, v69
	s_add_u32 s2, s20, s2
	v_or_b32_e32 v82, v99, v98
	v_mad_u64_u32 v[66:67], s[18:19], v70, s29, v[64:65]
	s_addc_u32 s33, s21, s3
	s_ashr_i32 s1, s0, 31
	v_subrev_u32_e32 v67, s31, v82
	s_lshl_b64 s[0:1], s[0:1], 1
	v_add_u32_e32 v162, s22, v67
	v_and_b32_e32 v114, 0xbe, v68
	v_ashrrev_i32_e32 v71, 31, v70
	v_ashrrev_i32_e32 v84, 4, v72
	v_ashrrev_i32_e32 v86, 4, v73
	v_ashrrev_i32_e32 v88, 4, v74
	v_ashrrev_i32_e32 v90, 4, v75
	v_ashrrev_i32_e32 v92, 4, v76
	v_ashrrev_i32_e32 v94, 4, v77
	v_ashrrev_i32_e32 v96, 4, v78
	v_or_b32_e32 v115, 27, v99
	s_add_u32 s0, s2, s0
	v_subrev_u32_e32 v166, 48, v162
	v_subrev_u32_e32 v168, 40, v162
	v_subrev_u32_e32 v170, 32, v162
	v_subrev_u32_e32 v172, 24, v162
	v_add_u32_e32 v174, -16, v162
	v_add_u32_e32 v176, -8, v162
	v_add_u32_e32 v178, 8, v162
	v_or_b32_e32 v100, 1, v99
	v_or_b32_e32 v101, 2, v99
	v_or_b32_e32 v102, 3, v99
	v_or_b32_e32 v103, 8, v99
	v_or_b32_e32 v104, 9, v99
	v_or_b32_e32 v105, 10, v99
	v_or_b32_e32 v106, 11, v99
	v_or_b32_e32 v107, 16, v99
	v_or_b32_e32 v108, 17, v99
	v_or_b32_e32 v109, 18, v99
	v_or_b32_e32 v110, 19, v99
	v_or_b32_e32 v111, 24, v99
	v_or_b32_e32 v112, 25, v99
	v_or_b32_e32 v113, 26, v99
	v_or_b32_e32 v118, 32, v98
	v_lshlrev_b64 v[116:117], 13, v[70:71]
	v_mad_u64_u32 v[68:69], s[18:19], v84, s29, v[64:65]
	v_ashrrev_i32_e32 v85, 31, v84
	v_mad_u64_u32 v[70:71], s[18:19], v86, s29, v[64:65]
	v_ashrrev_i32_e32 v87, 31, v86
	v_mad_u64_u32 v[72:73], s[18:19], v88, s29, v[64:65]
	v_ashrrev_i32_e32 v89, 31, v88
	v_mad_u64_u32 v[74:75], s[18:19], v90, s29, v[64:65]
	v_ashrrev_i32_e32 v91, 31, v90
	v_mad_u64_u32 v[76:77], s[18:19], v92, s29, v[64:65]
	v_ashrrev_i32_e32 v93, 31, v92
	v_mad_u64_u32 v[78:79], s[18:19], v94, s29, v[64:65]
	v_ashrrev_i32_e32 v95, 31, v94
	v_mad_u64_u32 v[80:81], s[18:19], v96, s29, v[64:65]
	v_ashrrev_i32_e32 v97, 31, v96
	v_mad_u64_u32 v[82:83], s[2:3], v82, s29, v[114:115]
	s_addc_u32 s1, s33, s1
	v_ashrrev_i32_e32 v163, 31, v162
	v_ashrrev_i32_e32 v167, 31, v166
	v_ashrrev_i32_e32 v169, 31, v168
	v_ashrrev_i32_e32 v171, 31, v170
	v_ashrrev_i32_e32 v173, 31, v172
	v_ashrrev_i32_e32 v175, 31, v174
	v_ashrrev_i32_e32 v177, 31, v176
	v_ashrrev_i32_e32 v179, 31, v178
	v_or_b32_e32 v69, v100, v98
	v_or_b32_e32 v71, v101, v98
	v_or_b32_e32 v73, v102, v98
	v_or_b32_e32 v75, v103, v98
	v_or_b32_e32 v77, v104, v98
	v_or_b32_e32 v79, v105, v98
	v_or_b32_e32 v81, v106, v98
	v_or_b32_e32 v83, v107, v98
	v_or_b32_e32 v148, v108, v98
	v_or_b32_e32 v150, v109, v98
	v_or_b32_e32 v152, v110, v98
	v_or_b32_e32 v154, v111, v98
	v_or_b32_e32 v156, v112, v98
	v_or_b32_e32 v158, v113, v98
	v_or_b32_e32 v98, v115, v98
	v_or_b32_e32 v99, v118, v99
	v_or_b32_e32 v100, v100, v118
	v_or_b32_e32 v101, v101, v118
	v_or_b32_e32 v102, v102, v118
	v_or_b32_e32 v103, v103, v118
	v_or_b32_e32 v104, v104, v118
	v_or_b32_e32 v105, v105, v118
	v_or_b32_e32 v106, v106, v118
	v_or_b32_e32 v107, v107, v118
	v_or_b32_e32 v108, v108, v118
	v_or_b32_e32 v109, v109, v118
	v_or_b32_e32 v110, v110, v118
	v_or_b32_e32 v111, v111, v118
	v_or_b32_e32 v112, v112, v118
	v_or_b32_e32 v113, v113, v118
	v_or_b32_e32 v115, v115, v118
	v_lshlrev_b64 v[118:119], 13, v[84:85]
	v_lshlrev_b64 v[120:121], 13, v[86:87]
; DI u16 f2bf(float x) { return (u16)(pack2(x, 0.f) & 0xffffu); }
; DI int opaque_tid() { int t = threadIdx.x; asm volatile("" : "+v"(t)); return t; }
; DI int crow(int i, int h) { return (i & 3) + 8 * (i >> 2) + 4 * h; }
; template <class F>
; DI void epi_bf16_tile(const f32x16 (&acc)[2][2], int m0, int n0, u16* dst0, long ld, char* smem, F f) {
;   const int tid = opaque_tid(), lane = tid & 63, w = tid >> 6, wm = w >> 1, wn = w & 1, h = lane >> 5;
;   u16* T = (u16*)smem;
; #pragma unroll
;   for (int mt = 0; mt < 2; mt++)
; #pragma unroll
;     for (int nt = 0; nt < 2; nt++)
; #pragma unroll
;       for (int i = 0; i < 16; i++) {
;         const int ml = wm * 64 + mt * 32 + crow(i, h), nl = wn * 64 + nt * 32 + (lane & 31);
;         T[ml * 136 + nl] = f2bf(f(m0 + ml, n0 + nl, acc[mt][nt][i]));
; DI void ffn_up_phase(const Params& p, const u16* xb, int ldx, const u16* wupT, u16* hid, char* smem) {
;     ...
;              [=](const f32x16 (&acc)[2][2], int m0, int n0) {
;                epi_bf16_tile(acc, m0, n0, hid + (long)m0 * 4096 + n0, 4096, smem, [=](int m, int n, float v) {
;                  const float a = fmaxf(v * rs[m], 0.f);
;                  return a * a;
	v_lshlrev_b64 v[122:123], 13, v[88:89]
	v_lshlrev_b64 v[124:125], 13, v[90:91]
	v_lshlrev_b64 v[126:127], 13, v[92:93]
	v_lshlrev_b64 v[128:129], 13, v[94:95]
	v_lshlrev_b64 v[130:131], 13, v[96:97]
	v_lshl_add_u64 v[164:165], s[0:1], 0, v[64:65]
	v_lshl_add_u64 v[162:163], v[162:163], 2, s[12:13]
	v_lshl_add_u64 v[166:167], v[166:167], 2, s[12:13]
	v_lshl_add_u64 v[180:181], v[168:169], 2, s[12:13]
	v_lshl_add_u64 v[182:183], v[170:171], 2, s[12:13]
	v_lshl_add_u64 v[184:185], v[172:173], 2, s[12:13]
	v_lshl_add_u64 v[186:187], v[174:175], 2, s[12:13]
	v_lshl_add_u64 v[188:189], v[176:177], 2, s[12:13]
	v_lshl_add_u64 v[190:191], v[178:179], 2, s[12:13]
	v_lshl_add_u64 v[116:117], v[164:165], 0, v[116:117]
	v_lshl_add_u64 v[118:119], v[164:165], 0, v[118:119]
	v_lshl_add_u64 v[120:121], v[164:165], 0, v[120:121]
	v_lshl_add_u64 v[122:123], v[164:165], 0, v[122:123]
	v_lshl_add_u64 v[124:125], v[164:165], 0, v[124:125]
	v_lshl_add_u64 v[126:127], v[164:165], 0, v[126:127]
	v_lshl_add_u64 v[128:129], v[164:165], 0, v[128:129]
	v_lshl_add_u64 v[130:131], v[164:165], 0, v[130:131]
	global_load_dwordx4 v[162:165], v[162:163], off
	s_nop 0
	global_load_dwordx4 v[166:169], v[166:167], off
	s_nop 0
	global_load_dwordx4 v[170:173], v[180:181], off
	global_load_dwordx4 v[174:177], v[182:183], off
	s_nop 0
	global_load_dwordx4 v[178:181], v[184:185], off
	s_nop 0
	global_load_dwordx4 v[182:185], v[186:187], off
	s_nop 0
	global_load_dwordx4 v[186:189], v[188:189], off
	s_nop 0
	global_load_dwordx4 v[190:193], v[190:191], off
	v_mad_u64_u32 v[132:133], s[2:3], v69, s29, v[114:115]
	v_mad_u64_u32 v[134:135], s[2:3], v71, s29, v[114:115]
	v_mad_u64_u32 v[136:137], s[2:3], v73, s29, v[114:115]
	v_mad_u64_u32 v[138:139], s[2:3], v75, s29, v[114:115]
	v_mad_u64_u32 v[140:141], s[2:3], v77, s29, v[114:115]
	v_mad_u64_u32 v[142:143], s[2:3], v79, s29, v[114:115]
	v_mad_u64_u32 v[144:145], s[2:3], v81, s29, v[114:115]
	v_mad_u64_u32 v[146:147], s[2:3], v83, s29, v[114:115]
	v_mad_u64_u32 v[148:149], s[2:3], v148, s29, v[114:115]
	v_mad_u64_u32 v[150:151], s[2:3], v150, s29, v[114:115]
	v_mad_u64_u32 v[152:153], s[2:3], v152, s29, v[114:115]
	v_mad_u64_u32 v[154:155], s[2:3], v154, s29, v[114:115]
	v_mad_u64_u32 v[156:157], s[2:3], v156, s29, v[114:115]
	v_mad_u64_u32 v[158:159], s[2:3], v158, s29, v[114:115]
	v_mad_u64_u32 v[160:161], s[2:3], v98, s29, v[114:115]
	v_mad_u64_u32 v[84:85], s[2:3], v99, s29, v[114:115]
	v_mad_u64_u32 v[86:87], s[2:3], v100, s29, v[114:115]
	v_mad_u64_u32 v[88:89], s[2:3], v101, s29, v[114:115]
	v_mad_u64_u32 v[90:91], s[2:3], v102, s29, v[114:115]
	v_mad_u64_u32 v[92:93], s[2:3], v103, s29, v[114:115]
	v_mad_u64_u32 v[94:95], s[2:3], v104, s29, v[114:115]
	v_mad_u64_u32 v[96:97], s[2:3], v105, s29, v[114:115]
	v_mad_u64_u32 v[98:99], s[2:3], v106, s29, v[114:115]
	v_mad_u64_u32 v[100:101], s[2:3], v107, s29, v[114:115]
	v_mad_u64_u32 v[102:103], s[2:3], v108, s29, v[114:115]
	v_mad_u64_u32 v[104:105], s[2:3], v109, s29, v[114:115]
	v_mad_u64_u32 v[106:107], s[2:3], v110, s29, v[114:115]
	v_mad_u64_u32 v[108:109], s[2:3], v111, s29, v[114:115]
	v_mad_u64_u32 v[110:111], s[2:3], v112, s29, v[114:115]
	v_mad_u64_u32 v[112:113], s[2:3], v113, s29, v[114:115]
	v_mad_u64_u32 v[114:115], s[2:3], v115, s29, v[114:115]
	s_add_i32 s30, s30, s50
	s_add_i32 s22, s22, s23
	s_cmpk_lt_i32 s30, 0x1200
	s_waitcnt vmcnt(6)
	v_mul_f32_e32 v48, v48, v166
	v_mul_f32_e32 v49, v49, v167
	v_mul_f32_e32 v50, v50, v168
	v_mul_f32_e32 v51, v51, v169
	s_waitcnt vmcnt(2)
	v_mul_f32_e32 v16, v16, v182
	v_mul_f32_e32 v24, v24, v162
	v_mul_f32_e32 v25, v25, v163
	v_mul_f32_e32 v26, v26, v164
	v_mul_f32_e32 v27, v27, v165
	v_mul_f32_e32 v8, v8, v162
	v_mul_f32_e32 v9, v9, v163
	v_mul_f32_e32 v10, v10, v164
	v_mul_f32_e32 v11, v11, v165
	v_mul_f32_e32 v17, v17, v183
	v_mul_f32_e32 v18, v18, v184
	v_mul_f32_e32 v19, v19, v185
	s_waitcnt vmcnt(1)
	v_mul_f32_e32 v20, v20, v186
	v_mul_f32_e32 v21, v21, v187
	v_mul_f32_e32 v22, v22, v188
	v_mul_f32_e32 v23, v23, v189
	s_waitcnt vmcnt(0)
	v_mul_f32_e32 v28, v28, v190
	v_mul_f32_e32 v29, v29, v191
	v_mul_f32_e32 v30, v30, v192
	v_mul_f32_e32 v31, v31, v193
	v_mul_f32_e32 v0, v0, v182
	v_mul_f32_e32 v1, v1, v183
	v_mul_f32_e32 v2, v2, v184
	v_mul_f32_e32 v3, v3, v185
	v_mul_f32_e32 v4, v4, v186
	v_mul_f32_e32 v5, v5, v187
	v_mul_f32_e32 v6, v6, v188
	v_mul_f32_e32 v7, v7, v189
	v_mul_f32_e32 v12, v12, v190
	v_mul_f32_e32 v13, v13, v191
	v_mul_f32_e32 v14, v14, v192
	v_mul_f32_e32 v15, v15, v193
	v_mul_f32_e32 v52, v52, v170
	v_mul_f32_e32 v53, v53, v171
	v_mul_f32_e32 v54, v54, v172
	v_mul_f32_e32 v55, v55, v173
	v_mul_f32_e32 v56, v56, v174
	v_mul_f32_e32 v57, v57, v175
	v_mul_f32_e32 v58, v58, v176
	v_mul_f32_e32 v59, v59, v177
	v_mul_f32_e32 v60, v60, v178
	v_mul_f32_e32 v61, v61, v179
	v_mul_f32_e32 v62, v62, v180
	v_mul_f32_e32 v63, v63, v181
	v_mul_f32_e32 v32, v32, v166
	v_mul_f32_e32 v33, v33, v167
	v_mul_f32_e32 v34, v34, v168
	v_mul_f32_e32 v35, v35, v169
	v_mul_f32_e32 v36, v36, v170
	v_mul_f32_e32 v37, v37, v171
	v_mul_f32_e32 v38, v38, v172
	v_mul_f32_e32 v39, v39, v173
	v_mul_f32_e32 v40, v40, v174
	v_mul_f32_e32 v41, v41, v175
	v_mul_f32_e32 v42, v42, v176
	v_mul_f32_e32 v43, v43, v177
	v_mul_f32_e32 v44, v44, v178
	v_mul_f32_e32 v45, v45, v179
	v_mul_f32_e32 v46, v46, v180
	v_mul_f32_e32 v47, v47, v181
	v_max_f32_e32 v24, 0, v24
	v_max_f32_e32 v25, 0, v25
	v_max_f32_e32 v26, 0, v26
	v_max_f32_e32 v27, 0, v27
	v_max_f32_e32 v8, 0, v8
	v_max_f32_e32 v9, 0, v9
	v_max_f32_e32 v10, 0, v10
	v_max_f32_e32 v11, 0, v11
	v_max_f32_e32 v48, 0, v48
	v_max_f32_e32 v16, 0, v16
	v_max_f32_e32 v17, 0, v17
; DI void ffn_up_phase(const Params& p, const u16* xb, int ldx, const u16* wupT, u16* hid, char* smem) {
;     ...
;                epi_bf16_tile(acc, m0, n0, hid + (long)m0 * 4096 + n0, 4096, smem, [=](int m, int n, float v) {
;                  const float a = fmaxf(v * rs[m], 0.f);
;                  return a * a;
	v_max_f32_e32 v18, 0, v18
	v_max_f32_e32 v19, 0, v19
	v_max_f32_e32 v20, 0, v20
	v_max_f32_e32 v21, 0, v21
	v_max_f32_e32 v22, 0, v22
	v_max_f32_e32 v23, 0, v23
	v_max_f32_e32 v28, 0, v28
	v_max_f32_e32 v29, 0, v29
	v_max_f32_e32 v30, 0, v30
	v_max_f32_e32 v31, 0, v31
	v_max_f32_e32 v0, 0, v0
	v_max_f32_e32 v1, 0, v1
	v_max_f32_e32 v2, 0, v2
	v_max_f32_e32 v3, 0, v3
	v_max_f32_e32 v4, 0, v4
	v_max_f32_e32 v5, 0, v5
	v_max_f32_e32 v6, 0, v6
	v_max_f32_e32 v7, 0, v7
	v_max_f32_e32 v12, 0, v12
	v_max_f32_e32 v13, 0, v13
	v_max_f32_e32 v14, 0, v14
	v_max_f32_e32 v15, 0, v15
	v_max_f32_e32 v49, 0, v49
	v_max_f32_e32 v50, 0, v50
	v_max_f32_e32 v51, 0, v51
	v_max_f32_e32 v52, 0, v52
	v_max_f32_e32 v53, 0, v53
	v_max_f32_e32 v54, 0, v54
	v_max_f32_e32 v55, 0, v55
	v_max_f32_e32 v56, 0, v56
	v_max_f32_e32 v57, 0, v57
	v_max_f32_e32 v58, 0, v58
	v_max_f32_e32 v59, 0, v59
	v_max_f32_e32 v60, 0, v60
	v_max_f32_e32 v61, 0, v61
	v_max_f32_e32 v62, 0, v62
	v_max_f32_e32 v63, 0, v63
	v_max_f32_e32 v32, 0, v32
	v_max_f32_e32 v33, 0, v33
	v_max_f32_e32 v34, 0, v34
	v_max_f32_e32 v35, 0, v35
	v_max_f32_e32 v36, 0, v36
	v_max_f32_e32 v37, 0, v37
	v_max_f32_e32 v38, 0, v38
	v_max_f32_e32 v39, 0, v39
	v_max_f32_e32 v40, 0, v40
	v_max_f32_e32 v41, 0, v41
	v_max_f32_e32 v42, 0, v42
	v_max_f32_e32 v43, 0, v43
	v_max_f32_e32 v44, 0, v44
	v_max_f32_e32 v45, 0, v45
	v_max_f32_e32 v46, 0, v46
	v_max_f32_e32 v47, 0, v47
	v_mul_f32_e32 v24, v24, v24
	v_mul_f32_e32 v25, v25, v25
	v_mul_f32_e32 v26, v26, v26
	v_mul_f32_e32 v27, v27, v27
	v_mul_f32_e32 v8, v8, v8
	v_mul_f32_e32 v9, v9, v9
	v_mul_f32_e32 v10, v10, v10
	v_mul_f32_e32 v11, v11, v11
	v_mul_f32_e32 v48, v48, v48
	v_mul_f32_e32 v16, v16, v16
	v_mul_f32_e32 v17, v17, v17
	v_mul_f32_e32 v18, v18, v18
	v_mul_f32_e32 v19, v19, v19
	v_mul_f32_e32 v20, v20, v20
	v_mul_f32_e32 v21, v21, v21
	v_mul_f32_e32 v22, v22, v22
	v_mul_f32_e32 v23, v23, v23
	v_mul_f32_e32 v28, v28, v28
	v_mul_f32_e32 v29, v29, v29
	v_mul_f32_e32 v30, v30, v30
	v_mul_f32_e32 v31, v31, v31
	v_mul_f32_e32 v0, v0, v0
	v_mul_f32_e32 v1, v1, v1
	v_mul_f32_e32 v2, v2, v2
	v_mul_f32_e32 v3, v3, v3
	v_mul_f32_e32 v4, v4, v4
	v_mul_f32_e32 v5, v5, v5
	v_mul_f32_e32 v6, v6, v6
	v_mul_f32_e32 v7, v7, v7
	v_mul_f32_e32 v12, v12, v12
	v_mul_f32_e32 v13, v13, v13
	v_mul_f32_e32 v14, v14, v14
	v_mul_f32_e32 v15, v15, v15
	v_mul_f32_e32 v49, v49, v49
	v_mul_f32_e32 v50, v50, v50
	v_mul_f32_e32 v51, v51, v51
	v_mul_f32_e32 v52, v52, v52
	v_mul_f32_e32 v53, v53, v53
	v_mul_f32_e32 v54, v54, v54
	v_mul_f32_e32 v55, v55, v55
	v_mul_f32_e32 v56, v56, v56
	v_mul_f32_e32 v57, v57, v57
	v_mul_f32_e32 v58, v58, v58
	v_mul_f32_e32 v59, v59, v59
	v_mul_f32_e32 v60, v60, v60
	v_mul_f32_e32 v61, v61, v61
	v_mul_f32_e32 v62, v62, v62
	v_mul_f32_e32 v63, v63, v63
	v_mul_f32_e32 v32, v32, v32
	v_mul_f32_e32 v33, v33, v33
	v_mul_f32_e32 v34, v34, v34
	v_mul_f32_e32 v35, v35, v35
	v_mul_f32_e32 v36, v36, v36
	v_mul_f32_e32 v37, v37, v37
	v_mul_f32_e32 v38, v38, v38
	v_mul_f32_e32 v39, v39, v39
	v_mul_f32_e32 v40, v40, v40
	v_mul_f32_e32 v41, v41, v41
	v_mul_f32_e32 v42, v42, v42
	v_mul_f32_e32 v43, v43, v43
	v_mul_f32_e32 v44, v44, v44
	v_mul_f32_e32 v45, v45, v45
	v_mul_f32_e32 v46, v46, v46
	v_mul_f32_e32 v47, v47, v47
	v_cvt_pk_bf16_f32 v24, v24, s0
	v_cvt_pk_bf16_f32 v25, v25, s0
	v_cvt_pk_bf16_f32 v26, v26, s0
	v_cvt_pk_bf16_f32 v27, v27, s0
	v_cvt_pk_bf16_f32 v8, v8, s0
	v_cvt_pk_bf16_f32 v9, v9, s0
	v_cvt_pk_bf16_f32 v10, v10, s0
	v_cvt_pk_bf16_f32 v11, v11, s0
	v_cvt_pk_bf16_f32 v48, v48, s0
	v_cvt_pk_bf16_f32 v16, v16, s0
	v_cvt_pk_bf16_f32 v17, v17, s0
	v_cvt_pk_bf16_f32 v18, v18, s0
	v_cvt_pk_bf16_f32 v19, v19, s0
	v_cvt_pk_bf16_f32 v20, v20, s0
	v_cvt_pk_bf16_f32 v21, v21, s0
	v_cvt_pk_bf16_f32 v22, v22, s0
	v_cvt_pk_bf16_f32 v23, v23, s0
	v_cvt_pk_bf16_f32 v28, v28, s0
	v_cvt_pk_bf16_f32 v29, v29, s0
	v_cvt_pk_bf16_f32 v30, v30, s0
	v_cvt_pk_bf16_f32 v31, v31, s0
	v_cvt_pk_bf16_f32 v0, v0, s0
	v_cvt_pk_bf16_f32 v1, v1, s0
	v_cvt_pk_bf16_f32 v2, v2, s0
	v_cvt_pk_bf16_f32 v3, v3, s0
; DI u16 f2bf(float x) { return (u16)(pack2(x, 0.f) & 0xffffu); }
; DI int opaque_tid() { int t = threadIdx.x; asm volatile("" : "+v"(t)); return t; }
; DI int crow(int i, int h) { return (i & 3) + 8 * (i >> 2) + 4 * h; }
; template <class F>
; DI void epi_bf16_tile(const f32x16 (&acc)[2][2], int m0, int n0, u16* dst0, long ld, char* smem, F f) {
;   const int tid = opaque_tid(), lane = tid & 63, w = tid >> 6, wm = w >> 1, wn = w & 1, h = lane >> 5;
;   u16* T = (u16*)smem;
; #pragma unroll
;   for (int mt = 0; mt < 2; mt++)
; #pragma unroll
;     for (int nt = 0; nt < 2; nt++)
; #pragma unroll
;       for (int i = 0; i < 16; i++) {
;         const int ml = wm * 64 + mt * 32 + crow(i, h), nl = wn * 64 + nt * 32 + (lane & 31);
;         T[ml * 136 + nl] = f2bf(f(m0 + ml, n0 + nl, acc[mt][nt][i]));
;       }
;   __syncthreads();
; #pragma unroll
;   for (int j = 0; j < 8; j++) {
;     const int idx = tid + 256 * j, row = idx >> 4, ch = idx & 15;
;     *(uint4*)(dst0 + (long)row * ld + ch * 8) = *(const uint4*)(T + row * 136 + ch * 8);
;   }
;   __syncthreads();
; }
; template <class AL, class BL, class EP>
; DI void gemm_phase(int MT, int NTL, int K, AL al, BL bl, EP ep, char* smem) {
;   for (int t = blockIdx.x; t < MT * NTL; t += gridDim.x) {
;     const int tm = t % MT, tn = t / MT;
;     f32x16 acc[2][2];
;     gemm_core(al, bl, tm * 128, tn * 128, K, smem, acc);
;     ep(acc, tm * 128, tn * 128);
;   }
	v_cvt_pk_bf16_f32 v4, v4, s0
	v_cvt_pk_bf16_f32 v5, v5, s0
	v_cvt_pk_bf16_f32 v6, v6, s0
	v_cvt_pk_bf16_f32 v7, v7, s0
	v_cvt_pk_bf16_f32 v12, v12, s0
	v_cvt_pk_bf16_f32 v13, v13, s0
	v_cvt_pk_bf16_f32 v14, v14, s0
	v_cvt_pk_bf16_f32 v15, v15, s0
	v_cvt_pk_bf16_f32 v49, v49, s0
	v_cvt_pk_bf16_f32 v50, v50, s0
	v_cvt_pk_bf16_f32 v51, v51, s0
	v_cvt_pk_bf16_f32 v52, v52, s0
	v_cvt_pk_bf16_f32 v53, v53, s0
	v_cvt_pk_bf16_f32 v54, v54, s0
	v_cvt_pk_bf16_f32 v55, v55, s0
	v_cvt_pk_bf16_f32 v56, v56, s0
	v_cvt_pk_bf16_f32 v57, v57, s0
	v_cvt_pk_bf16_f32 v58, v58, s0
	v_cvt_pk_bf16_f32 v59, v59, s0
	v_cvt_pk_bf16_f32 v60, v60, s0
	v_cvt_pk_bf16_f32 v61, v61, s0
	v_cvt_pk_bf16_f32 v62, v62, s0
	v_cvt_pk_bf16_f32 v63, v63, s0
	v_cvt_pk_bf16_f32 v32, v32, s0
	v_cvt_pk_bf16_f32 v33, v33, s0
	v_cvt_pk_bf16_f32 v34, v34, s0
	v_cvt_pk_bf16_f32 v35, v35, s0
	v_cvt_pk_bf16_f32 v36, v36, s0
	v_cvt_pk_bf16_f32 v37, v37, s0
	v_cvt_pk_bf16_f32 v38, v38, s0
	v_cvt_pk_bf16_f32 v39, v39, s0
	v_cvt_pk_bf16_f32 v40, v40, s0
	v_cvt_pk_bf16_f32 v41, v41, s0
	v_cvt_pk_bf16_f32 v42, v42, s0
	v_cvt_pk_bf16_f32 v43, v43, s0
	v_cvt_pk_bf16_f32 v44, v44, s0
	v_cvt_pk_bf16_f32 v45, v45, s0
	v_cvt_pk_bf16_f32 v46, v46, s0
	v_cvt_pk_bf16_f32 v47, v47, s0
	ds_write_b16 v82, v48
	ds_write_b16 v132, v49
	ds_write_b16 v134, v50
	ds_write_b16 v136, v51
	ds_write_b16 v138, v52
	ds_write_b16 v140, v53
	ds_write_b16 v142, v54
	ds_write_b16 v144, v55
	ds_write_b16 v146, v56
	ds_write_b16 v148, v57
	ds_write_b16 v150, v58
	ds_write_b16 v152, v59
	ds_write_b16 v154, v60
	ds_write_b16 v156, v61
	ds_write_b16 v158, v62
	ds_write_b16 v160, v63
	ds_write_b16 v82, v32 offset:64
	ds_write_b16 v132, v33 offset:64
	ds_write_b16 v134, v34 offset:64
	ds_write_b16 v136, v35 offset:64
	ds_write_b16 v138, v36 offset:64
	ds_write_b16 v140, v37 offset:64
	ds_write_b16 v142, v38 offset:64
	ds_write_b16 v144, v39 offset:64
	ds_write_b16 v146, v40 offset:64
	ds_write_b16 v148, v41 offset:64
	ds_write_b16 v150, v42 offset:64
	ds_write_b16 v152, v43 offset:64
	ds_write_b16 v154, v44 offset:64
	ds_write_b16 v156, v45 offset:64
	ds_write_b16 v158, v46 offset:64
	ds_write_b16 v160, v47 offset:64
	ds_write_b16 v84, v16
	ds_write_b16 v86, v17
	ds_write_b16 v88, v18
	ds_write_b16 v90, v19
	ds_write_b16 v92, v20
	ds_write_b16 v94, v21
	ds_write_b16 v96, v22
	ds_write_b16 v98, v23
	ds_write_b16 v100, v24
	ds_write_b16 v102, v25
	ds_write_b16 v104, v26
	ds_write_b16 v106, v27
	ds_write_b16 v108, v28
	ds_write_b16 v110, v29
	ds_write_b16 v112, v30
	ds_write_b16 v114, v31
	ds_write_b16 v84, v0 offset:64
	ds_write_b16 v86, v1 offset:64
	ds_write_b16 v88, v2 offset:64
	ds_write_b16 v90, v3 offset:64
	ds_write_b16 v92, v4 offset:64
	ds_write_b16 v94, v5 offset:64
	ds_write_b16 v96, v6 offset:64
	ds_write_b16 v98, v7 offset:64
	ds_write_b16 v100, v8 offset:64
	ds_write_b16 v102, v9 offset:64
	ds_write_b16 v104, v10 offset:64
	ds_write_b16 v106, v11 offset:64
	ds_write_b16 v108, v12 offset:64
	ds_write_b16 v110, v13 offset:64
	ds_write_b16 v112, v14 offset:64
	ds_write_b16 v114, v15 offset:64
	s_waitcnt lgkmcnt(0)
	s_barrier
	ds_read_b128 v[0:3], v66
	ds_read_b128 v[4:7], v68
	ds_read_b128 v[8:11], v70
	ds_read_b128 v[12:15], v72
	ds_read_b128 v[16:19], v74
	ds_read_b128 v[20:23], v76
	ds_read_b128 v[24:27], v78
	ds_read_b128 v[28:31], v80
	s_waitcnt lgkmcnt(7)
	global_store_dwordx4 v[116:117], v[0:3], off
	s_waitcnt lgkmcnt(6)
	global_store_dwordx4 v[118:119], v[4:7], off
	s_waitcnt lgkmcnt(5)
	global_store_dwordx4 v[120:121], v[8:11], off
	s_waitcnt lgkmcnt(4)
	global_store_dwordx4 v[122:123], v[12:15], off
	s_waitcnt lgkmcnt(3)
	global_store_dwordx4 v[124:125], v[16:19], off
	s_waitcnt lgkmcnt(2)
	global_store_dwordx4 v[126:127], v[20:23], off
	s_waitcnt lgkmcnt(1)
	global_store_dwordx4 v[128:129], v[24:27], off
	s_waitcnt lgkmcnt(0)
	global_store_dwordx4 v[130:131], v[28:31], off
	s_barrier
	s_cbranch_scc0 .Lfu1_exit
	s_cmp_lg_u32 s99, 0
	s_cbranch_scc0 .LBB0_1674
.Lfu1_exit:
	s_mov_b64 s[70:71], s[48:49]
